# K-loop: arrive at the closing barrier 2 MFMAs early, raised priority for the 2 trailing MFMAs
# speedup vs baseline: 1.0084x; 1.0084x over previous
; #define PG8_STAGE(bufoff, gbase, voff) do { _Pragma("unroll") for (int _i = 0; _i < 2; ++_i) \
;         __builtin_amdgcn_global_load_lds((const unsigned*)((const char*)(gbase) + (voff)[_i]), (PG8_LAS unsigned*)(lds + (bufoff) + ldsw + _i * 8192), 16, 0, 0); } while (0)
; #define PG8_LDA(dst, b, h) do { _Pragma("unroll") for (int m = 0; m < 4; ++m) _Pragma("unroll") for (int k = 0; k < 2; ++k) dst[m][k] = *(const PG8_LAS bf16x8*)(lds + PG8_SA(b, h) + aoff + m * 2048 + k * 1024); } while (0)
; #define PG8_LDB(dst, b, h) do { _Pragma("unroll") for (int n = 0; n < 2; ++n) _Pragma("unroll") for (int k = 0; k < 2; ++k) dst[n][k] = *(const PG8_LAS bf16x8*)(lds + PG8_SB(b, h) + boff + n * 2048 + k * 1024); } while (0)
; #define PG8_MMA(ai, bj, At, Bt) do { __builtin_amdgcn_s_setprio(1); _Pragma("unroll") for (int m = 0; m < 4; ++m) _Pragma("unroll") for (int n = 0; n < 2; ++n) _Pragma("unroll") for (int k = 0; k < 2; ++k) \
;         acc[ai][bj][m][n] = __builtin_amdgcn_mfma_f32_16x16x32_bf16(Bt[n][k], At[m][k], acc[ai][bj][m][n], 0, 0, 0); __builtin_amdgcn_s_setprio(0); } while (0)
; #define PG8_WAIT_V(n) asm volatile("s_waitcnt vmcnt(" #n ")" ::: "memory")
; #define PG8_BAR __builtin_amdgcn_s_barrier()
; template <class Epi, class Sched, bool ALIGN_EPI = false, bool SP2 = false>
; __device__ __forceinline__ void gemm_phase(PG8_LAS unsigned char* lds, const Gemm g, const Sched& S, const Epi& E, const int wv  ) {
;     ...
;         for (int t = 0; t < nt; t += 2) {
;             const bool last = (t == nt - 2);
;             const char* a1 = cA + (size_t)(t + 1) * kstep;
;             const char* a2 = last ? nA : cA + (size_t)(t + 2) * kstep; const char* b2 = last ? nB : cB + (size_t)(t + 2) * kstep;
;             const char* a3 = a2 + kstep; const char* b3 = b2 + kstep;
;             if (last && has_next) S.a_ready(nxt);
;             if constexpr (SP2) {
;             PG8_LDB(B0, 0, 0); PG8_LDB(B1, 0, 1); PG8_SCHED; PG8_LDA(At, 0, 0); PG8_STAGE(PG8_SA(1, 1), a1 + hstepA, voffA);
;             PG8_WAIT_V(8); PG8_WAIT_L(0); PG8_BAR; PG8_MMA(0, 0, At, B0); PG8_MMA(0, 1, At, B1); PG8_BAR; PG8_SCHED;
;             PG8_LDA(At, 0, 1); PG8_STAGE(PG8_SB(0, 0), b2, voffB); PG8_STAGE(PG8_SB(0, 1), b2 + hstepB, voffB); PG8_STAGE(PG8_SA(0, 0), a2, voffA);
;             PG8_WAIT_V(8); PG8_WAIT_L(0); PG8_BAR; PG8_MMA(1, 0, At, B0); PG8_MMA(1, 1, At, B1); PG8_BAR; PG8_SCHED;
.LBB0_121:
	ds_read_b128 v[146:149], v152
	ds_read_b128 v[156:159], v152 offset:1024
	ds_read_b128 v[160:163], v152 offset:2048
	ds_read_b128 v[164:167], v152 offset:3072
	ds_read_b128 v[168:171], v153
	ds_read_b128 v[172:175], v153 offset:1024
	ds_read_b128 v[176:179], v153 offset:2048
	ds_read_b128 v[180:183], v153 offset:3072
	s_add_u32 s66, s64, 0xfff00080
	s_addc_u32 s67, s65, -1
	s_cmp_eq_u32 s96, 60
	s_cselect_b32 s69, s57, s67
	s_cselect_b32 s68, s92, s66
	s_cselect_b32 s67, s55, s95
	s_cselect_b32 s66, s93, s94
	v_lshl_add_u64 v[216:217], s[64:65], 0, v[138:139]
	s_add_i32 m0, s75, 0xc000
	ds_read_b128 v[184:187], v154
	ds_read_b128 v[188:191], v154 offset:1024
	ds_read_b128 v[192:195], v154 offset:2048
	ds_read_b128 v[196:199], v154 offset:3072
	ds_read_b128 v[200:203], v154 offset:4096
	ds_read_b128 v[204:207], v154 offset:5120
	ds_read_b128 v[208:211], v154 offset:6144
	ds_read_b128 v[212:215], v154 offset:7168
	global_load_lds_dwordx4 v[216:217], off
	v_lshl_add_u64 v[216:217], s[64:65], 0, v[140:141]
	s_add_i32 m0, s75, 0xe000
	s_nop 0
	global_load_lds_dwordx4 v[216:217], off
	s_waitcnt vmcnt(8)
	s_waitcnt lgkmcnt(0)
	s_barrier
	s_setprio 1
	s_waitcnt lgkmcnt(0)
	v_mfma_f32_16x16x32_bf16 v[76:79], v[146:149], v[184:187], v[76:79]
	v_mfma_f32_16x16x32_bf16 v[72:75], v[160:163], v[184:187], v[72:75]
	v_mfma_f32_16x16x32_bf16 v[68:71], v[146:149], v[192:195], v[68:71]
	v_mfma_f32_16x16x32_bf16 v[64:67], v[160:163], v[192:195], v[64:67]
	v_mfma_f32_16x16x32_bf16 v[56:59], v[146:149], v[200:203], v[56:59]
	v_mfma_f32_16x16x32_bf16 v[52:55], v[160:163], v[200:203], v[52:55]
	v_mfma_f32_16x16x32_bf16 v[44:47], v[146:149], v[208:211], v[44:47]
	v_mfma_f32_16x16x32_bf16 v[40:43], v[160:163], v[208:211], v[40:43]
	v_mfma_f32_16x16x32_bf16 v[76:79], v[156:159], v[188:191], v[76:79]
	v_mfma_f32_16x16x32_bf16 v[72:75], v[164:167], v[188:191], v[72:75]
	v_mfma_f32_16x16x32_bf16 v[68:71], v[156:159], v[196:199], v[68:71]
	v_mfma_f32_16x16x32_bf16 v[64:67], v[164:167], v[196:199], v[64:67]
	v_mfma_f32_16x16x32_bf16 v[56:59], v[156:159], v[204:207], v[56:59]
	v_mfma_f32_16x16x32_bf16 v[52:55], v[164:167], v[204:207], v[52:55]
	v_mfma_f32_16x16x32_bf16 v[44:47], v[156:159], v[212:215], v[44:47]
	v_mfma_f32_16x16x32_bf16 v[40:43], v[164:167], v[212:215], v[40:43]
	s_setprio 0
	s_setprio 1
	v_mfma_f32_16x16x32_bf16 v[124:127], v[168:171], v[184:187], v[124:127]
	v_mfma_f32_16x16x32_bf16 v[120:123], v[176:179], v[184:187], v[120:123]
	v_mfma_f32_16x16x32_bf16 v[116:119], v[168:171], v[192:195], v[116:119]
	v_mfma_f32_16x16x32_bf16 v[112:115], v[176:179], v[192:195], v[112:115]
	v_mfma_f32_16x16x32_bf16 v[108:111], v[168:171], v[200:203], v[108:111]
	v_mfma_f32_16x16x32_bf16 v[104:107], v[176:179], v[200:203], v[104:107]
	v_mfma_f32_16x16x32_bf16 v[100:103], v[168:171], v[208:211], v[100:103]
	v_mfma_f32_16x16x32_bf16 v[96:99], v[176:179], v[208:211], v[96:99]
	v_mfma_f32_16x16x32_bf16 v[124:127], v[172:175], v[188:191], v[124:127]
	v_mfma_f32_16x16x32_bf16 v[120:123], v[180:183], v[188:191], v[120:123]
	v_mfma_f32_16x16x32_bf16 v[116:119], v[172:175], v[196:199], v[116:119]
	v_mfma_f32_16x16x32_bf16 v[112:115], v[180:183], v[196:199], v[112:115]
	v_mfma_f32_16x16x32_bf16 v[108:111], v[172:175], v[204:207], v[108:111]
	v_mfma_f32_16x16x32_bf16 v[104:107], v[180:183], v[204:207], v[104:107]
	s_setprio 2
	s_barrier
	v_mfma_f32_16x16x32_bf16 v[100:103], v[172:175], v[212:215], v[100:103]
	v_mfma_f32_16x16x32_bf16 v[96:99], v[180:183], v[212:215], v[96:99]
	s_setprio 0
	s_add_i32 s97, s84, s74
	v_lshl_add_u64 v[216:217], s[66:67], 0, v[130:131]
	s_mov_b32 m0, s97
	ds_read_b128 v[184:187], v154 offset:16384
	ds_read_b128 v[188:191], v154 offset:17408
	ds_read_b128 v[192:195], v154 offset:18432
	ds_read_b128 v[196:199], v154 offset:19456
	ds_read_b128 v[200:203], v154 offset:20480
	ds_read_b128 v[204:207], v154 offset:21504
	ds_read_b128 v[208:211], v154 offset:22528
	ds_read_b128 v[212:215], v154 offset:23552
	global_load_lds_dwordx4 v[216:217], off
	s_add_i32 m0, s97, 0x2000
	s_add_u32 vcc_lo, s66, 0x100000
	v_lshl_add_u64 v[218:219], s[66:67], 0, v[134:135]
	s_addc_u32 vcc_hi, s67, 0
	s_add_i32 s97, s85, s74
	global_load_lds_dwordx4 v[218:219], off
	v_lshl_add_u64 v[220:221], vcc, 0, v[130:131]
	s_mov_b32 m0, s97
	v_lshl_add_u64 v[222:223], s[68:69], 0, v[132:133]
	global_load_lds_dwordx4 v[220:221], off
	v_lshl_add_u64 v[220:221], vcc, 0, v[134:135]
	s_add_i32 m0, s97, 0x2000
	s_nop 0
	global_load_lds_dwordx4 v[220:221], off
	v_lshl_add_u64 v[220:221], s[68:69], 0, v[128:129]
	s_mov_b32 m0, s75
	s_nop 0
	global_load_lds_dwordx4 v[220:221], off
	s_mov_b32 m0, s76
	s_nop 0
	global_load_lds_dwordx4 v[222:223], off
	s_waitcnt vmcnt(8)
	s_waitcnt lgkmcnt(0)
	s_barrier
; #define PG8_STAGE(bufoff, gbase, voff) do { _Pragma("unroll") for (int _i = 0; _i < 2; ++_i) \
;         __builtin_amdgcn_global_load_lds((const unsigned*)((const char*)(gbase) + (voff)[_i]), (PG8_LAS unsigned*)(lds + (bufoff) + ldsw + _i * 8192), 16, 0, 0); } while (0)
; #define PG8_LDA(dst, b, h) do { _Pragma("unroll") for (int m = 0; m < 4; ++m) _Pragma("unroll") for (int k = 0; k < 2; ++k) dst[m][k] = *(const PG8_LAS bf16x8*)(lds + PG8_SA(b, h) + aoff + m * 2048 + k * 1024); } while (0)
; #define PG8_LDB(dst, b, h) do { _Pragma("unroll") for (int n = 0; n < 2; ++n) _Pragma("unroll") for (int k = 0; k < 2; ++k) dst[n][k] = *(const PG8_LAS bf16x8*)(lds + PG8_SB(b, h) + boff + n * 2048 + k * 1024); } while (0)
; #define PG8_MMA(ai, bj, At, Bt) do { __builtin_amdgcn_s_setprio(1); _Pragma("unroll") for (int m = 0; m < 4; ++m) _Pragma("unroll") for (int n = 0; n < 2; ++n) _Pragma("unroll") for (int k = 0; k < 2; ++k) \
;         acc[ai][bj][m][n] = __builtin_amdgcn_mfma_f32_16x16x32_bf16(Bt[n][k], At[m][k], acc[ai][bj][m][n], 0, 0, 0); __builtin_amdgcn_s_setprio(0); } while (0)
; #define PG8_WAIT_V(n) asm volatile("s_waitcnt vmcnt(" #n ")" ::: "memory")
; #define PG8_WAIT_L(n) asm volatile("s_waitcnt lgkmcnt(" #n ")" ::: "memory")
; #define PG8_BAR __builtin_amdgcn_s_barrier()
; #define PG8_SCHED __builtin_amdgcn_sched_barrier(0)
; template <class Epi, class Sched, bool ALIGN_EPI = false, bool SP2 = false>
; __device__ __forceinline__ void gemm_phase(PG8_LAS unsigned char* lds, const Gemm g, const Sched& S, const Epi& E, const int wv  ) {
;     ...
;             PG8_WAIT_V(8); PG8_WAIT_L(0); PG8_BAR; PG8_MMA(1, 0, At, B0); PG8_MMA(1, 1, At, B1); PG8_BAR; PG8_SCHED;
;             PG8_LDB(B0, 1, 0); PG8_LDB(B1, 1, 1); PG8_SCHED; PG8_LDA(At, 1, 0); PG8_STAGE(PG8_SA(0, 1), a2 + hstepA, voffA);
;             PG8_WAIT_V(8); PG8_WAIT_L(0); PG8_BAR; PG8_MMA(0, 0, At, B0); PG8_MMA(0, 1, At, B1); PG8_BAR; PG8_SCHED;
	s_setprio 1
	s_waitcnt lgkmcnt(0)
	v_mfma_f32_16x16x32_bf16 v[28:31], v[146:149], v[184:187], v[28:31]
	v_mfma_f32_16x16x32_bf16 v[24:27], v[160:163], v[184:187], v[24:27]
	v_mfma_f32_16x16x32_bf16 v[20:23], v[146:149], v[192:195], v[20:23]
	v_mfma_f32_16x16x32_bf16 v[16:19], v[160:163], v[192:195], v[16:19]
	v_mfma_f32_16x16x32_bf16 v[12:15], v[146:149], v[200:203], v[12:15]
	v_mfma_f32_16x16x32_bf16 v[8:11], v[160:163], v[200:203], v[8:11]
	v_mfma_f32_16x16x32_bf16 v[4:7], v[146:149], v[208:211], v[4:7]
	v_mfma_f32_16x16x32_bf16 v[0:3], v[160:163], v[208:211], v[0:3]
	v_mfma_f32_16x16x32_bf16 v[28:31], v[156:159], v[188:191], v[28:31]
	v_mfma_f32_16x16x32_bf16 v[24:27], v[164:167], v[188:191], v[24:27]
	v_mfma_f32_16x16x32_bf16 v[20:23], v[156:159], v[196:199], v[20:23]
	v_mfma_f32_16x16x32_bf16 v[16:19], v[164:167], v[196:199], v[16:19]
	v_mfma_f32_16x16x32_bf16 v[12:15], v[156:159], v[204:207], v[12:15]
	v_mfma_f32_16x16x32_bf16 v[8:11], v[164:167], v[204:207], v[8:11]
	v_mfma_f32_16x16x32_bf16 v[4:7], v[156:159], v[212:215], v[4:7]
	v_mfma_f32_16x16x32_bf16 v[0:3], v[164:167], v[212:215], v[0:3]
	s_setprio 0
	s_setprio 1
	v_mfma_f32_16x16x32_bf16 v[92:95], v[168:171], v[184:187], v[92:95]
	v_mfma_f32_16x16x32_bf16 v[88:91], v[176:179], v[184:187], v[88:91]
	v_mfma_f32_16x16x32_bf16 v[84:87], v[168:171], v[192:195], v[84:87]
	v_mfma_f32_16x16x32_bf16 v[80:83], v[176:179], v[192:195], v[80:83]
	v_mfma_f32_16x16x32_bf16 v[60:63], v[168:171], v[200:203], v[60:63]
	v_mfma_f32_16x16x32_bf16 v[48:51], v[176:179], v[200:203], v[48:51]
	v_mfma_f32_16x16x32_bf16 v[36:39], v[168:171], v[208:211], v[36:39]
	v_mfma_f32_16x16x32_bf16 v[32:35], v[176:179], v[208:211], v[32:35]
	v_mfma_f32_16x16x32_bf16 v[92:95], v[172:175], v[188:191], v[92:95]
	v_mfma_f32_16x16x32_bf16 v[88:91], v[180:183], v[188:191], v[88:91]
	v_mfma_f32_16x16x32_bf16 v[84:87], v[172:175], v[196:199], v[84:87]
	v_mfma_f32_16x16x32_bf16 v[80:83], v[180:183], v[196:199], v[80:83]
	v_mfma_f32_16x16x32_bf16 v[60:63], v[172:175], v[204:207], v[60:63]
	v_mfma_f32_16x16x32_bf16 v[48:51], v[180:183], v[204:207], v[48:51]
	s_setprio 2
	s_barrier
	v_mfma_f32_16x16x32_bf16 v[36:39], v[172:175], v[212:215], v[36:39]
	v_mfma_f32_16x16x32_bf16 v[32:35], v[180:183], v[212:215], v[32:35]
	s_setprio 0
	s_add_i32 s97, 0, 0x18000
	v_add_u32_e32 v155, s97, v150
	s_add_i32 vcc_lo, 0, 0x1c000
	ds_read_b128 v[146:149], v155
	ds_read_b128 v[156:159], v155 offset:1024
	ds_read_b128 v[160:163], v155 offset:2048
	ds_read_b128 v[164:167], v155 offset:3072
	v_add_u32_e32 v155, vcc_lo, v150
	ds_read_b128 v[168:171], v155
	ds_read_b128 v[172:175], v155 offset:1024
	ds_read_b128 v[176:179], v155 offset:2048
	ds_read_b128 v[180:183], v155 offset:3072
	s_add_u32 s68, s68, 0x100000
	s_addc_u32 s69, s69, 0
	s_mov_b32 m0, s77
	v_lshl_add_u64 v[224:225], s[68:69], 0, v[128:129]
	ds_read_b128 v[184:187], v154 offset:32768
	ds_read_b128 v[188:191], v154 offset:33792
	ds_read_b128 v[192:195], v154 offset:34816
	ds_read_b128 v[196:199], v154 offset:35840
	ds_read_b128 v[200:203], v154 offset:36864
	ds_read_b128 v[204:207], v154 offset:37888
	ds_read_b128 v[208:211], v154 offset:38912
	ds_read_b128 v[212:215], v154 offset:39936
	global_load_lds_dwordx4 v[224:225], off
	v_lshl_add_u64 v[224:225], s[68:69], 0, v[132:133]
	s_mov_b32 m0, s78
	s_nop 0
	global_load_lds_dwordx4 v[224:225], off
	s_waitcnt vmcnt(8)
	s_waitcnt lgkmcnt(0)
	s_barrier
	s_setprio 1
	s_waitcnt lgkmcnt(0)
	v_mfma_f32_16x16x32_bf16 v[76:79], v[146:149], v[184:187], v[76:79]
	v_mfma_f32_16x16x32_bf16 v[72:75], v[160:163], v[184:187], v[72:75]
	v_mfma_f32_16x16x32_bf16 v[68:71], v[146:149], v[192:195], v[68:71]
	v_mfma_f32_16x16x32_bf16 v[64:67], v[160:163], v[192:195], v[64:67]
	v_mfma_f32_16x16x32_bf16 v[56:59], v[146:149], v[200:203], v[56:59]
	v_mfma_f32_16x16x32_bf16 v[52:55], v[160:163], v[200:203], v[52:55]
	v_mfma_f32_16x16x32_bf16 v[44:47], v[146:149], v[208:211], v[44:47]
	v_mfma_f32_16x16x32_bf16 v[40:43], v[160:163], v[208:211], v[40:43]
	v_mfma_f32_16x16x32_bf16 v[76:79], v[156:159], v[188:191], v[76:79]
	v_mfma_f32_16x16x32_bf16 v[72:75], v[164:167], v[188:191], v[72:75]
	v_mfma_f32_16x16x32_bf16 v[68:71], v[156:159], v[196:199], v[68:71]
	v_mfma_f32_16x16x32_bf16 v[64:67], v[164:167], v[196:199], v[64:67]
	v_mfma_f32_16x16x32_bf16 v[56:59], v[156:159], v[204:207], v[56:59]
	v_mfma_f32_16x16x32_bf16 v[52:55], v[164:167], v[204:207], v[52:55]
	v_mfma_f32_16x16x32_bf16 v[44:47], v[156:159], v[212:215], v[44:47]
	v_mfma_f32_16x16x32_bf16 v[40:43], v[164:167], v[212:215], v[40:43]
	s_setprio 0
	s_setprio 1
	v_mfma_f32_16x16x32_bf16 v[124:127], v[168:171], v[184:187], v[124:127]
	v_mfma_f32_16x16x32_bf16 v[120:123], v[176:179], v[184:187], v[120:123]
	v_mfma_f32_16x16x32_bf16 v[116:119], v[168:171], v[192:195], v[116:119]
	v_mfma_f32_16x16x32_bf16 v[112:115], v[176:179], v[192:195], v[112:115]
	v_mfma_f32_16x16x32_bf16 v[108:111], v[168:171], v[200:203], v[108:111]
	v_mfma_f32_16x16x32_bf16 v[104:107], v[176:179], v[200:203], v[104:107]
	v_mfma_f32_16x16x32_bf16 v[100:103], v[168:171], v[208:211], v[100:103]
	v_mfma_f32_16x16x32_bf16 v[96:99], v[176:179], v[208:211], v[96:99]
	v_mfma_f32_16x16x32_bf16 v[124:127], v[172:175], v[188:191], v[124:127]
	v_mfma_f32_16x16x32_bf16 v[120:123], v[180:183], v[188:191], v[120:123]
	v_mfma_f32_16x16x32_bf16 v[116:119], v[172:175], v[196:199], v[116:119]
	v_mfma_f32_16x16x32_bf16 v[112:115], v[180:183], v[196:199], v[112:115]
	v_mfma_f32_16x16x32_bf16 v[108:111], v[172:175], v[204:207], v[108:111]
	v_mfma_f32_16x16x32_bf16 v[104:107], v[180:183], v[204:207], v[104:107]
	s_setprio 2
	s_barrier
; #define PG8_STAGE(bufoff, gbase, voff) do { _Pragma("unroll") for (int _i = 0; _i < 2; ++_i) \
;         __builtin_amdgcn_global_load_lds((const unsigned*)((const char*)(gbase) + (voff)[_i]), (PG8_LAS unsigned*)(lds + (bufoff) + ldsw + _i * 8192), 16, 0, 0); } while (0)
; #define PG8_LDA(dst, b, h) do { _Pragma("unroll") for (int m = 0; m < 4; ++m) _Pragma("unroll") for (int k = 0; k < 2; ++k) dst[m][k] = *(const PG8_LAS bf16x8*)(lds + PG8_SA(b, h) + aoff + m * 2048 + k * 1024); } while (0)
; #define PG8_MMA(ai, bj, At, Bt) do { __builtin_amdgcn_s_setprio(1); _Pragma("unroll") for (int m = 0; m < 4; ++m) _Pragma("unroll") for (int n = 0; n < 2; ++n) _Pragma("unroll") for (int k = 0; k < 2; ++k) \
;         acc[ai][bj][m][n] = __builtin_amdgcn_mfma_f32_16x16x32_bf16(Bt[n][k], At[m][k], acc[ai][bj][m][n], 0, 0, 0); __builtin_amdgcn_s_setprio(0); } while (0)
; #define PG8_WAIT_V(n) asm volatile("s_waitcnt vmcnt(" #n ")" ::: "memory")
; #define PG8_WAIT_L(n) asm volatile("s_waitcnt lgkmcnt(" #n ")" ::: "memory")
; #define PG8_BAR __builtin_amdgcn_s_barrier()
; #define PG8_SCHED __builtin_amdgcn_sched_barrier(0)
; template <class Epi, class Sched, bool ALIGN_EPI = false, bool SP2 = false>
; __device__ __forceinline__ void gemm_phase(PG8_LAS unsigned char* lds, const Gemm g, const Sched& S, const Epi& E, const int wv  ) {
;     ...
;             PG8_WAIT_V(8); PG8_WAIT_L(0); PG8_BAR; PG8_MMA(0, 0, At, B0); PG8_MMA(0, 1, At, B1); PG8_BAR; PG8_SCHED;
;             PG8_LDA(At, 1, 1); PG8_STAGE(PG8_SB(1, 0), b3, voffB); PG8_STAGE(PG8_SB(1, 1), b3 + hstepB, voffB); PG8_STAGE(PG8_SA(1, 0), a3, voffA);
;             PG8_WAIT_V(8); PG8_WAIT_L(0); PG8_BAR; PG8_MMA(1, 0, At, B0); PG8_MMA(1, 1, At, B1); PG8_BAR; PG8_SCHED;
;     ...
;         if constexpr (ALIGN_EPI) { if (wr == 0) PG8_BAR; }
	v_mfma_f32_16x16x32_bf16 v[100:103], v[172:175], v[212:215], v[100:103]
	v_mfma_f32_16x16x32_bf16 v[96:99], v[180:183], v[212:215], v[96:99]
	s_setprio 0
	s_add_i32 s68, s97, s74
	v_lshl_add_u64 v[216:217], v[216:217], 0, s[18:19]
	s_mov_b32 m0, s68
	ds_read_b128 v[184:187], v154 offset:49152
	ds_read_b128 v[188:191], v154 offset:50176
	ds_read_b128 v[192:195], v154 offset:51200
	ds_read_b128 v[196:199], v154 offset:52224
	ds_read_b128 v[200:203], v154 offset:53248
	ds_read_b128 v[204:207], v154 offset:54272
	ds_read_b128 v[208:211], v154 offset:55296
	ds_read_b128 v[212:215], v154 offset:56320
	global_load_lds_dwordx4 v[216:217], off
	s_add_i32 m0, s68, 0x2000
	s_add_u32 s66, s66, 0x100080
	v_lshl_add_u64 v[216:217], v[218:219], 0, s[18:19]
	s_addc_u32 s67, s67, 0
	s_add_i32 s68, vcc_lo, s74
	global_load_lds_dwordx4 v[216:217], off
	v_lshl_add_u64 v[216:217], s[66:67], 0, v[130:131]
	s_mov_b32 m0, s68
	s_nop 0
	global_load_lds_dwordx4 v[216:217], off
	v_lshl_add_u64 v[216:217], s[66:67], 0, v[134:135]
	s_add_i32 m0, s68, 0x2000
	s_nop 0
	global_load_lds_dwordx4 v[216:217], off
	v_lshl_add_u64 v[216:217], v[220:221], 0, s[18:19]
	s_mov_b32 m0, s81
	s_nop 0
	global_load_lds_dwordx4 v[216:217], off
	v_lshl_add_u64 v[216:217], v[222:223], 0, s[18:19]
	s_mov_b32 m0, s82
	s_nop 0
	global_load_lds_dwordx4 v[216:217], off
	s_waitcnt vmcnt(8)
	s_waitcnt lgkmcnt(0)
	s_barrier
	s_setprio 1
	s_waitcnt lgkmcnt(0)
	v_mfma_f32_16x16x32_bf16 v[28:31], v[146:149], v[184:187], v[28:31]
	v_mfma_f32_16x16x32_bf16 v[24:27], v[160:163], v[184:187], v[24:27]
	v_mfma_f32_16x16x32_bf16 v[20:23], v[146:149], v[192:195], v[20:23]
	v_mfma_f32_16x16x32_bf16 v[16:19], v[160:163], v[192:195], v[16:19]
	v_mfma_f32_16x16x32_bf16 v[12:15], v[146:149], v[200:203], v[12:15]
	v_mfma_f32_16x16x32_bf16 v[8:11], v[160:163], v[200:203], v[8:11]
	v_mfma_f32_16x16x32_bf16 v[4:7], v[146:149], v[208:211], v[4:7]
	v_mfma_f32_16x16x32_bf16 v[0:3], v[160:163], v[208:211], v[0:3]
	v_mfma_f32_16x16x32_bf16 v[28:31], v[156:159], v[188:191], v[28:31]
	v_mfma_f32_16x16x32_bf16 v[24:27], v[164:167], v[188:191], v[24:27]
	v_mfma_f32_16x16x32_bf16 v[20:23], v[156:159], v[196:199], v[20:23]
	v_mfma_f32_16x16x32_bf16 v[16:19], v[164:167], v[196:199], v[16:19]
	v_mfma_f32_16x16x32_bf16 v[12:15], v[156:159], v[204:207], v[12:15]
	v_mfma_f32_16x16x32_bf16 v[8:11], v[164:167], v[204:207], v[8:11]
	v_mfma_f32_16x16x32_bf16 v[4:7], v[156:159], v[212:215], v[4:7]
	v_mfma_f32_16x16x32_bf16 v[0:3], v[164:167], v[212:215], v[0:3]
	s_setprio 0
	s_setprio 1
	v_mfma_f32_16x16x32_bf16 v[92:95], v[168:171], v[184:187], v[92:95]
	v_mfma_f32_16x16x32_bf16 v[88:91], v[176:179], v[184:187], v[88:91]
	v_mfma_f32_16x16x32_bf16 v[84:87], v[168:171], v[192:195], v[84:87]
	v_mfma_f32_16x16x32_bf16 v[80:83], v[176:179], v[192:195], v[80:83]
	v_mfma_f32_16x16x32_bf16 v[60:63], v[168:171], v[200:203], v[60:63]
	v_mfma_f32_16x16x32_bf16 v[48:51], v[176:179], v[200:203], v[48:51]
	v_mfma_f32_16x16x32_bf16 v[36:39], v[168:171], v[208:211], v[36:39]
	v_mfma_f32_16x16x32_bf16 v[32:35], v[176:179], v[208:211], v[32:35]
	v_mfma_f32_16x16x32_bf16 v[92:95], v[172:175], v[188:191], v[92:95]
	v_mfma_f32_16x16x32_bf16 v[88:91], v[180:183], v[188:191], v[88:91]
	v_mfma_f32_16x16x32_bf16 v[84:87], v[172:175], v[196:199], v[84:87]
	v_mfma_f32_16x16x32_bf16 v[80:83], v[180:183], v[196:199], v[80:83]
	v_mfma_f32_16x16x32_bf16 v[60:63], v[172:175], v[204:207], v[60:63]
	v_mfma_f32_16x16x32_bf16 v[48:51], v[180:183], v[204:207], v[48:51]
	s_setprio 2
	s_barrier
	v_mfma_f32_16x16x32_bf16 v[36:39], v[172:175], v[212:215], v[36:39]
	v_mfma_f32_16x16x32_bf16 v[32:35], v[180:183], v[212:215], v[32:35]
	s_setprio 0
	s_add_i32 s96, s96, 2
	s_add_u32 s64, s64, 0x100
	s_addc_u32 s65, s65, 0
	s_add_u32 s94, s94, 0x100
	s_addc_u32 s95, s95, 0
	s_cmp_gt_u32 s96, 61
	s_cbranch_scc0 .LBB0_121
	s_and_b64 vcc, exec, s[20:21]
	s_cbranch_vccz .LBB0_124
	s_barrier

; #define PG8_STAGE(bufoff, gbase, voff) do { _Pragma("unroll") for (int _i = 0; _i < 2; ++_i) \
;         __builtin_amdgcn_global_load_lds((const unsigned*)((const char*)(gbase) + (voff)[_i]), (PG8_LAS unsigned*)(lds + (bufoff) + ldsw + _i * 8192), 16, 0, 0); } while (0)
; #define PG8_LDA(dst, b, h) do { _Pragma("unroll") for (int m = 0; m < 4; ++m) _Pragma("unroll") for (int k = 0; k < 2; ++k) dst[m][k] = *(const PG8_LAS bf16x8*)(lds + PG8_SA(b, h) + aoff + m * 2048 + k * 1024); } while (0)
; #define PG8_LDB(dst, b, h) do { _Pragma("unroll") for (int n = 0; n < 2; ++n) _Pragma("unroll") for (int k = 0; k < 2; ++k) dst[n][k] = *(const PG8_LAS bf16x8*)(lds + PG8_SB(b, h) + boff + n * 2048 + k * 1024); } while (0)
; #define PG8_MMA(ai, bj, At, Bt) do { __builtin_amdgcn_s_setprio(1); _Pragma("unroll") for (int m = 0; m < 4; ++m) _Pragma("unroll") for (int n = 0; n < 2; ++n) _Pragma("unroll") for (int k = 0; k < 2; ++k) \
;         acc[ai][bj][m][n] = __builtin_amdgcn_mfma_f32_16x16x32_bf16(Bt[n][k], At[m][k], acc[ai][bj][m][n], 0, 0, 0); __builtin_amdgcn_s_setprio(0); } while (0)
; #define PG8_WAIT_V(n) asm volatile("s_waitcnt vmcnt(" #n ")" ::: "memory")
; #define PG8_BAR __builtin_amdgcn_s_barrier()
; template <class Epi, class Sched, bool ALIGN_EPI = false, bool SP2 = false>
; __device__ __forceinline__ void gemm_phase(PG8_LAS unsigned char* lds, const Gemm g, const Sched& S, const Epi& E, const int wv  ) {
;     ...
;         for (int t = 0; t < nt; t += 2) {
;             const bool last = (t == nt - 2);
;             const char* a1 = cA + (size_t)(t + 1) * kstep;
;             const char* a2 = last ? nA : cA + (size_t)(t + 2) * kstep; const char* b2 = last ? nB : cB + (size_t)(t + 2) * kstep;
;             const char* a3 = a2 + kstep; const char* b3 = b2 + kstep;
;             if (last && has_next) S.a_ready(nxt);
;             if constexpr (SP2) {
;             PG8_LDB(B0, 0, 0); PG8_LDB(B1, 0, 1); PG8_SCHED; PG8_LDA(At, 0, 0); PG8_STAGE(PG8_SA(1, 1), a1 + hstepA, voffA);
;             PG8_WAIT_V(8); PG8_WAIT_L(0); PG8_BAR; PG8_MMA(0, 0, At, B0); PG8_MMA(0, 1, At, B1); PG8_BAR; PG8_SCHED;
;             PG8_LDA(At, 0, 1); PG8_STAGE(PG8_SB(0, 0), b2, voffB); PG8_STAGE(PG8_SB(0, 1), b2 + hstepB, voffB); PG8_STAGE(PG8_SA(0, 0), a2, voffA);
;             PG8_WAIT_V(8); PG8_WAIT_L(0); PG8_BAR; PG8_MMA(1, 0, At, B0); PG8_MMA(1, 1, At, B1); PG8_BAR; PG8_SCHED;
.LBB0_706:
	ds_read_b128 v[146:149], v152
	ds_read_b128 v[156:159], v152 offset:1024
	ds_read_b128 v[160:163], v152 offset:2048
	ds_read_b128 v[164:167], v152 offset:3072
	ds_read_b128 v[168:171], v153
	ds_read_b128 v[172:175], v153 offset:1024
	ds_read_b128 v[176:179], v153 offset:2048
	ds_read_b128 v[180:183], v153 offset:3072
	s_add_u32 s60, s58, 0xfff00080
	s_addc_u32 s61, s59, -1
	s_cmp_eq_u32 s87, 60
	s_cselect_b32 s63, s51, s61
	s_cselect_b32 s62, s83, s60
	s_cselect_b32 s61, s49, s86
	s_cselect_b32 s60, s84, s85
	v_lshl_add_u64 v[216:217], s[58:59], 0, v[138:139]
	s_add_i32 m0, s68, 0xc000
	ds_read_b128 v[184:187], v154
	ds_read_b128 v[188:191], v154 offset:1024
	ds_read_b128 v[192:195], v154 offset:2048
	ds_read_b128 v[196:199], v154 offset:3072
	ds_read_b128 v[200:203], v154 offset:4096
	ds_read_b128 v[204:207], v154 offset:5120
	ds_read_b128 v[208:211], v154 offset:6144
	ds_read_b128 v[212:215], v154 offset:7168
	global_load_lds_dwordx4 v[216:217], off
	v_lshl_add_u64 v[216:217], s[58:59], 0, v[140:141]
	s_add_i32 m0, s68, 0xe000
	s_nop 0
	global_load_lds_dwordx4 v[216:217], off
	s_waitcnt vmcnt(8)
	s_waitcnt lgkmcnt(0)
	s_barrier
	s_setprio 1
	s_waitcnt lgkmcnt(0)
	v_mfma_f32_16x16x32_bf16 v[76:79], v[146:149], v[184:187], v[76:79]
	v_mfma_f32_16x16x32_bf16 v[72:75], v[160:163], v[184:187], v[72:75]
	v_mfma_f32_16x16x32_bf16 v[68:71], v[146:149], v[192:195], v[68:71]
	v_mfma_f32_16x16x32_bf16 v[64:67], v[160:163], v[192:195], v[64:67]
	v_mfma_f32_16x16x32_bf16 v[56:59], v[146:149], v[200:203], v[56:59]
	v_mfma_f32_16x16x32_bf16 v[52:55], v[160:163], v[200:203], v[52:55]
	v_mfma_f32_16x16x32_bf16 v[44:47], v[146:149], v[208:211], v[44:47]
	v_mfma_f32_16x16x32_bf16 v[40:43], v[160:163], v[208:211], v[40:43]
	v_mfma_f32_16x16x32_bf16 v[76:79], v[156:159], v[188:191], v[76:79]
	v_mfma_f32_16x16x32_bf16 v[72:75], v[164:167], v[188:191], v[72:75]
	v_mfma_f32_16x16x32_bf16 v[68:71], v[156:159], v[196:199], v[68:71]
	v_mfma_f32_16x16x32_bf16 v[64:67], v[164:167], v[196:199], v[64:67]
	v_mfma_f32_16x16x32_bf16 v[56:59], v[156:159], v[204:207], v[56:59]
	v_mfma_f32_16x16x32_bf16 v[52:55], v[164:167], v[204:207], v[52:55]
	v_mfma_f32_16x16x32_bf16 v[44:47], v[156:159], v[212:215], v[44:47]
	v_mfma_f32_16x16x32_bf16 v[40:43], v[164:167], v[212:215], v[40:43]
	s_setprio 0
	s_setprio 1
	v_mfma_f32_16x16x32_bf16 v[124:127], v[168:171], v[184:187], v[124:127]
	v_mfma_f32_16x16x32_bf16 v[120:123], v[176:179], v[184:187], v[120:123]
	v_mfma_f32_16x16x32_bf16 v[116:119], v[168:171], v[192:195], v[116:119]
	v_mfma_f32_16x16x32_bf16 v[112:115], v[176:179], v[192:195], v[112:115]
	v_mfma_f32_16x16x32_bf16 v[108:111], v[168:171], v[200:203], v[108:111]
	v_mfma_f32_16x16x32_bf16 v[104:107], v[176:179], v[200:203], v[104:107]
	v_mfma_f32_16x16x32_bf16 v[100:103], v[168:171], v[208:211], v[100:103]
	v_mfma_f32_16x16x32_bf16 v[96:99], v[176:179], v[208:211], v[96:99]
	v_mfma_f32_16x16x32_bf16 v[124:127], v[172:175], v[188:191], v[124:127]
	v_mfma_f32_16x16x32_bf16 v[120:123], v[180:183], v[188:191], v[120:123]
	v_mfma_f32_16x16x32_bf16 v[116:119], v[172:175], v[196:199], v[116:119]
	v_mfma_f32_16x16x32_bf16 v[112:115], v[180:183], v[196:199], v[112:115]
	v_mfma_f32_16x16x32_bf16 v[108:111], v[172:175], v[204:207], v[108:111]
	v_mfma_f32_16x16x32_bf16 v[104:107], v[180:183], v[204:207], v[104:107]
	s_setprio 2
	s_barrier
	v_mfma_f32_16x16x32_bf16 v[100:103], v[172:175], v[212:215], v[100:103]
	v_mfma_f32_16x16x32_bf16 v[96:99], v[180:183], v[212:215], v[96:99]
	s_setprio 0
	s_add_i32 s90, s77, s67
	v_lshl_add_u64 v[216:217], s[60:61], 0, v[130:131]
	s_mov_b32 m0, s90
	ds_read_b128 v[184:187], v154 offset:16384
	ds_read_b128 v[188:191], v154 offset:17408
	ds_read_b128 v[192:195], v154 offset:18432
	ds_read_b128 v[196:199], v154 offset:19456
	ds_read_b128 v[200:203], v154 offset:20480
	ds_read_b128 v[204:207], v154 offset:21504
	ds_read_b128 v[208:211], v154 offset:22528
	ds_read_b128 v[212:215], v154 offset:23552
	global_load_lds_dwordx4 v[216:217], off
	s_add_i32 m0, s90, 0x2000
	s_add_u32 s90, s60, 0x100000
	v_lshl_add_u64 v[218:219], s[60:61], 0, v[134:135]
	s_addc_u32 s91, s61, 0
	s_add_i32 s92, s78, s67
	global_load_lds_dwordx4 v[218:219], off
	v_lshl_add_u64 v[220:221], s[90:91], 0, v[130:131]
	s_mov_b32 m0, s92
	v_lshl_add_u64 v[222:223], s[62:63], 0, v[132:133]
	global_load_lds_dwordx4 v[220:221], off
	v_lshl_add_u64 v[220:221], s[90:91], 0, v[134:135]
	s_add_i32 m0, s92, 0x2000
	s_nop 0
	global_load_lds_dwordx4 v[220:221], off
	v_lshl_add_u64 v[220:221], s[62:63], 0, v[128:129]
	s_mov_b32 m0, s68
	s_nop 0
	global_load_lds_dwordx4 v[220:221], off
	s_mov_b32 m0, s69
	s_nop 0
	global_load_lds_dwordx4 v[222:223], off
	s_waitcnt vmcnt(8)
	s_waitcnt lgkmcnt(0)
	s_barrier
; #define PG8_STAGE(bufoff, gbase, voff) do { _Pragma("unroll") for (int _i = 0; _i < 2; ++_i) \
;         __builtin_amdgcn_global_load_lds((const unsigned*)((const char*)(gbase) + (voff)[_i]), (PG8_LAS unsigned*)(lds + (bufoff) + ldsw + _i * 8192), 16, 0, 0); } while (0)
; #define PG8_LDA(dst, b, h) do { _Pragma("unroll") for (int m = 0; m < 4; ++m) _Pragma("unroll") for (int k = 0; k < 2; ++k) dst[m][k] = *(const PG8_LAS bf16x8*)(lds + PG8_SA(b, h) + aoff + m * 2048 + k * 1024); } while (0)
; #define PG8_LDB(dst, b, h) do { _Pragma("unroll") for (int n = 0; n < 2; ++n) _Pragma("unroll") for (int k = 0; k < 2; ++k) dst[n][k] = *(const PG8_LAS bf16x8*)(lds + PG8_SB(b, h) + boff + n * 2048 + k * 1024); } while (0)
; #define PG8_MMA(ai, bj, At, Bt) do { __builtin_amdgcn_s_setprio(1); _Pragma("unroll") for (int m = 0; m < 4; ++m) _Pragma("unroll") for (int n = 0; n < 2; ++n) _Pragma("unroll") for (int k = 0; k < 2; ++k) \
;         acc[ai][bj][m][n] = __builtin_amdgcn_mfma_f32_16x16x32_bf16(Bt[n][k], At[m][k], acc[ai][bj][m][n], 0, 0, 0); __builtin_amdgcn_s_setprio(0); } while (0)
; #define PG8_WAIT_V(n) asm volatile("s_waitcnt vmcnt(" #n ")" ::: "memory")
; #define PG8_WAIT_L(n) asm volatile("s_waitcnt lgkmcnt(" #n ")" ::: "memory")
; #define PG8_BAR __builtin_amdgcn_s_barrier()
; #define PG8_SCHED __builtin_amdgcn_sched_barrier(0)
; template <class Epi, class Sched, bool ALIGN_EPI = false, bool SP2 = false>
; __device__ __forceinline__ void gemm_phase(PG8_LAS unsigned char* lds, const Gemm g, const Sched& S, const Epi& E, const int wv  ) {
;     ...
;             PG8_WAIT_V(8); PG8_WAIT_L(0); PG8_BAR; PG8_MMA(1, 0, At, B0); PG8_MMA(1, 1, At, B1); PG8_BAR; PG8_SCHED;
;             PG8_LDB(B0, 1, 0); PG8_LDB(B1, 1, 1); PG8_SCHED; PG8_LDA(At, 1, 0); PG8_STAGE(PG8_SA(0, 1), a2 + hstepA, voffA);
;             PG8_WAIT_V(8); PG8_WAIT_L(0); PG8_BAR; PG8_MMA(0, 0, At, B0); PG8_MMA(0, 1, At, B1); PG8_BAR; PG8_SCHED;
	s_setprio 1
	s_waitcnt lgkmcnt(0)
	v_mfma_f32_16x16x32_bf16 v[28:31], v[146:149], v[184:187], v[28:31]
	v_mfma_f32_16x16x32_bf16 v[24:27], v[160:163], v[184:187], v[24:27]
	v_mfma_f32_16x16x32_bf16 v[20:23], v[146:149], v[192:195], v[20:23]
	v_mfma_f32_16x16x32_bf16 v[16:19], v[160:163], v[192:195], v[16:19]
	v_mfma_f32_16x16x32_bf16 v[12:15], v[146:149], v[200:203], v[12:15]
	v_mfma_f32_16x16x32_bf16 v[8:11], v[160:163], v[200:203], v[8:11]
	v_mfma_f32_16x16x32_bf16 v[4:7], v[146:149], v[208:211], v[4:7]
	v_mfma_f32_16x16x32_bf16 v[0:3], v[160:163], v[208:211], v[0:3]
	v_mfma_f32_16x16x32_bf16 v[28:31], v[156:159], v[188:191], v[28:31]
	v_mfma_f32_16x16x32_bf16 v[24:27], v[164:167], v[188:191], v[24:27]
	v_mfma_f32_16x16x32_bf16 v[20:23], v[156:159], v[196:199], v[20:23]
	v_mfma_f32_16x16x32_bf16 v[16:19], v[164:167], v[196:199], v[16:19]
	v_mfma_f32_16x16x32_bf16 v[12:15], v[156:159], v[204:207], v[12:15]
	v_mfma_f32_16x16x32_bf16 v[8:11], v[164:167], v[204:207], v[8:11]
	v_mfma_f32_16x16x32_bf16 v[4:7], v[156:159], v[212:215], v[4:7]
	v_mfma_f32_16x16x32_bf16 v[0:3], v[164:167], v[212:215], v[0:3]
	s_setprio 0
	s_setprio 1
	v_mfma_f32_16x16x32_bf16 v[92:95], v[168:171], v[184:187], v[92:95]
	v_mfma_f32_16x16x32_bf16 v[88:91], v[176:179], v[184:187], v[88:91]
	v_mfma_f32_16x16x32_bf16 v[84:87], v[168:171], v[192:195], v[84:87]
	v_mfma_f32_16x16x32_bf16 v[80:83], v[176:179], v[192:195], v[80:83]
	v_mfma_f32_16x16x32_bf16 v[60:63], v[168:171], v[200:203], v[60:63]
	v_mfma_f32_16x16x32_bf16 v[48:51], v[176:179], v[200:203], v[48:51]
	v_mfma_f32_16x16x32_bf16 v[36:39], v[168:171], v[208:211], v[36:39]
	v_mfma_f32_16x16x32_bf16 v[32:35], v[176:179], v[208:211], v[32:35]
	v_mfma_f32_16x16x32_bf16 v[92:95], v[172:175], v[188:191], v[92:95]
	v_mfma_f32_16x16x32_bf16 v[88:91], v[180:183], v[188:191], v[88:91]
	v_mfma_f32_16x16x32_bf16 v[84:87], v[172:175], v[196:199], v[84:87]
	v_mfma_f32_16x16x32_bf16 v[80:83], v[180:183], v[196:199], v[80:83]
	v_mfma_f32_16x16x32_bf16 v[60:63], v[172:175], v[204:207], v[60:63]
	v_mfma_f32_16x16x32_bf16 v[48:51], v[180:183], v[204:207], v[48:51]
	s_setprio 2
	s_barrier
	v_mfma_f32_16x16x32_bf16 v[36:39], v[172:175], v[212:215], v[36:39]
	v_mfma_f32_16x16x32_bf16 v[32:35], v[180:183], v[212:215], v[32:35]
	s_setprio 0
	s_add_i32 s90, 0, 0x18000
	v_add_u32_e32 v155, s90, v150
	s_add_i32 s91, 0, 0x1c000
	ds_read_b128 v[146:149], v155
	ds_read_b128 v[156:159], v155 offset:1024
	ds_read_b128 v[160:163], v155 offset:2048
	ds_read_b128 v[164:167], v155 offset:3072
	v_add_u32_e32 v155, s91, v150
	ds_read_b128 v[168:171], v155
	ds_read_b128 v[172:175], v155 offset:1024
	ds_read_b128 v[176:179], v155 offset:2048
	ds_read_b128 v[180:183], v155 offset:3072
	s_add_u32 s62, s62, 0x100000
	s_addc_u32 s63, s63, 0
	s_mov_b32 m0, s70
	v_lshl_add_u64 v[224:225], s[62:63], 0, v[128:129]
	ds_read_b128 v[184:187], v154 offset:32768
	ds_read_b128 v[188:191], v154 offset:33792
	ds_read_b128 v[192:195], v154 offset:34816
	ds_read_b128 v[196:199], v154 offset:35840
	ds_read_b128 v[200:203], v154 offset:36864
	ds_read_b128 v[204:207], v154 offset:37888
	ds_read_b128 v[208:211], v154 offset:38912
	ds_read_b128 v[212:215], v154 offset:39936
	global_load_lds_dwordx4 v[224:225], off
	v_lshl_add_u64 v[224:225], s[62:63], 0, v[132:133]
	s_mov_b32 m0, s71
	s_nop 0
	global_load_lds_dwordx4 v[224:225], off
	s_waitcnt vmcnt(8)
	s_waitcnt lgkmcnt(0)
	s_barrier
	s_setprio 1
	s_waitcnt lgkmcnt(0)
	v_mfma_f32_16x16x32_bf16 v[76:79], v[146:149], v[184:187], v[76:79]
	v_mfma_f32_16x16x32_bf16 v[72:75], v[160:163], v[184:187], v[72:75]
	v_mfma_f32_16x16x32_bf16 v[68:71], v[146:149], v[192:195], v[68:71]
	v_mfma_f32_16x16x32_bf16 v[64:67], v[160:163], v[192:195], v[64:67]
	v_mfma_f32_16x16x32_bf16 v[56:59], v[146:149], v[200:203], v[56:59]
	v_mfma_f32_16x16x32_bf16 v[52:55], v[160:163], v[200:203], v[52:55]
	v_mfma_f32_16x16x32_bf16 v[44:47], v[146:149], v[208:211], v[44:47]
	v_mfma_f32_16x16x32_bf16 v[40:43], v[160:163], v[208:211], v[40:43]
	v_mfma_f32_16x16x32_bf16 v[76:79], v[156:159], v[188:191], v[76:79]
	v_mfma_f32_16x16x32_bf16 v[72:75], v[164:167], v[188:191], v[72:75]
	v_mfma_f32_16x16x32_bf16 v[68:71], v[156:159], v[196:199], v[68:71]
	v_mfma_f32_16x16x32_bf16 v[64:67], v[164:167], v[196:199], v[64:67]
	v_mfma_f32_16x16x32_bf16 v[56:59], v[156:159], v[204:207], v[56:59]
	v_mfma_f32_16x16x32_bf16 v[52:55], v[164:167], v[204:207], v[52:55]
	v_mfma_f32_16x16x32_bf16 v[44:47], v[156:159], v[212:215], v[44:47]
	v_mfma_f32_16x16x32_bf16 v[40:43], v[164:167], v[212:215], v[40:43]
	s_setprio 0
	s_setprio 1
	v_mfma_f32_16x16x32_bf16 v[124:127], v[168:171], v[184:187], v[124:127]
	v_mfma_f32_16x16x32_bf16 v[120:123], v[176:179], v[184:187], v[120:123]
	v_mfma_f32_16x16x32_bf16 v[116:119], v[168:171], v[192:195], v[116:119]
	v_mfma_f32_16x16x32_bf16 v[112:115], v[176:179], v[192:195], v[112:115]
	v_mfma_f32_16x16x32_bf16 v[108:111], v[168:171], v[200:203], v[108:111]
	v_mfma_f32_16x16x32_bf16 v[104:107], v[176:179], v[200:203], v[104:107]
	v_mfma_f32_16x16x32_bf16 v[100:103], v[168:171], v[208:211], v[100:103]
	v_mfma_f32_16x16x32_bf16 v[96:99], v[176:179], v[208:211], v[96:99]
	v_mfma_f32_16x16x32_bf16 v[124:127], v[172:175], v[188:191], v[124:127]
	v_mfma_f32_16x16x32_bf16 v[120:123], v[180:183], v[188:191], v[120:123]
	v_mfma_f32_16x16x32_bf16 v[116:119], v[172:175], v[196:199], v[116:119]
	v_mfma_f32_16x16x32_bf16 v[112:115], v[180:183], v[196:199], v[112:115]
	v_mfma_f32_16x16x32_bf16 v[108:111], v[172:175], v[204:207], v[108:111]
	v_mfma_f32_16x16x32_bf16 v[104:107], v[180:183], v[204:207], v[104:107]
	s_setprio 2
	s_barrier
; #define PG8_STAGE(bufoff, gbase, voff) do { _Pragma("unroll") for (int _i = 0; _i < 2; ++_i) \
;         __builtin_amdgcn_global_load_lds((const unsigned*)((const char*)(gbase) + (voff)[_i]), (PG8_LAS unsigned*)(lds + (bufoff) + ldsw + _i * 8192), 16, 0, 0); } while (0)
; #define PG8_LDA(dst, b, h) do { _Pragma("unroll") for (int m = 0; m < 4; ++m) _Pragma("unroll") for (int k = 0; k < 2; ++k) dst[m][k] = *(const PG8_LAS bf16x8*)(lds + PG8_SA(b, h) + aoff + m * 2048 + k * 1024); } while (0)
; #define PG8_MMA(ai, bj, At, Bt) do { __builtin_amdgcn_s_setprio(1); _Pragma("unroll") for (int m = 0; m < 4; ++m) _Pragma("unroll") for (int n = 0; n < 2; ++n) _Pragma("unroll") for (int k = 0; k < 2; ++k) \
;         acc[ai][bj][m][n] = __builtin_amdgcn_mfma_f32_16x16x32_bf16(Bt[n][k], At[m][k], acc[ai][bj][m][n], 0, 0, 0); __builtin_amdgcn_s_setprio(0); } while (0)
; #define PG8_WAIT_V(n) asm volatile("s_waitcnt vmcnt(" #n ")" ::: "memory")
; #define PG8_WAIT_L(n) asm volatile("s_waitcnt lgkmcnt(" #n ")" ::: "memory")
; #define PG8_BAR __builtin_amdgcn_s_barrier()
; #define PG8_SCHED __builtin_amdgcn_sched_barrier(0)
; template <class Epi, class Sched, bool ALIGN_EPI = false, bool SP2 = false>
; __device__ __forceinline__ void gemm_phase(PG8_LAS unsigned char* lds, const Gemm g, const Sched& S, const Epi& E, const int wv  ) {
;     ...
;             PG8_WAIT_V(8); PG8_WAIT_L(0); PG8_BAR; PG8_MMA(0, 0, At, B0); PG8_MMA(0, 1, At, B1); PG8_BAR; PG8_SCHED;
;             PG8_LDA(At, 1, 1); PG8_STAGE(PG8_SB(1, 0), b3, voffB); PG8_STAGE(PG8_SB(1, 1), b3 + hstepB, voffB); PG8_STAGE(PG8_SA(1, 0), a3, voffA);
;             PG8_WAIT_V(8); PG8_WAIT_L(0); PG8_BAR; PG8_MMA(1, 0, At, B0); PG8_MMA(1, 1, At, B1); PG8_BAR; PG8_SCHED;
;     ...
;         if constexpr (ALIGN_EPI) { if (wr == 0) PG8_BAR; }
	v_mfma_f32_16x16x32_bf16 v[100:103], v[172:175], v[212:215], v[100:103]
	v_mfma_f32_16x16x32_bf16 v[96:99], v[180:183], v[212:215], v[96:99]
	s_setprio 0
	s_add_i32 s62, s90, s67
	v_lshl_add_u64 v[216:217], v[216:217], 0, s[12:13]
	s_mov_b32 m0, s62
	ds_read_b128 v[184:187], v154 offset:49152
	ds_read_b128 v[188:191], v154 offset:50176
	ds_read_b128 v[192:195], v154 offset:51200
	ds_read_b128 v[196:199], v154 offset:52224
	ds_read_b128 v[200:203], v154 offset:53248
	ds_read_b128 v[204:207], v154 offset:54272
	ds_read_b128 v[208:211], v154 offset:55296
	ds_read_b128 v[212:215], v154 offset:56320
	global_load_lds_dwordx4 v[216:217], off
	s_add_i32 m0, s62, 0x2000
	s_add_u32 s60, s60, 0x100080
	v_lshl_add_u64 v[216:217], v[218:219], 0, s[12:13]
	s_addc_u32 s61, s61, 0
	s_add_i32 s62, s91, s67
	global_load_lds_dwordx4 v[216:217], off
	v_lshl_add_u64 v[216:217], s[60:61], 0, v[130:131]
	s_mov_b32 m0, s62
	s_nop 0
	global_load_lds_dwordx4 v[216:217], off
	v_lshl_add_u64 v[216:217], s[60:61], 0, v[134:135]
	s_add_i32 m0, s62, 0x2000
	s_nop 0
	global_load_lds_dwordx4 v[216:217], off
	v_lshl_add_u64 v[216:217], v[220:221], 0, s[12:13]
	s_mov_b32 m0, s74
	s_nop 0
	global_load_lds_dwordx4 v[216:217], off
	v_lshl_add_u64 v[216:217], v[222:223], 0, s[12:13]
	s_mov_b32 m0, s75
	s_nop 0
	global_load_lds_dwordx4 v[216:217], off
	s_waitcnt vmcnt(8)
	s_waitcnt lgkmcnt(0)
	s_barrier
	s_setprio 1
	s_waitcnt lgkmcnt(0)
	v_mfma_f32_16x16x32_bf16 v[28:31], v[146:149], v[184:187], v[28:31]
	v_mfma_f32_16x16x32_bf16 v[24:27], v[160:163], v[184:187], v[24:27]
	v_mfma_f32_16x16x32_bf16 v[20:23], v[146:149], v[192:195], v[20:23]
	v_mfma_f32_16x16x32_bf16 v[16:19], v[160:163], v[192:195], v[16:19]
	v_mfma_f32_16x16x32_bf16 v[12:15], v[146:149], v[200:203], v[12:15]
	v_mfma_f32_16x16x32_bf16 v[8:11], v[160:163], v[200:203], v[8:11]
	v_mfma_f32_16x16x32_bf16 v[4:7], v[146:149], v[208:211], v[4:7]
	v_mfma_f32_16x16x32_bf16 v[0:3], v[160:163], v[208:211], v[0:3]
	v_mfma_f32_16x16x32_bf16 v[28:31], v[156:159], v[188:191], v[28:31]
	v_mfma_f32_16x16x32_bf16 v[24:27], v[164:167], v[188:191], v[24:27]
	v_mfma_f32_16x16x32_bf16 v[20:23], v[156:159], v[196:199], v[20:23]
	v_mfma_f32_16x16x32_bf16 v[16:19], v[164:167], v[196:199], v[16:19]
	v_mfma_f32_16x16x32_bf16 v[12:15], v[156:159], v[204:207], v[12:15]
	v_mfma_f32_16x16x32_bf16 v[8:11], v[164:167], v[204:207], v[8:11]
	v_mfma_f32_16x16x32_bf16 v[4:7], v[156:159], v[212:215], v[4:7]
	v_mfma_f32_16x16x32_bf16 v[0:3], v[164:167], v[212:215], v[0:3]
	s_setprio 0
	s_setprio 1
	v_mfma_f32_16x16x32_bf16 v[92:95], v[168:171], v[184:187], v[92:95]
	v_mfma_f32_16x16x32_bf16 v[88:91], v[176:179], v[184:187], v[88:91]
	v_mfma_f32_16x16x32_bf16 v[84:87], v[168:171], v[192:195], v[84:87]
	v_mfma_f32_16x16x32_bf16 v[80:83], v[176:179], v[192:195], v[80:83]
	v_mfma_f32_16x16x32_bf16 v[60:63], v[168:171], v[200:203], v[60:63]
	v_mfma_f32_16x16x32_bf16 v[48:51], v[176:179], v[200:203], v[48:51]
	v_mfma_f32_16x16x32_bf16 v[36:39], v[168:171], v[208:211], v[36:39]
	v_mfma_f32_16x16x32_bf16 v[32:35], v[176:179], v[208:211], v[32:35]
	v_mfma_f32_16x16x32_bf16 v[92:95], v[172:175], v[188:191], v[92:95]
	v_mfma_f32_16x16x32_bf16 v[88:91], v[180:183], v[188:191], v[88:91]
	v_mfma_f32_16x16x32_bf16 v[84:87], v[172:175], v[196:199], v[84:87]
	v_mfma_f32_16x16x32_bf16 v[80:83], v[180:183], v[196:199], v[80:83]
	v_mfma_f32_16x16x32_bf16 v[60:63], v[172:175], v[204:207], v[60:63]
	v_mfma_f32_16x16x32_bf16 v[48:51], v[180:183], v[204:207], v[48:51]
	s_setprio 2
	s_barrier
	v_mfma_f32_16x16x32_bf16 v[36:39], v[172:175], v[212:215], v[36:39]
	v_mfma_f32_16x16x32_bf16 v[32:35], v[180:183], v[212:215], v[32:35]
	s_setprio 0
	s_add_i32 s87, s87, 2
	s_add_u32 s58, s58, 0x100
	s_addc_u32 s59, s59, 0
	s_add_u32 s85, s85, 0x100
	s_addc_u32 s86, s86, 0
	s_cmp_gt_u32 s87, 61
	s_cbranch_scc0 .LBB0_706
	s_and_b64 vcc, exec, s[14:15]
	s_cbranch_vccz .LBB0_709
	s_barrier

; #define PG8_STAGE(bufoff, gbase, voff) do { _Pragma("unroll") for (int _i = 0; _i < 2; ++_i) \
;         __builtin_amdgcn_global_load_lds((const unsigned*)((const char*)(gbase) + (voff)[_i]), (PG8_LAS unsigned*)(lds + (bufoff) + ldsw + _i * 8192), 16, 0, 0); } while (0)
; #define PG8_LDA(dst, b, h) do { _Pragma("unroll") for (int m = 0; m < 4; ++m) _Pragma("unroll") for (int k = 0; k < 2; ++k) dst[m][k] = *(const PG8_LAS bf16x8*)(lds + PG8_SA(b, h) + aoff + m * 2048 + k * 1024); } while (0)
; #define PG8_LDB(dst, b, h) do { _Pragma("unroll") for (int n = 0; n < 2; ++n) _Pragma("unroll") for (int k = 0; k < 2; ++k) dst[n][k] = *(const PG8_LAS bf16x8*)(lds + PG8_SB(b, h) + boff + n * 2048 + k * 1024); } while (0)
; #define PG8_MMA(ai, bj, At, Bt) do { __builtin_amdgcn_s_setprio(1); _Pragma("unroll") for (int m = 0; m < 4; ++m) _Pragma("unroll") for (int n = 0; n < 2; ++n) _Pragma("unroll") for (int k = 0; k < 2; ++k) \
;         acc[ai][bj][m][n] = __builtin_amdgcn_mfma_f32_16x16x32_bf16(Bt[n][k], At[m][k], acc[ai][bj][m][n], 0, 0, 0); __builtin_amdgcn_s_setprio(0); } while (0)
; #define PG8_WAIT_V(n) asm volatile("s_waitcnt vmcnt(" #n ")" ::: "memory")
; #define PG8_BAR __builtin_amdgcn_s_barrier()
; template <class Epi, class Sched, bool ALIGN_EPI = false, bool SP2 = false>
; __device__ __forceinline__ void gemm_phase(PG8_LAS unsigned char* lds, const Gemm g, const Sched& S, const Epi& E, const int wv  ) {
;     ...
;         for (int t = 0; t < nt; t += 2) {
;             const bool last = (t == nt - 2);
;             const char* a1 = cA + (size_t)(t + 1) * kstep;
;             const char* a2 = last ? nA : cA + (size_t)(t + 2) * kstep; const char* b2 = last ? nB : cB + (size_t)(t + 2) * kstep;
;             const char* a3 = a2 + kstep; const char* b3 = b2 + kstep;
;             if (last && has_next) S.a_ready(nxt);
;             if constexpr (SP2) {
;             PG8_LDB(B0, 0, 0); PG8_LDB(B1, 0, 1); PG8_SCHED; PG8_LDA(At, 0, 0); PG8_STAGE(PG8_SA(1, 1), a1 + hstepA, voffA);
;             PG8_WAIT_V(8); PG8_WAIT_L(0); PG8_BAR; PG8_MMA(0, 0, At, B0); PG8_MMA(0, 1, At, B1); PG8_BAR; PG8_SCHED;
;             PG8_LDA(At, 0, 1); PG8_STAGE(PG8_SB(0, 0), b2, voffB); PG8_STAGE(PG8_SB(0, 1), b2 + hstepB, voffB); PG8_STAGE(PG8_SA(0, 0), a2, voffA);
;             PG8_WAIT_V(8); PG8_WAIT_L(0); PG8_BAR; PG8_MMA(1, 0, At, B0); PG8_MMA(1, 1, At, B1); PG8_BAR; PG8_SCHED;
.LBB0_850:
	ds_read_b128 v[146:149], v152
	ds_read_b128 v[156:159], v152 offset:1024
	ds_read_b128 v[160:163], v152 offset:2048
	ds_read_b128 v[164:167], v152 offset:3072
	ds_read_b128 v[168:171], v153
	ds_read_b128 v[172:175], v153 offset:1024
	ds_read_b128 v[176:179], v153 offset:2048
	ds_read_b128 v[180:183], v153 offset:3072
	s_add_u32 s60, s58, 0xfff00080
	s_addc_u32 s61, s59, -1
	s_cmp_eq_u32 s92, 60
	s_cselect_b32 s63, s51, s61
	s_cselect_b32 s62, s86, s60
	s_cselect_b32 s61, s49, s91
	s_cselect_b32 s60, s87, s90
	v_lshl_add_u64 v[216:217], s[58:59], 0, v[138:139]
	s_add_i32 m0, s71, 0xc000
	ds_read_b128 v[184:187], v154
	ds_read_b128 v[188:191], v154 offset:1024
	ds_read_b128 v[192:195], v154 offset:2048
	ds_read_b128 v[196:199], v154 offset:3072
	ds_read_b128 v[200:203], v154 offset:4096
	ds_read_b128 v[204:207], v154 offset:5120
	ds_read_b128 v[208:211], v154 offset:6144
	ds_read_b128 v[212:215], v154 offset:7168
	global_load_lds_dwordx4 v[216:217], off
	v_lshl_add_u64 v[216:217], s[58:59], 0, v[140:141]
	s_add_i32 m0, s71, 0xe000
	s_nop 0
	global_load_lds_dwordx4 v[216:217], off
	s_waitcnt vmcnt(8)
	s_waitcnt lgkmcnt(0)
	s_barrier
	s_setprio 1
	s_waitcnt lgkmcnt(0)
	v_mfma_f32_16x16x32_bf16 v[76:79], v[146:149], v[184:187], v[76:79]
	v_mfma_f32_16x16x32_bf16 v[72:75], v[160:163], v[184:187], v[72:75]
	v_mfma_f32_16x16x32_bf16 v[68:71], v[146:149], v[192:195], v[68:71]
	v_mfma_f32_16x16x32_bf16 v[64:67], v[160:163], v[192:195], v[64:67]
	v_mfma_f32_16x16x32_bf16 v[56:59], v[146:149], v[200:203], v[56:59]
	v_mfma_f32_16x16x32_bf16 v[52:55], v[160:163], v[200:203], v[52:55]
	v_mfma_f32_16x16x32_bf16 v[44:47], v[146:149], v[208:211], v[44:47]
	v_mfma_f32_16x16x32_bf16 v[40:43], v[160:163], v[208:211], v[40:43]
	v_mfma_f32_16x16x32_bf16 v[76:79], v[156:159], v[188:191], v[76:79]
	v_mfma_f32_16x16x32_bf16 v[72:75], v[164:167], v[188:191], v[72:75]
	v_mfma_f32_16x16x32_bf16 v[68:71], v[156:159], v[196:199], v[68:71]
	v_mfma_f32_16x16x32_bf16 v[64:67], v[164:167], v[196:199], v[64:67]
	v_mfma_f32_16x16x32_bf16 v[56:59], v[156:159], v[204:207], v[56:59]
	v_mfma_f32_16x16x32_bf16 v[52:55], v[164:167], v[204:207], v[52:55]
	v_mfma_f32_16x16x32_bf16 v[44:47], v[156:159], v[212:215], v[44:47]
	v_mfma_f32_16x16x32_bf16 v[40:43], v[164:167], v[212:215], v[40:43]
	s_setprio 0
	s_setprio 1
	v_mfma_f32_16x16x32_bf16 v[124:127], v[168:171], v[184:187], v[124:127]
	v_mfma_f32_16x16x32_bf16 v[120:123], v[176:179], v[184:187], v[120:123]
	v_mfma_f32_16x16x32_bf16 v[116:119], v[168:171], v[192:195], v[116:119]
	v_mfma_f32_16x16x32_bf16 v[112:115], v[176:179], v[192:195], v[112:115]
	v_mfma_f32_16x16x32_bf16 v[108:111], v[168:171], v[200:203], v[108:111]
	v_mfma_f32_16x16x32_bf16 v[104:107], v[176:179], v[200:203], v[104:107]
	v_mfma_f32_16x16x32_bf16 v[100:103], v[168:171], v[208:211], v[100:103]
	v_mfma_f32_16x16x32_bf16 v[96:99], v[176:179], v[208:211], v[96:99]
	v_mfma_f32_16x16x32_bf16 v[124:127], v[172:175], v[188:191], v[124:127]
	v_mfma_f32_16x16x32_bf16 v[120:123], v[180:183], v[188:191], v[120:123]
	v_mfma_f32_16x16x32_bf16 v[116:119], v[172:175], v[196:199], v[116:119]
	v_mfma_f32_16x16x32_bf16 v[112:115], v[180:183], v[196:199], v[112:115]
	v_mfma_f32_16x16x32_bf16 v[108:111], v[172:175], v[204:207], v[108:111]
	v_mfma_f32_16x16x32_bf16 v[104:107], v[180:183], v[204:207], v[104:107]
	s_setprio 2
	s_barrier
	v_mfma_f32_16x16x32_bf16 v[100:103], v[172:175], v[212:215], v[100:103]
	v_mfma_f32_16x16x32_bf16 v[96:99], v[180:183], v[212:215], v[96:99]
	s_setprio 0
	s_add_i32 s93, s80, s70
	v_lshl_add_u64 v[216:217], s[60:61], 0, v[130:131]
	s_mov_b32 m0, s93
	ds_read_b128 v[184:187], v154 offset:16384
	ds_read_b128 v[188:191], v154 offset:17408
	ds_read_b128 v[192:195], v154 offset:18432
	ds_read_b128 v[196:199], v154 offset:19456
	ds_read_b128 v[200:203], v154 offset:20480
	ds_read_b128 v[204:207], v154 offset:21504
	ds_read_b128 v[208:211], v154 offset:22528
	ds_read_b128 v[212:215], v154 offset:23552
	global_load_lds_dwordx4 v[216:217], off
	s_add_i32 m0, s93, 0x2000
	s_add_u32 s94, s60, 0x100000
	v_lshl_add_u64 v[218:219], s[60:61], 0, v[134:135]
	s_addc_u32 s95, s61, 0
	s_add_i32 s93, s81, s70
	global_load_lds_dwordx4 v[218:219], off
	v_lshl_add_u64 v[220:221], s[94:95], 0, v[130:131]
	s_mov_b32 m0, s93
	v_lshl_add_u64 v[222:223], s[62:63], 0, v[132:133]
	global_load_lds_dwordx4 v[220:221], off
	v_lshl_add_u64 v[220:221], s[94:95], 0, v[134:135]
	s_add_i32 m0, s93, 0x2000
	s_nop 0
	global_load_lds_dwordx4 v[220:221], off
	v_lshl_add_u64 v[220:221], s[62:63], 0, v[128:129]
	s_mov_b32 m0, s71
	s_nop 0
	global_load_lds_dwordx4 v[220:221], off
	s_mov_b32 m0, s72
	s_nop 0
	global_load_lds_dwordx4 v[222:223], off
	s_waitcnt vmcnt(8)
	s_waitcnt lgkmcnt(0)
	s_barrier
; #define PG8_STAGE(bufoff, gbase, voff) do { _Pragma("unroll") for (int _i = 0; _i < 2; ++_i) \
;         __builtin_amdgcn_global_load_lds((const unsigned*)((const char*)(gbase) + (voff)[_i]), (PG8_LAS unsigned*)(lds + (bufoff) + ldsw + _i * 8192), 16, 0, 0); } while (0)
; #define PG8_LDA(dst, b, h) do { _Pragma("unroll") for (int m = 0; m < 4; ++m) _Pragma("unroll") for (int k = 0; k < 2; ++k) dst[m][k] = *(const PG8_LAS bf16x8*)(lds + PG8_SA(b, h) + aoff + m * 2048 + k * 1024); } while (0)
; #define PG8_LDB(dst, b, h) do { _Pragma("unroll") for (int n = 0; n < 2; ++n) _Pragma("unroll") for (int k = 0; k < 2; ++k) dst[n][k] = *(const PG8_LAS bf16x8*)(lds + PG8_SB(b, h) + boff + n * 2048 + k * 1024); } while (0)
; #define PG8_MMA(ai, bj, At, Bt) do { __builtin_amdgcn_s_setprio(1); _Pragma("unroll") for (int m = 0; m < 4; ++m) _Pragma("unroll") for (int n = 0; n < 2; ++n) _Pragma("unroll") for (int k = 0; k < 2; ++k) \
;         acc[ai][bj][m][n] = __builtin_amdgcn_mfma_f32_16x16x32_bf16(Bt[n][k], At[m][k], acc[ai][bj][m][n], 0, 0, 0); __builtin_amdgcn_s_setprio(0); } while (0)
; #define PG8_WAIT_V(n) asm volatile("s_waitcnt vmcnt(" #n ")" ::: "memory")
; #define PG8_WAIT_L(n) asm volatile("s_waitcnt lgkmcnt(" #n ")" ::: "memory")
; #define PG8_BAR __builtin_amdgcn_s_barrier()
; #define PG8_SCHED __builtin_amdgcn_sched_barrier(0)
; template <class Epi, class Sched, bool ALIGN_EPI = false, bool SP2 = false>
; __device__ __forceinline__ void gemm_phase(PG8_LAS unsigned char* lds, const Gemm g, const Sched& S, const Epi& E, const int wv  ) {
;     ...
;             PG8_WAIT_V(8); PG8_WAIT_L(0); PG8_BAR; PG8_MMA(1, 0, At, B0); PG8_MMA(1, 1, At, B1); PG8_BAR; PG8_SCHED;
;             PG8_LDB(B0, 1, 0); PG8_LDB(B1, 1, 1); PG8_SCHED; PG8_LDA(At, 1, 0); PG8_STAGE(PG8_SA(0, 1), a2 + hstepA, voffA);
;             PG8_WAIT_V(8); PG8_WAIT_L(0); PG8_BAR; PG8_MMA(0, 0, At, B0); PG8_MMA(0, 1, At, B1); PG8_BAR; PG8_SCHED;
	s_setprio 1
	s_waitcnt lgkmcnt(0)
	v_mfma_f32_16x16x32_bf16 v[28:31], v[146:149], v[184:187], v[28:31]
	v_mfma_f32_16x16x32_bf16 v[24:27], v[160:163], v[184:187], v[24:27]
	v_mfma_f32_16x16x32_bf16 v[20:23], v[146:149], v[192:195], v[20:23]
	v_mfma_f32_16x16x32_bf16 v[16:19], v[160:163], v[192:195], v[16:19]
	v_mfma_f32_16x16x32_bf16 v[12:15], v[146:149], v[200:203], v[12:15]
	v_mfma_f32_16x16x32_bf16 v[8:11], v[160:163], v[200:203], v[8:11]
	v_mfma_f32_16x16x32_bf16 v[4:7], v[146:149], v[208:211], v[4:7]
	v_mfma_f32_16x16x32_bf16 v[0:3], v[160:163], v[208:211], v[0:3]
	v_mfma_f32_16x16x32_bf16 v[28:31], v[156:159], v[188:191], v[28:31]
	v_mfma_f32_16x16x32_bf16 v[24:27], v[164:167], v[188:191], v[24:27]
	v_mfma_f32_16x16x32_bf16 v[20:23], v[156:159], v[196:199], v[20:23]
	v_mfma_f32_16x16x32_bf16 v[16:19], v[164:167], v[196:199], v[16:19]
	v_mfma_f32_16x16x32_bf16 v[12:15], v[156:159], v[204:207], v[12:15]
	v_mfma_f32_16x16x32_bf16 v[8:11], v[164:167], v[204:207], v[8:11]
	v_mfma_f32_16x16x32_bf16 v[4:7], v[156:159], v[212:215], v[4:7]
	v_mfma_f32_16x16x32_bf16 v[0:3], v[164:167], v[212:215], v[0:3]
	s_setprio 0
	s_setprio 1
	v_mfma_f32_16x16x32_bf16 v[92:95], v[168:171], v[184:187], v[92:95]
	v_mfma_f32_16x16x32_bf16 v[88:91], v[176:179], v[184:187], v[88:91]
	v_mfma_f32_16x16x32_bf16 v[84:87], v[168:171], v[192:195], v[84:87]
	v_mfma_f32_16x16x32_bf16 v[80:83], v[176:179], v[192:195], v[80:83]
	v_mfma_f32_16x16x32_bf16 v[60:63], v[168:171], v[200:203], v[60:63]
	v_mfma_f32_16x16x32_bf16 v[48:51], v[176:179], v[200:203], v[48:51]
	v_mfma_f32_16x16x32_bf16 v[36:39], v[168:171], v[208:211], v[36:39]
	v_mfma_f32_16x16x32_bf16 v[32:35], v[176:179], v[208:211], v[32:35]
	v_mfma_f32_16x16x32_bf16 v[92:95], v[172:175], v[188:191], v[92:95]
	v_mfma_f32_16x16x32_bf16 v[88:91], v[180:183], v[188:191], v[88:91]
	v_mfma_f32_16x16x32_bf16 v[84:87], v[172:175], v[196:199], v[84:87]
	v_mfma_f32_16x16x32_bf16 v[80:83], v[180:183], v[196:199], v[80:83]
	v_mfma_f32_16x16x32_bf16 v[60:63], v[172:175], v[204:207], v[60:63]
	v_mfma_f32_16x16x32_bf16 v[48:51], v[180:183], v[204:207], v[48:51]
	s_setprio 2
	s_barrier
	v_mfma_f32_16x16x32_bf16 v[36:39], v[172:175], v[212:215], v[36:39]
	v_mfma_f32_16x16x32_bf16 v[32:35], v[180:183], v[212:215], v[32:35]
	s_setprio 0
	s_add_i32 s93, 0, 0x18000
	v_add_u32_e32 v155, s93, v150
	s_add_i32 s94, 0, 0x1c000
	ds_read_b128 v[146:149], v155
	ds_read_b128 v[156:159], v155 offset:1024
	ds_read_b128 v[160:163], v155 offset:2048
	ds_read_b128 v[164:167], v155 offset:3072
	v_add_u32_e32 v155, s94, v150
	ds_read_b128 v[168:171], v155
	ds_read_b128 v[172:175], v155 offset:1024
	ds_read_b128 v[176:179], v155 offset:2048
	ds_read_b128 v[180:183], v155 offset:3072
	s_add_u32 s62, s62, 0x100000
	s_addc_u32 s63, s63, 0
	s_mov_b32 m0, s73
	v_lshl_add_u64 v[224:225], s[62:63], 0, v[128:129]
	ds_read_b128 v[184:187], v154 offset:32768
	ds_read_b128 v[188:191], v154 offset:33792
	ds_read_b128 v[192:195], v154 offset:34816
	ds_read_b128 v[196:199], v154 offset:35840
	ds_read_b128 v[200:203], v154 offset:36864
	ds_read_b128 v[204:207], v154 offset:37888
	ds_read_b128 v[208:211], v154 offset:38912
	ds_read_b128 v[212:215], v154 offset:39936
	global_load_lds_dwordx4 v[224:225], off
	v_lshl_add_u64 v[224:225], s[62:63], 0, v[132:133]
	s_mov_b32 m0, s74
	s_nop 0
	global_load_lds_dwordx4 v[224:225], off
	s_waitcnt vmcnt(8)
	s_waitcnt lgkmcnt(0)
	s_barrier
	s_setprio 1
	s_waitcnt lgkmcnt(0)
	v_mfma_f32_16x16x32_bf16 v[76:79], v[146:149], v[184:187], v[76:79]
	v_mfma_f32_16x16x32_bf16 v[72:75], v[160:163], v[184:187], v[72:75]
	v_mfma_f32_16x16x32_bf16 v[68:71], v[146:149], v[192:195], v[68:71]
	v_mfma_f32_16x16x32_bf16 v[64:67], v[160:163], v[192:195], v[64:67]
	v_mfma_f32_16x16x32_bf16 v[56:59], v[146:149], v[200:203], v[56:59]
	v_mfma_f32_16x16x32_bf16 v[52:55], v[160:163], v[200:203], v[52:55]
	v_mfma_f32_16x16x32_bf16 v[44:47], v[146:149], v[208:211], v[44:47]
	v_mfma_f32_16x16x32_bf16 v[40:43], v[160:163], v[208:211], v[40:43]
	v_mfma_f32_16x16x32_bf16 v[76:79], v[156:159], v[188:191], v[76:79]
	v_mfma_f32_16x16x32_bf16 v[72:75], v[164:167], v[188:191], v[72:75]
	v_mfma_f32_16x16x32_bf16 v[68:71], v[156:159], v[196:199], v[68:71]
	v_mfma_f32_16x16x32_bf16 v[64:67], v[164:167], v[196:199], v[64:67]
	v_mfma_f32_16x16x32_bf16 v[56:59], v[156:159], v[204:207], v[56:59]
	v_mfma_f32_16x16x32_bf16 v[52:55], v[164:167], v[204:207], v[52:55]
	v_mfma_f32_16x16x32_bf16 v[44:47], v[156:159], v[212:215], v[44:47]
	v_mfma_f32_16x16x32_bf16 v[40:43], v[164:167], v[212:215], v[40:43]
	s_setprio 0
	s_setprio 1
	v_mfma_f32_16x16x32_bf16 v[124:127], v[168:171], v[184:187], v[124:127]
	v_mfma_f32_16x16x32_bf16 v[120:123], v[176:179], v[184:187], v[120:123]
	v_mfma_f32_16x16x32_bf16 v[116:119], v[168:171], v[192:195], v[116:119]
	v_mfma_f32_16x16x32_bf16 v[112:115], v[176:179], v[192:195], v[112:115]
	v_mfma_f32_16x16x32_bf16 v[108:111], v[168:171], v[200:203], v[108:111]
	v_mfma_f32_16x16x32_bf16 v[104:107], v[176:179], v[200:203], v[104:107]
	v_mfma_f32_16x16x32_bf16 v[100:103], v[168:171], v[208:211], v[100:103]
	v_mfma_f32_16x16x32_bf16 v[96:99], v[176:179], v[208:211], v[96:99]
	v_mfma_f32_16x16x32_bf16 v[124:127], v[172:175], v[188:191], v[124:127]
	v_mfma_f32_16x16x32_bf16 v[120:123], v[180:183], v[188:191], v[120:123]
	v_mfma_f32_16x16x32_bf16 v[116:119], v[172:175], v[196:199], v[116:119]
	v_mfma_f32_16x16x32_bf16 v[112:115], v[180:183], v[196:199], v[112:115]
	v_mfma_f32_16x16x32_bf16 v[108:111], v[172:175], v[204:207], v[108:111]
	v_mfma_f32_16x16x32_bf16 v[104:107], v[180:183], v[204:207], v[104:107]
	s_setprio 2
	s_barrier
; #define PG8_STAGE(bufoff, gbase, voff) do { _Pragma("unroll") for (int _i = 0; _i < 2; ++_i) \
;         __builtin_amdgcn_global_load_lds((const unsigned*)((const char*)(gbase) + (voff)[_i]), (PG8_LAS unsigned*)(lds + (bufoff) + ldsw + _i * 8192), 16, 0, 0); } while (0)
; #define PG8_LDA(dst, b, h) do { _Pragma("unroll") for (int m = 0; m < 4; ++m) _Pragma("unroll") for (int k = 0; k < 2; ++k) dst[m][k] = *(const PG8_LAS bf16x8*)(lds + PG8_SA(b, h) + aoff + m * 2048 + k * 1024); } while (0)
; #define PG8_MMA(ai, bj, At, Bt) do { __builtin_amdgcn_s_setprio(1); _Pragma("unroll") for (int m = 0; m < 4; ++m) _Pragma("unroll") for (int n = 0; n < 2; ++n) _Pragma("unroll") for (int k = 0; k < 2; ++k) \
;         acc[ai][bj][m][n] = __builtin_amdgcn_mfma_f32_16x16x32_bf16(Bt[n][k], At[m][k], acc[ai][bj][m][n], 0, 0, 0); __builtin_amdgcn_s_setprio(0); } while (0)
; #define PG8_WAIT_V(n) asm volatile("s_waitcnt vmcnt(" #n ")" ::: "memory")
; #define PG8_WAIT_L(n) asm volatile("s_waitcnt lgkmcnt(" #n ")" ::: "memory")
; #define PG8_BAR __builtin_amdgcn_s_barrier()
; #define PG8_SCHED __builtin_amdgcn_sched_barrier(0)
; template <class Epi, class Sched, bool ALIGN_EPI = false, bool SP2 = false>
; __device__ __forceinline__ void gemm_phase(PG8_LAS unsigned char* lds, const Gemm g, const Sched& S, const Epi& E, const int wv  ) {
;     ...
;             PG8_WAIT_V(8); PG8_WAIT_L(0); PG8_BAR; PG8_MMA(0, 0, At, B0); PG8_MMA(0, 1, At, B1); PG8_BAR; PG8_SCHED;
;             PG8_LDA(At, 1, 1); PG8_STAGE(PG8_SB(1, 0), b3, voffB); PG8_STAGE(PG8_SB(1, 1), b3 + hstepB, voffB); PG8_STAGE(PG8_SA(1, 0), a3, voffA);
;             PG8_WAIT_V(8); PG8_WAIT_L(0); PG8_BAR; PG8_MMA(1, 0, At, B0); PG8_MMA(1, 1, At, B1); PG8_BAR; PG8_SCHED;
;     ...
;         if constexpr (ALIGN_EPI) { if (wr == 0) PG8_BAR; }
	v_mfma_f32_16x16x32_bf16 v[100:103], v[172:175], v[212:215], v[100:103]
	v_mfma_f32_16x16x32_bf16 v[96:99], v[180:183], v[212:215], v[96:99]
	s_setprio 0
	s_add_i32 s62, s93, s70
	v_lshl_add_u64 v[216:217], v[216:217], 0, s[10:11]
	s_mov_b32 m0, s62
	ds_read_b128 v[184:187], v154 offset:49152
	ds_read_b128 v[188:191], v154 offset:50176
	ds_read_b128 v[192:195], v154 offset:51200
	ds_read_b128 v[196:199], v154 offset:52224
	ds_read_b128 v[200:203], v154 offset:53248
	ds_read_b128 v[204:207], v154 offset:54272
	ds_read_b128 v[208:211], v154 offset:55296
	ds_read_b128 v[212:215], v154 offset:56320
	global_load_lds_dwordx4 v[216:217], off
	s_add_i32 m0, s62, 0x2000
	s_add_u32 s60, s60, 0x100080
	v_lshl_add_u64 v[216:217], v[218:219], 0, s[10:11]
	s_addc_u32 s61, s61, 0
	s_add_i32 s62, s94, s70
	global_load_lds_dwordx4 v[216:217], off
	v_lshl_add_u64 v[216:217], s[60:61], 0, v[130:131]
	s_mov_b32 m0, s62
	s_nop 0
	global_load_lds_dwordx4 v[216:217], off
	v_lshl_add_u64 v[216:217], s[60:61], 0, v[134:135]
	s_add_i32 m0, s62, 0x2000
	s_nop 0
	global_load_lds_dwordx4 v[216:217], off
	v_lshl_add_u64 v[216:217], v[220:221], 0, s[10:11]
	s_mov_b32 m0, s77
	s_nop 0
	global_load_lds_dwordx4 v[216:217], off
	v_lshl_add_u64 v[216:217], v[222:223], 0, s[10:11]
	s_mov_b32 m0, s78
	s_nop 0
	global_load_lds_dwordx4 v[216:217], off
	s_waitcnt vmcnt(8)
	s_waitcnt lgkmcnt(0)
	s_barrier
	s_setprio 1
	s_waitcnt lgkmcnt(0)
	v_mfma_f32_16x16x32_bf16 v[28:31], v[146:149], v[184:187], v[28:31]
	v_mfma_f32_16x16x32_bf16 v[24:27], v[160:163], v[184:187], v[24:27]
	v_mfma_f32_16x16x32_bf16 v[20:23], v[146:149], v[192:195], v[20:23]
	v_mfma_f32_16x16x32_bf16 v[16:19], v[160:163], v[192:195], v[16:19]
	v_mfma_f32_16x16x32_bf16 v[12:15], v[146:149], v[200:203], v[12:15]
	v_mfma_f32_16x16x32_bf16 v[8:11], v[160:163], v[200:203], v[8:11]
	v_mfma_f32_16x16x32_bf16 v[4:7], v[146:149], v[208:211], v[4:7]
	v_mfma_f32_16x16x32_bf16 v[0:3], v[160:163], v[208:211], v[0:3]
	v_mfma_f32_16x16x32_bf16 v[28:31], v[156:159], v[188:191], v[28:31]
	v_mfma_f32_16x16x32_bf16 v[24:27], v[164:167], v[188:191], v[24:27]
	v_mfma_f32_16x16x32_bf16 v[20:23], v[156:159], v[196:199], v[20:23]
	v_mfma_f32_16x16x32_bf16 v[16:19], v[164:167], v[196:199], v[16:19]
	v_mfma_f32_16x16x32_bf16 v[12:15], v[156:159], v[204:207], v[12:15]
	v_mfma_f32_16x16x32_bf16 v[8:11], v[164:167], v[204:207], v[8:11]
	v_mfma_f32_16x16x32_bf16 v[4:7], v[156:159], v[212:215], v[4:7]
	v_mfma_f32_16x16x32_bf16 v[0:3], v[164:167], v[212:215], v[0:3]
	s_setprio 0
	s_setprio 1
	v_mfma_f32_16x16x32_bf16 v[92:95], v[168:171], v[184:187], v[92:95]
	v_mfma_f32_16x16x32_bf16 v[88:91], v[176:179], v[184:187], v[88:91]
	v_mfma_f32_16x16x32_bf16 v[84:87], v[168:171], v[192:195], v[84:87]
	v_mfma_f32_16x16x32_bf16 v[80:83], v[176:179], v[192:195], v[80:83]
	v_mfma_f32_16x16x32_bf16 v[60:63], v[168:171], v[200:203], v[60:63]
	v_mfma_f32_16x16x32_bf16 v[48:51], v[176:179], v[200:203], v[48:51]
	v_mfma_f32_16x16x32_bf16 v[36:39], v[168:171], v[208:211], v[36:39]
	v_mfma_f32_16x16x32_bf16 v[32:35], v[176:179], v[208:211], v[32:35]
	v_mfma_f32_16x16x32_bf16 v[92:95], v[172:175], v[188:191], v[92:95]
	v_mfma_f32_16x16x32_bf16 v[88:91], v[180:183], v[188:191], v[88:91]
	v_mfma_f32_16x16x32_bf16 v[84:87], v[172:175], v[196:199], v[84:87]
	v_mfma_f32_16x16x32_bf16 v[80:83], v[180:183], v[196:199], v[80:83]
	v_mfma_f32_16x16x32_bf16 v[60:63], v[172:175], v[204:207], v[60:63]
	v_mfma_f32_16x16x32_bf16 v[48:51], v[180:183], v[204:207], v[48:51]
	s_setprio 2
	s_barrier
	v_mfma_f32_16x16x32_bf16 v[36:39], v[172:175], v[212:215], v[36:39]
	v_mfma_f32_16x16x32_bf16 v[32:35], v[180:183], v[212:215], v[32:35]
	s_setprio 0
	s_add_i32 s92, s92, 2
	s_add_u32 s58, s58, 0x100
	s_addc_u32 s59, s59, 0
	s_add_u32 s90, s90, 0x100
	s_addc_u32 s91, s91, 0
	s_cmp_gt_u32 s92, 61
	s_cbranch_scc0 .LBB0_850
	s_and_b64 vcc, exec, s[12:13]
	s_cbranch_vccz .LBB0_853
	s_barrier

; #define PG8_STAGE(bufoff, gbase, voff) do { _Pragma("unroll") for (int _i = 0; _i < 2; ++_i) \
;         __builtin_amdgcn_global_load_lds((const unsigned*)((const char*)(gbase) + (voff)[_i]), (PG8_LAS unsigned*)(lds + (bufoff) + ldsw + _i * 8192), 16, 0, 0); } while (0)
; #define PG8_LDA(dst, b, h) do { _Pragma("unroll") for (int m = 0; m < 4; ++m) _Pragma("unroll") for (int k = 0; k < 2; ++k) dst[m][k] = *(const PG8_LAS bf16x8*)(lds + PG8_SA(b, h) + aoff + m * 2048 + k * 1024); } while (0)
; #define PG8_LDB(dst, b, h) do { _Pragma("unroll") for (int n = 0; n < 2; ++n) _Pragma("unroll") for (int k = 0; k < 2; ++k) dst[n][k] = *(const PG8_LAS bf16x8*)(lds + PG8_SB(b, h) + boff + n * 2048 + k * 1024); } while (0)
; #define PG8_MMA(ai, bj, At, Bt) do { __builtin_amdgcn_s_setprio(1); _Pragma("unroll") for (int m = 0; m < 4; ++m) _Pragma("unroll") for (int n = 0; n < 2; ++n) _Pragma("unroll") for (int k = 0; k < 2; ++k) \
;         acc[ai][bj][m][n] = __builtin_amdgcn_mfma_f32_16x16x32_bf16(Bt[n][k], At[m][k], acc[ai][bj][m][n], 0, 0, 0); __builtin_amdgcn_s_setprio(0); } while (0)
; #define PG8_WAIT_V(n) asm volatile("s_waitcnt vmcnt(" #n ")" ::: "memory")
; #define PG8_BAR __builtin_amdgcn_s_barrier()
; template <class Epi, class Sched, bool ALIGN_EPI = false, bool SP2 = false>
; __device__ __forceinline__ void gemm_phase(PG8_LAS unsigned char* lds, const Gemm g, const Sched& S, const Epi& E, const int wv  ) {
;     ...
;         for (int t = 0; t < nt; t += 2) {
;             const bool last = (t == nt - 2);
;             const char* a1 = cA + (size_t)(t + 1) * kstep;
;             const char* a2 = last ? nA : cA + (size_t)(t + 2) * kstep; const char* b2 = last ? nB : cB + (size_t)(t + 2) * kstep;
;             const char* a3 = a2 + kstep; const char* b3 = b2 + kstep;
;             if (last && has_next) S.a_ready(nxt);
;             if constexpr (SP2) {
;             PG8_LDB(B0, 0, 0); PG8_LDB(B1, 0, 1); PG8_SCHED; PG8_LDA(At, 0, 0); PG8_STAGE(PG8_SA(1, 1), a1 + hstepA, voffA);
;             PG8_WAIT_V(8); PG8_WAIT_L(0); PG8_BAR; PG8_MMA(0, 0, At, B0); PG8_MMA(0, 1, At, B1); PG8_BAR; PG8_SCHED;
;             PG8_LDA(At, 0, 1); PG8_STAGE(PG8_SB(0, 0), b2, voffB); PG8_STAGE(PG8_SB(0, 1), b2 + hstepB, voffB); PG8_STAGE(PG8_SA(0, 0), a2, voffA);
;             PG8_WAIT_V(8); PG8_WAIT_L(0); PG8_BAR; PG8_MMA(1, 0, At, B0); PG8_MMA(1, 1, At, B1); PG8_BAR; PG8_SCHED;
.LBB0_871:
	ds_read_b128 v[142:145], v148
	ds_read_b128 v[152:155], v148 offset:1024
	ds_read_b128 v[156:159], v148 offset:2048
	ds_read_b128 v[160:163], v148 offset:3072
	ds_read_b128 v[164:167], v149
	ds_read_b128 v[168:171], v149 offset:1024
	ds_read_b128 v[172:175], v149 offset:2048
	ds_read_b128 v[176:179], v149 offset:3072
	s_add_u32 s60, s58, 0xfff00080
	s_addc_u32 s61, s59, -1
	s_cmp_eq_u32 s96, 60
	s_cselect_b32 s63, s49, s61
	s_cselect_b32 s62, s92, s60
	s_cselect_b32 s61, s47, s95
	s_cselect_b32 s60, s93, s94
	v_lshl_add_u64 v[212:213], s[58:59], 0, v[138:139]
	s_add_i32 m0, s75, 0xc000
	ds_read_b128 v[180:183], v150
	ds_read_b128 v[184:187], v150 offset:1024
	ds_read_b128 v[188:191], v150 offset:2048
	ds_read_b128 v[192:195], v150 offset:3072
	ds_read_b128 v[196:199], v150 offset:4096
	ds_read_b128 v[200:203], v150 offset:5120
	ds_read_b128 v[204:207], v150 offset:6144
	ds_read_b128 v[208:211], v150 offset:7168
	global_load_lds_dwordx4 v[212:213], off
	v_lshl_add_u64 v[212:213], s[58:59], 0, v[140:141]
	s_add_i32 m0, s75, 0xe000
	s_nop 0
	global_load_lds_dwordx4 v[212:213], off
	s_waitcnt vmcnt(8)
	s_waitcnt lgkmcnt(0)
	s_barrier
	s_setprio 1
	s_waitcnt lgkmcnt(0)
	v_mfma_f32_16x16x32_bf16 v[76:79], v[142:145], v[180:183], v[76:79]
	v_mfma_f32_16x16x32_bf16 v[72:75], v[156:159], v[180:183], v[72:75]
	v_mfma_f32_16x16x32_bf16 v[68:71], v[142:145], v[188:191], v[68:71]
	v_mfma_f32_16x16x32_bf16 v[64:67], v[156:159], v[188:191], v[64:67]
	v_mfma_f32_16x16x32_bf16 v[56:59], v[142:145], v[196:199], v[56:59]
	v_mfma_f32_16x16x32_bf16 v[52:55], v[156:159], v[196:199], v[52:55]
	v_mfma_f32_16x16x32_bf16 v[44:47], v[142:145], v[204:207], v[44:47]
	v_mfma_f32_16x16x32_bf16 v[40:43], v[156:159], v[204:207], v[40:43]
	v_mfma_f32_16x16x32_bf16 v[76:79], v[152:155], v[184:187], v[76:79]
	v_mfma_f32_16x16x32_bf16 v[72:75], v[160:163], v[184:187], v[72:75]
	v_mfma_f32_16x16x32_bf16 v[68:71], v[152:155], v[192:195], v[68:71]
	v_mfma_f32_16x16x32_bf16 v[64:67], v[160:163], v[192:195], v[64:67]
	v_mfma_f32_16x16x32_bf16 v[56:59], v[152:155], v[200:203], v[56:59]
	v_mfma_f32_16x16x32_bf16 v[52:55], v[160:163], v[200:203], v[52:55]
	v_mfma_f32_16x16x32_bf16 v[44:47], v[152:155], v[208:211], v[44:47]
	v_mfma_f32_16x16x32_bf16 v[40:43], v[160:163], v[208:211], v[40:43]
	s_setprio 0
	s_setprio 1
	v_mfma_f32_16x16x32_bf16 v[124:127], v[164:167], v[180:183], v[124:127]
	v_mfma_f32_16x16x32_bf16 v[120:123], v[172:175], v[180:183], v[120:123]
	v_mfma_f32_16x16x32_bf16 v[116:119], v[164:167], v[188:191], v[116:119]
	v_mfma_f32_16x16x32_bf16 v[112:115], v[172:175], v[188:191], v[112:115]
	v_mfma_f32_16x16x32_bf16 v[108:111], v[164:167], v[196:199], v[108:111]
	v_mfma_f32_16x16x32_bf16 v[104:107], v[172:175], v[196:199], v[104:107]
	v_mfma_f32_16x16x32_bf16 v[100:103], v[164:167], v[204:207], v[100:103]
	v_mfma_f32_16x16x32_bf16 v[96:99], v[172:175], v[204:207], v[96:99]
	v_mfma_f32_16x16x32_bf16 v[124:127], v[168:171], v[184:187], v[124:127]
	v_mfma_f32_16x16x32_bf16 v[120:123], v[176:179], v[184:187], v[120:123]
	v_mfma_f32_16x16x32_bf16 v[116:119], v[168:171], v[192:195], v[116:119]
	v_mfma_f32_16x16x32_bf16 v[112:115], v[176:179], v[192:195], v[112:115]
	v_mfma_f32_16x16x32_bf16 v[108:111], v[168:171], v[200:203], v[108:111]
	v_mfma_f32_16x16x32_bf16 v[104:107], v[176:179], v[200:203], v[104:107]
	s_setprio 2
	s_barrier
	v_mfma_f32_16x16x32_bf16 v[100:103], v[168:171], v[208:211], v[100:103]
	v_mfma_f32_16x16x32_bf16 v[96:99], v[176:179], v[208:211], v[96:99]
	s_setprio 0
	s_add_i32 s97, s84, s73
	v_lshl_add_u64 v[212:213], s[60:61], 0, v[132:133]
	s_mov_b32 m0, s97
	ds_read_b128 v[180:183], v150 offset:16384
	ds_read_b128 v[184:187], v150 offset:17408
	ds_read_b128 v[188:191], v150 offset:18432
	ds_read_b128 v[192:195], v150 offset:19456
	ds_read_b128 v[196:199], v150 offset:20480
	ds_read_b128 v[200:203], v150 offset:21504
	ds_read_b128 v[204:207], v150 offset:22528
	ds_read_b128 v[208:211], v150 offset:23552
	global_load_lds_dwordx4 v[212:213], off
	s_add_i32 m0, s97, 0x2000
	s_add_u32 vcc_lo, s60, 0x100000
	v_lshl_add_u64 v[214:215], s[60:61], 0, v[128:129]
	s_addc_u32 vcc_hi, s61, 0
	s_add_i32 s97, s85, s73
	global_load_lds_dwordx4 v[214:215], off
	v_lshl_add_u64 v[216:217], vcc, 0, v[132:133]
	s_mov_b32 m0, s97
	v_lshl_add_u64 v[218:219], s[62:63], 0, v[130:131]
	global_load_lds_dwordx4 v[216:217], off
	v_lshl_add_u64 v[216:217], vcc, 0, v[128:129]
	s_add_i32 m0, s97, 0x2000
	s_nop 0
	global_load_lds_dwordx4 v[216:217], off
	v_lshl_add_u64 v[216:217], s[62:63], 0, v[134:135]
	s_mov_b32 m0, s75
	s_nop 0
	global_load_lds_dwordx4 v[216:217], off
	s_mov_b32 m0, s76
	s_nop 0
	global_load_lds_dwordx4 v[218:219], off
	s_waitcnt vmcnt(8)
	s_waitcnt lgkmcnt(0)
	s_barrier
; #define PG8_STAGE(bufoff, gbase, voff) do { _Pragma("unroll") for (int _i = 0; _i < 2; ++_i) \
;         __builtin_amdgcn_global_load_lds((const unsigned*)((const char*)(gbase) + (voff)[_i]), (PG8_LAS unsigned*)(lds + (bufoff) + ldsw + _i * 8192), 16, 0, 0); } while (0)
; #define PG8_LDA(dst, b, h) do { _Pragma("unroll") for (int m = 0; m < 4; ++m) _Pragma("unroll") for (int k = 0; k < 2; ++k) dst[m][k] = *(const PG8_LAS bf16x8*)(lds + PG8_SA(b, h) + aoff + m * 2048 + k * 1024); } while (0)
; #define PG8_LDB(dst, b, h) do { _Pragma("unroll") for (int n = 0; n < 2; ++n) _Pragma("unroll") for (int k = 0; k < 2; ++k) dst[n][k] = *(const PG8_LAS bf16x8*)(lds + PG8_SB(b, h) + boff + n * 2048 + k * 1024); } while (0)
; #define PG8_MMA(ai, bj, At, Bt) do { __builtin_amdgcn_s_setprio(1); _Pragma("unroll") for (int m = 0; m < 4; ++m) _Pragma("unroll") for (int n = 0; n < 2; ++n) _Pragma("unroll") for (int k = 0; k < 2; ++k) \
;         acc[ai][bj][m][n] = __builtin_amdgcn_mfma_f32_16x16x32_bf16(Bt[n][k], At[m][k], acc[ai][bj][m][n], 0, 0, 0); __builtin_amdgcn_s_setprio(0); } while (0)
; #define PG8_WAIT_V(n) asm volatile("s_waitcnt vmcnt(" #n ")" ::: "memory")
; #define PG8_WAIT_L(n) asm volatile("s_waitcnt lgkmcnt(" #n ")" ::: "memory")
; #define PG8_BAR __builtin_amdgcn_s_barrier()
; #define PG8_SCHED __builtin_amdgcn_sched_barrier(0)
; template <class Epi, class Sched, bool ALIGN_EPI = false, bool SP2 = false>
; __device__ __forceinline__ void gemm_phase(PG8_LAS unsigned char* lds, const Gemm g, const Sched& S, const Epi& E, const int wv  ) {
;     ...
;             PG8_WAIT_V(8); PG8_WAIT_L(0); PG8_BAR; PG8_MMA(1, 0, At, B0); PG8_MMA(1, 1, At, B1); PG8_BAR; PG8_SCHED;
;             PG8_LDB(B0, 1, 0); PG8_LDB(B1, 1, 1); PG8_SCHED; PG8_LDA(At, 1, 0); PG8_STAGE(PG8_SA(0, 1), a2 + hstepA, voffA);
;             PG8_WAIT_V(8); PG8_WAIT_L(0); PG8_BAR; PG8_MMA(0, 0, At, B0); PG8_MMA(0, 1, At, B1); PG8_BAR; PG8_SCHED;
	s_setprio 1
	s_waitcnt lgkmcnt(0)
	v_mfma_f32_16x16x32_bf16 v[28:31], v[142:145], v[180:183], v[28:31]
	v_mfma_f32_16x16x32_bf16 v[24:27], v[156:159], v[180:183], v[24:27]
	v_mfma_f32_16x16x32_bf16 v[20:23], v[142:145], v[188:191], v[20:23]
	v_mfma_f32_16x16x32_bf16 v[16:19], v[156:159], v[188:191], v[16:19]
	v_mfma_f32_16x16x32_bf16 v[12:15], v[142:145], v[196:199], v[12:15]
	v_mfma_f32_16x16x32_bf16 v[8:11], v[156:159], v[196:199], v[8:11]
	v_mfma_f32_16x16x32_bf16 v[4:7], v[142:145], v[204:207], v[4:7]
	v_mfma_f32_16x16x32_bf16 v[0:3], v[156:159], v[204:207], v[0:3]
	v_mfma_f32_16x16x32_bf16 v[28:31], v[152:155], v[184:187], v[28:31]
	v_mfma_f32_16x16x32_bf16 v[24:27], v[160:163], v[184:187], v[24:27]
	v_mfma_f32_16x16x32_bf16 v[20:23], v[152:155], v[192:195], v[20:23]
	v_mfma_f32_16x16x32_bf16 v[16:19], v[160:163], v[192:195], v[16:19]
	v_mfma_f32_16x16x32_bf16 v[12:15], v[152:155], v[200:203], v[12:15]
	v_mfma_f32_16x16x32_bf16 v[8:11], v[160:163], v[200:203], v[8:11]
	v_mfma_f32_16x16x32_bf16 v[4:7], v[152:155], v[208:211], v[4:7]
	v_mfma_f32_16x16x32_bf16 v[0:3], v[160:163], v[208:211], v[0:3]
	s_setprio 0
	s_setprio 1
	v_mfma_f32_16x16x32_bf16 v[92:95], v[164:167], v[180:183], v[92:95]
	v_mfma_f32_16x16x32_bf16 v[88:91], v[172:175], v[180:183], v[88:91]
	v_mfma_f32_16x16x32_bf16 v[84:87], v[164:167], v[188:191], v[84:87]
	v_mfma_f32_16x16x32_bf16 v[80:83], v[172:175], v[188:191], v[80:83]
	v_mfma_f32_16x16x32_bf16 v[60:63], v[164:167], v[196:199], v[60:63]
	v_mfma_f32_16x16x32_bf16 v[48:51], v[172:175], v[196:199], v[48:51]
	v_mfma_f32_16x16x32_bf16 v[36:39], v[164:167], v[204:207], v[36:39]
	v_mfma_f32_16x16x32_bf16 v[32:35], v[172:175], v[204:207], v[32:35]
	v_mfma_f32_16x16x32_bf16 v[92:95], v[168:171], v[184:187], v[92:95]
	v_mfma_f32_16x16x32_bf16 v[88:91], v[176:179], v[184:187], v[88:91]
	v_mfma_f32_16x16x32_bf16 v[84:87], v[168:171], v[192:195], v[84:87]
	v_mfma_f32_16x16x32_bf16 v[80:83], v[176:179], v[192:195], v[80:83]
	v_mfma_f32_16x16x32_bf16 v[60:63], v[168:171], v[200:203], v[60:63]
	v_mfma_f32_16x16x32_bf16 v[48:51], v[176:179], v[200:203], v[48:51]
	s_setprio 2
	s_barrier
	v_mfma_f32_16x16x32_bf16 v[36:39], v[168:171], v[208:211], v[36:39]
	v_mfma_f32_16x16x32_bf16 v[32:35], v[176:179], v[208:211], v[32:35]
	s_setprio 0
	s_add_i32 s97, 0, 0x18000
	v_add_u32_e32 v151, s97, v146
	s_add_i32 vcc_lo, 0, 0x1c000
	ds_read_b128 v[142:145], v151
	ds_read_b128 v[152:155], v151 offset:1024
	ds_read_b128 v[156:159], v151 offset:2048
	ds_read_b128 v[160:163], v151 offset:3072
	v_add_u32_e32 v151, vcc_lo, v146
	ds_read_b128 v[164:167], v151
	ds_read_b128 v[168:171], v151 offset:1024
	ds_read_b128 v[172:175], v151 offset:2048
	ds_read_b128 v[176:179], v151 offset:3072
	s_add_u32 s62, s62, 0x100000
	s_addc_u32 s63, s63, 0
	s_mov_b32 m0, s77
	v_lshl_add_u64 v[220:221], s[62:63], 0, v[134:135]
	ds_read_b128 v[180:183], v150 offset:32768
	ds_read_b128 v[184:187], v150 offset:33792
	ds_read_b128 v[188:191], v150 offset:34816
	ds_read_b128 v[192:195], v150 offset:35840
	ds_read_b128 v[196:199], v150 offset:36864
	ds_read_b128 v[200:203], v150 offset:37888
	ds_read_b128 v[204:207], v150 offset:38912
	ds_read_b128 v[208:211], v150 offset:39936
	global_load_lds_dwordx4 v[220:221], off
	v_lshl_add_u64 v[220:221], s[62:63], 0, v[130:131]
	s_mov_b32 m0, s78
	s_nop 0
	global_load_lds_dwordx4 v[220:221], off
	s_waitcnt vmcnt(8)
	s_waitcnt lgkmcnt(0)
	s_barrier
	s_setprio 1
	s_waitcnt lgkmcnt(0)
	v_mfma_f32_16x16x32_bf16 v[76:79], v[142:145], v[180:183], v[76:79]
	v_mfma_f32_16x16x32_bf16 v[72:75], v[156:159], v[180:183], v[72:75]
	v_mfma_f32_16x16x32_bf16 v[68:71], v[142:145], v[188:191], v[68:71]
	v_mfma_f32_16x16x32_bf16 v[64:67], v[156:159], v[188:191], v[64:67]
	v_mfma_f32_16x16x32_bf16 v[56:59], v[142:145], v[196:199], v[56:59]
	v_mfma_f32_16x16x32_bf16 v[52:55], v[156:159], v[196:199], v[52:55]
	v_mfma_f32_16x16x32_bf16 v[44:47], v[142:145], v[204:207], v[44:47]
	v_mfma_f32_16x16x32_bf16 v[40:43], v[156:159], v[204:207], v[40:43]
	v_mfma_f32_16x16x32_bf16 v[76:79], v[152:155], v[184:187], v[76:79]
	v_mfma_f32_16x16x32_bf16 v[72:75], v[160:163], v[184:187], v[72:75]
	v_mfma_f32_16x16x32_bf16 v[68:71], v[152:155], v[192:195], v[68:71]
	v_mfma_f32_16x16x32_bf16 v[64:67], v[160:163], v[192:195], v[64:67]
	v_mfma_f32_16x16x32_bf16 v[56:59], v[152:155], v[200:203], v[56:59]
	v_mfma_f32_16x16x32_bf16 v[52:55], v[160:163], v[200:203], v[52:55]
	v_mfma_f32_16x16x32_bf16 v[44:47], v[152:155], v[208:211], v[44:47]
	v_mfma_f32_16x16x32_bf16 v[40:43], v[160:163], v[208:211], v[40:43]
	s_setprio 0
	s_setprio 1
	v_mfma_f32_16x16x32_bf16 v[124:127], v[164:167], v[180:183], v[124:127]
	v_mfma_f32_16x16x32_bf16 v[120:123], v[172:175], v[180:183], v[120:123]
	v_mfma_f32_16x16x32_bf16 v[116:119], v[164:167], v[188:191], v[116:119]
	v_mfma_f32_16x16x32_bf16 v[112:115], v[172:175], v[188:191], v[112:115]
	v_mfma_f32_16x16x32_bf16 v[108:111], v[164:167], v[196:199], v[108:111]
	v_mfma_f32_16x16x32_bf16 v[104:107], v[172:175], v[196:199], v[104:107]
	v_mfma_f32_16x16x32_bf16 v[100:103], v[164:167], v[204:207], v[100:103]
	v_mfma_f32_16x16x32_bf16 v[96:99], v[172:175], v[204:207], v[96:99]
	v_mfma_f32_16x16x32_bf16 v[124:127], v[168:171], v[184:187], v[124:127]
	v_mfma_f32_16x16x32_bf16 v[120:123], v[176:179], v[184:187], v[120:123]
	v_mfma_f32_16x16x32_bf16 v[116:119], v[168:171], v[192:195], v[116:119]
	v_mfma_f32_16x16x32_bf16 v[112:115], v[176:179], v[192:195], v[112:115]
	v_mfma_f32_16x16x32_bf16 v[108:111], v[168:171], v[200:203], v[108:111]
	v_mfma_f32_16x16x32_bf16 v[104:107], v[176:179], v[200:203], v[104:107]
	s_setprio 2
	s_barrier
; #define PG8_STAGE(bufoff, gbase, voff) do { _Pragma("unroll") for (int _i = 0; _i < 2; ++_i) \
;         __builtin_amdgcn_global_load_lds((const unsigned*)((const char*)(gbase) + (voff)[_i]), (PG8_LAS unsigned*)(lds + (bufoff) + ldsw + _i * 8192), 16, 0, 0); } while (0)
; #define PG8_LDA(dst, b, h) do { _Pragma("unroll") for (int m = 0; m < 4; ++m) _Pragma("unroll") for (int k = 0; k < 2; ++k) dst[m][k] = *(const PG8_LAS bf16x8*)(lds + PG8_SA(b, h) + aoff + m * 2048 + k * 1024); } while (0)
; #define PG8_MMA(ai, bj, At, Bt) do { __builtin_amdgcn_s_setprio(1); _Pragma("unroll") for (int m = 0; m < 4; ++m) _Pragma("unroll") for (int n = 0; n < 2; ++n) _Pragma("unroll") for (int k = 0; k < 2; ++k) \
;         acc[ai][bj][m][n] = __builtin_amdgcn_mfma_f32_16x16x32_bf16(Bt[n][k], At[m][k], acc[ai][bj][m][n], 0, 0, 0); __builtin_amdgcn_s_setprio(0); } while (0)
; #define PG8_WAIT_V(n) asm volatile("s_waitcnt vmcnt(" #n ")" ::: "memory")
; #define PG8_WAIT_L(n) asm volatile("s_waitcnt lgkmcnt(" #n ")" ::: "memory")
; #define PG8_BAR __builtin_amdgcn_s_barrier()
; #define PG8_SCHED __builtin_amdgcn_sched_barrier(0)
; template <class Epi, class Sched, bool ALIGN_EPI = false, bool SP2 = false>
; __device__ __forceinline__ void gemm_phase(PG8_LAS unsigned char* lds, const Gemm g, const Sched& S, const Epi& E, const int wv  ) {
;     ...
;             PG8_WAIT_V(8); PG8_WAIT_L(0); PG8_BAR; PG8_MMA(0, 0, At, B0); PG8_MMA(0, 1, At, B1); PG8_BAR; PG8_SCHED;
;             PG8_LDA(At, 1, 1); PG8_STAGE(PG8_SB(1, 0), b3, voffB); PG8_STAGE(PG8_SB(1, 1), b3 + hstepB, voffB); PG8_STAGE(PG8_SA(1, 0), a3, voffA);
;             PG8_WAIT_V(8); PG8_WAIT_L(0); PG8_BAR; PG8_MMA(1, 0, At, B0); PG8_MMA(1, 1, At, B1); PG8_BAR; PG8_SCHED;
;     ...
;         if constexpr (ALIGN_EPI) { if (wr == 0) PG8_BAR; }
	v_mfma_f32_16x16x32_bf16 v[100:103], v[168:171], v[208:211], v[100:103]
	v_mfma_f32_16x16x32_bf16 v[96:99], v[176:179], v[208:211], v[96:99]
	s_setprio 0
	s_add_i32 s62, s97, s73
	v_lshl_add_u64 v[212:213], v[212:213], 0, s[8:9]
	s_mov_b32 m0, s62
	ds_read_b128 v[180:183], v150 offset:49152
	ds_read_b128 v[184:187], v150 offset:50176
	ds_read_b128 v[188:191], v150 offset:51200
	ds_read_b128 v[192:195], v150 offset:52224
	ds_read_b128 v[196:199], v150 offset:53248
	ds_read_b128 v[200:203], v150 offset:54272
	ds_read_b128 v[204:207], v150 offset:55296
	ds_read_b128 v[208:211], v150 offset:56320
	global_load_lds_dwordx4 v[212:213], off
	s_add_i32 m0, s62, 0x2000
	s_add_u32 s60, s60, 0x100080
	v_lshl_add_u64 v[212:213], v[214:215], 0, s[8:9]
	s_addc_u32 s61, s61, 0
	s_add_i32 s62, vcc_lo, s73
	global_load_lds_dwordx4 v[212:213], off
	v_lshl_add_u64 v[212:213], s[60:61], 0, v[132:133]
	s_mov_b32 m0, s62
	s_nop 0
	global_load_lds_dwordx4 v[212:213], off
	v_lshl_add_u64 v[212:213], s[60:61], 0, v[128:129]
	s_add_i32 m0, s62, 0x2000
	s_nop 0
	global_load_lds_dwordx4 v[212:213], off
	v_lshl_add_u64 v[212:213], v[216:217], 0, s[8:9]
	s_mov_b32 m0, s80
	s_nop 0
	global_load_lds_dwordx4 v[212:213], off
	v_lshl_add_u64 v[212:213], v[218:219], 0, s[8:9]
	s_mov_b32 m0, s81
	s_nop 0
	global_load_lds_dwordx4 v[212:213], off
	s_waitcnt vmcnt(8)
	s_waitcnt lgkmcnt(0)
	s_barrier
	s_setprio 1
	s_waitcnt lgkmcnt(0)
	v_mfma_f32_16x16x32_bf16 v[28:31], v[142:145], v[180:183], v[28:31]
	v_mfma_f32_16x16x32_bf16 v[24:27], v[156:159], v[180:183], v[24:27]
	v_mfma_f32_16x16x32_bf16 v[20:23], v[142:145], v[188:191], v[20:23]
	v_mfma_f32_16x16x32_bf16 v[16:19], v[156:159], v[188:191], v[16:19]
	v_mfma_f32_16x16x32_bf16 v[12:15], v[142:145], v[196:199], v[12:15]
	v_mfma_f32_16x16x32_bf16 v[8:11], v[156:159], v[196:199], v[8:11]
	v_mfma_f32_16x16x32_bf16 v[4:7], v[142:145], v[204:207], v[4:7]
	v_mfma_f32_16x16x32_bf16 v[0:3], v[156:159], v[204:207], v[0:3]
	v_mfma_f32_16x16x32_bf16 v[28:31], v[152:155], v[184:187], v[28:31]
	v_mfma_f32_16x16x32_bf16 v[24:27], v[160:163], v[184:187], v[24:27]
	v_mfma_f32_16x16x32_bf16 v[20:23], v[152:155], v[192:195], v[20:23]
	v_mfma_f32_16x16x32_bf16 v[16:19], v[160:163], v[192:195], v[16:19]
	v_mfma_f32_16x16x32_bf16 v[12:15], v[152:155], v[200:203], v[12:15]
	v_mfma_f32_16x16x32_bf16 v[8:11], v[160:163], v[200:203], v[8:11]
	v_mfma_f32_16x16x32_bf16 v[4:7], v[152:155], v[208:211], v[4:7]
	v_mfma_f32_16x16x32_bf16 v[0:3], v[160:163], v[208:211], v[0:3]
	s_setprio 0
	s_setprio 1
	v_mfma_f32_16x16x32_bf16 v[92:95], v[164:167], v[180:183], v[92:95]
	v_mfma_f32_16x16x32_bf16 v[88:91], v[172:175], v[180:183], v[88:91]
	v_mfma_f32_16x16x32_bf16 v[84:87], v[164:167], v[188:191], v[84:87]
	v_mfma_f32_16x16x32_bf16 v[80:83], v[172:175], v[188:191], v[80:83]
	v_mfma_f32_16x16x32_bf16 v[60:63], v[164:167], v[196:199], v[60:63]
	v_mfma_f32_16x16x32_bf16 v[48:51], v[172:175], v[196:199], v[48:51]
	v_mfma_f32_16x16x32_bf16 v[36:39], v[164:167], v[204:207], v[36:39]
	v_mfma_f32_16x16x32_bf16 v[32:35], v[172:175], v[204:207], v[32:35]
	v_mfma_f32_16x16x32_bf16 v[92:95], v[168:171], v[184:187], v[92:95]
	v_mfma_f32_16x16x32_bf16 v[88:91], v[176:179], v[184:187], v[88:91]
	v_mfma_f32_16x16x32_bf16 v[84:87], v[168:171], v[192:195], v[84:87]
	v_mfma_f32_16x16x32_bf16 v[80:83], v[176:179], v[192:195], v[80:83]
	v_mfma_f32_16x16x32_bf16 v[60:63], v[168:171], v[200:203], v[60:63]
	v_mfma_f32_16x16x32_bf16 v[48:51], v[176:179], v[200:203], v[48:51]
	s_setprio 2
	s_barrier
	v_mfma_f32_16x16x32_bf16 v[36:39], v[168:171], v[208:211], v[36:39]
	v_mfma_f32_16x16x32_bf16 v[32:35], v[176:179], v[208:211], v[32:35]
	s_setprio 0
	s_add_i32 s96, s96, 2
	s_add_u32 s58, s58, 0x100
	s_addc_u32 s59, s59, 0
	s_add_u32 s94, s94, 0x100
	s_addc_u32 s95, s95, 0
	s_cmp_gt_u32 s96, 61
	s_cbranch_scc0 .LBB0_871
	s_and_b64 vcc, exec, s[10:11]
	s_cbranch_vccz .LBB0_874
	s_barrier

; #define PG8_STAGE(bufoff, gbase, voff) do { _Pragma("unroll") for (int _i = 0; _i < 2; ++_i) \
;         __builtin_amdgcn_global_load_lds((const unsigned*)((const char*)(gbase) + (voff)[_i]), (PG8_LAS unsigned*)(lds + (bufoff) + ldsw + _i * 8192), 16, 0, 0); } while (0)
; #define PG8_LDA(dst, b, h) do { _Pragma("unroll") for (int m = 0; m < 4; ++m) _Pragma("unroll") for (int k = 0; k < 2; ++k) dst[m][k] = *(const PG8_LAS bf16x8*)(lds + PG8_SA(b, h) + aoff + m * 2048 + k * 1024); } while (0)
; #define PG8_LDB(dst, b, h) do { _Pragma("unroll") for (int n = 0; n < 2; ++n) _Pragma("unroll") for (int k = 0; k < 2; ++k) dst[n][k] = *(const PG8_LAS bf16x8*)(lds + PG8_SB(b, h) + boff + n * 2048 + k * 1024); } while (0)
; #define PG8_MMA(ai, bj, At, Bt) do { __builtin_amdgcn_s_setprio(1); _Pragma("unroll") for (int m = 0; m < 4; ++m) _Pragma("unroll") for (int n = 0; n < 2; ++n) _Pragma("unroll") for (int k = 0; k < 2; ++k) \
;         acc[ai][bj][m][n] = __builtin_amdgcn_mfma_f32_16x16x32_bf16(Bt[n][k], At[m][k], acc[ai][bj][m][n], 0, 0, 0); __builtin_amdgcn_s_setprio(0); } while (0)
; #define PG8_WAIT_V(n) asm volatile("s_waitcnt vmcnt(" #n ")" ::: "memory")
; #define PG8_BAR __builtin_amdgcn_s_barrier()
; template <class Epi, class Sched, bool ALIGN_EPI = false, bool SP2 = false>
; __device__ __forceinline__ void gemm_phase(PG8_LAS unsigned char* lds, const Gemm g, const Sched& S, const Epi& E, const int wv  ) {
;     ...
;         for (int t = 0; t < nt; t += 2) {
;             const bool last = (t == nt - 2);
;             const char* a1 = cA + (size_t)(t + 1) * kstep;
;             const char* a2 = last ? nA : cA + (size_t)(t + 2) * kstep; const char* b2 = last ? nB : cB + (size_t)(t + 2) * kstep;
;             const char* a3 = a2 + kstep; const char* b3 = b2 + kstep;
;             if (last && has_next) S.a_ready(nxt);
;             if constexpr (SP2) {
;             PG8_LDB(B0, 0, 0); PG8_LDB(B1, 0, 1); PG8_SCHED; PG8_LDA(At, 0, 0); PG8_STAGE(PG8_SA(1, 1), a1 + hstepA, voffA);
;             PG8_WAIT_V(8); PG8_WAIT_L(0); PG8_BAR; PG8_MMA(0, 0, At, B0); PG8_MMA(0, 1, At, B1); PG8_BAR; PG8_SCHED;
;             PG8_LDA(At, 0, 1); PG8_STAGE(PG8_SB(0, 0), b2, voffB); PG8_STAGE(PG8_SB(0, 1), b2 + hstepB, voffB); PG8_STAGE(PG8_SA(0, 0), a2, voffA);
;             PG8_WAIT_V(8); PG8_WAIT_L(0); PG8_BAR; PG8_MMA(1, 0, At, B0); PG8_MMA(1, 1, At, B1); PG8_BAR; PG8_SCHED;
.LBB0_892:
	ds_read_b128 v[142:145], v148
	ds_read_b128 v[152:155], v148 offset:1024
	ds_read_b128 v[156:159], v148 offset:2048
	ds_read_b128 v[160:163], v148 offset:3072
	ds_read_b128 v[164:167], v149
	ds_read_b128 v[168:171], v149 offset:1024
	ds_read_b128 v[172:175], v149 offset:2048
	ds_read_b128 v[176:179], v149 offset:3072
	s_add_u32 s60, s58, 0xfff00080
	s_addc_u32 s61, s59, -1
	s_cmp_eq_u32 s92, 60
	s_cselect_b32 s63, s49, s61
	s_cselect_b32 s62, s86, s60
	s_cselect_b32 s61, s47, s91
	s_cselect_b32 s60, s87, s90
	v_lshl_add_u64 v[212:213], s[58:59], 0, v[138:139]
	s_add_i32 m0, s71, 0xc000
	ds_read_b128 v[180:183], v150
	ds_read_b128 v[184:187], v150 offset:1024
	ds_read_b128 v[188:191], v150 offset:2048
	ds_read_b128 v[192:195], v150 offset:3072
	ds_read_b128 v[196:199], v150 offset:4096
	ds_read_b128 v[200:203], v150 offset:5120
	ds_read_b128 v[204:207], v150 offset:6144
	ds_read_b128 v[208:211], v150 offset:7168
	global_load_lds_dwordx4 v[212:213], off
	v_lshl_add_u64 v[212:213], s[58:59], 0, v[140:141]
	s_add_i32 m0, s71, 0xe000
	s_nop 0
	global_load_lds_dwordx4 v[212:213], off
	s_waitcnt vmcnt(8)
	s_waitcnt lgkmcnt(0)
	s_barrier
	s_setprio 1
	s_waitcnt lgkmcnt(0)
	v_mfma_f32_16x16x32_bf16 v[76:79], v[142:145], v[180:183], v[76:79]
	v_mfma_f32_16x16x32_bf16 v[72:75], v[156:159], v[180:183], v[72:75]
	v_mfma_f32_16x16x32_bf16 v[68:71], v[142:145], v[188:191], v[68:71]
	v_mfma_f32_16x16x32_bf16 v[64:67], v[156:159], v[188:191], v[64:67]
	v_mfma_f32_16x16x32_bf16 v[56:59], v[142:145], v[196:199], v[56:59]
	v_mfma_f32_16x16x32_bf16 v[52:55], v[156:159], v[196:199], v[52:55]
	v_mfma_f32_16x16x32_bf16 v[44:47], v[142:145], v[204:207], v[44:47]
	v_mfma_f32_16x16x32_bf16 v[40:43], v[156:159], v[204:207], v[40:43]
	v_mfma_f32_16x16x32_bf16 v[76:79], v[152:155], v[184:187], v[76:79]
	v_mfma_f32_16x16x32_bf16 v[72:75], v[160:163], v[184:187], v[72:75]
	v_mfma_f32_16x16x32_bf16 v[68:71], v[152:155], v[192:195], v[68:71]
	v_mfma_f32_16x16x32_bf16 v[64:67], v[160:163], v[192:195], v[64:67]
	v_mfma_f32_16x16x32_bf16 v[56:59], v[152:155], v[200:203], v[56:59]
	v_mfma_f32_16x16x32_bf16 v[52:55], v[160:163], v[200:203], v[52:55]
	v_mfma_f32_16x16x32_bf16 v[44:47], v[152:155], v[208:211], v[44:47]
	v_mfma_f32_16x16x32_bf16 v[40:43], v[160:163], v[208:211], v[40:43]
	s_setprio 0
	s_setprio 1
	v_mfma_f32_16x16x32_bf16 v[124:127], v[164:167], v[180:183], v[124:127]
	v_mfma_f32_16x16x32_bf16 v[120:123], v[172:175], v[180:183], v[120:123]
	v_mfma_f32_16x16x32_bf16 v[116:119], v[164:167], v[188:191], v[116:119]
	v_mfma_f32_16x16x32_bf16 v[112:115], v[172:175], v[188:191], v[112:115]
	v_mfma_f32_16x16x32_bf16 v[108:111], v[164:167], v[196:199], v[108:111]
	v_mfma_f32_16x16x32_bf16 v[104:107], v[172:175], v[196:199], v[104:107]
	v_mfma_f32_16x16x32_bf16 v[100:103], v[164:167], v[204:207], v[100:103]
	v_mfma_f32_16x16x32_bf16 v[96:99], v[172:175], v[204:207], v[96:99]
	v_mfma_f32_16x16x32_bf16 v[124:127], v[168:171], v[184:187], v[124:127]
	v_mfma_f32_16x16x32_bf16 v[120:123], v[176:179], v[184:187], v[120:123]
	v_mfma_f32_16x16x32_bf16 v[116:119], v[168:171], v[192:195], v[116:119]
	v_mfma_f32_16x16x32_bf16 v[112:115], v[176:179], v[192:195], v[112:115]
	v_mfma_f32_16x16x32_bf16 v[108:111], v[168:171], v[200:203], v[108:111]
	v_mfma_f32_16x16x32_bf16 v[104:107], v[176:179], v[200:203], v[104:107]
	s_setprio 2
	s_barrier
	v_mfma_f32_16x16x32_bf16 v[100:103], v[168:171], v[208:211], v[100:103]
	v_mfma_f32_16x16x32_bf16 v[96:99], v[176:179], v[208:211], v[96:99]
	s_setprio 0
	s_add_i32 s93, s84, s69
	v_lshl_add_u64 v[212:213], s[60:61], 0, v[132:133]
	s_mov_b32 m0, s93
	ds_read_b128 v[180:183], v150 offset:16384
	ds_read_b128 v[184:187], v150 offset:17408
	ds_read_b128 v[188:191], v150 offset:18432
	ds_read_b128 v[192:195], v150 offset:19456
	ds_read_b128 v[196:199], v150 offset:20480
	ds_read_b128 v[200:203], v150 offset:21504
	ds_read_b128 v[204:207], v150 offset:22528
	ds_read_b128 v[208:211], v150 offset:23552
	global_load_lds_dwordx4 v[212:213], off
	s_add_i32 m0, s93, 0x2000
	s_add_u32 s94, s60, 0x100000
	v_lshl_add_u64 v[214:215], s[60:61], 0, v[128:129]
	s_addc_u32 s95, s61, 0
	s_add_i32 s93, s85, s69
	global_load_lds_dwordx4 v[214:215], off
	v_lshl_add_u64 v[216:217], s[94:95], 0, v[132:133]
	s_mov_b32 m0, s93
	v_lshl_add_u64 v[218:219], s[62:63], 0, v[130:131]
	global_load_lds_dwordx4 v[216:217], off
	v_lshl_add_u64 v[216:217], s[94:95], 0, v[128:129]
	s_add_i32 m0, s93, 0x2000
	s_nop 0
	global_load_lds_dwordx4 v[216:217], off
	v_lshl_add_u64 v[216:217], s[62:63], 0, v[134:135]
	s_mov_b32 m0, s71
	s_nop 0
	global_load_lds_dwordx4 v[216:217], off
	s_mov_b32 m0, s72
	s_nop 0
	global_load_lds_dwordx4 v[218:219], off
	s_waitcnt vmcnt(8)
	s_waitcnt lgkmcnt(0)
	s_barrier
; #define PG8_STAGE(bufoff, gbase, voff) do { _Pragma("unroll") for (int _i = 0; _i < 2; ++_i) \
;         __builtin_amdgcn_global_load_lds((const unsigned*)((const char*)(gbase) + (voff)[_i]), (PG8_LAS unsigned*)(lds + (bufoff) + ldsw + _i * 8192), 16, 0, 0); } while (0)
; #define PG8_LDA(dst, b, h) do { _Pragma("unroll") for (int m = 0; m < 4; ++m) _Pragma("unroll") for (int k = 0; k < 2; ++k) dst[m][k] = *(const PG8_LAS bf16x8*)(lds + PG8_SA(b, h) + aoff + m * 2048 + k * 1024); } while (0)
; #define PG8_LDB(dst, b, h) do { _Pragma("unroll") for (int n = 0; n < 2; ++n) _Pragma("unroll") for (int k = 0; k < 2; ++k) dst[n][k] = *(const PG8_LAS bf16x8*)(lds + PG8_SB(b, h) + boff + n * 2048 + k * 1024); } while (0)
; #define PG8_MMA(ai, bj, At, Bt) do { __builtin_amdgcn_s_setprio(1); _Pragma("unroll") for (int m = 0; m < 4; ++m) _Pragma("unroll") for (int n = 0; n < 2; ++n) _Pragma("unroll") for (int k = 0; k < 2; ++k) \
;         acc[ai][bj][m][n] = __builtin_amdgcn_mfma_f32_16x16x32_bf16(Bt[n][k], At[m][k], acc[ai][bj][m][n], 0, 0, 0); __builtin_amdgcn_s_setprio(0); } while (0)
; #define PG8_WAIT_V(n) asm volatile("s_waitcnt vmcnt(" #n ")" ::: "memory")
; #define PG8_WAIT_L(n) asm volatile("s_waitcnt lgkmcnt(" #n ")" ::: "memory")
; #define PG8_BAR __builtin_amdgcn_s_barrier()
; #define PG8_SCHED __builtin_amdgcn_sched_barrier(0)
; template <class Epi, class Sched, bool ALIGN_EPI = false, bool SP2 = false>
; __device__ __forceinline__ void gemm_phase(PG8_LAS unsigned char* lds, const Gemm g, const Sched& S, const Epi& E, const int wv  ) {
;     ...
;             PG8_WAIT_V(8); PG8_WAIT_L(0); PG8_BAR; PG8_MMA(1, 0, At, B0); PG8_MMA(1, 1, At, B1); PG8_BAR; PG8_SCHED;
;             PG8_LDB(B0, 1, 0); PG8_LDB(B1, 1, 1); PG8_SCHED; PG8_LDA(At, 1, 0); PG8_STAGE(PG8_SA(0, 1), a2 + hstepA, voffA);
;             PG8_WAIT_V(8); PG8_WAIT_L(0); PG8_BAR; PG8_MMA(0, 0, At, B0); PG8_MMA(0, 1, At, B1); PG8_BAR; PG8_SCHED;
	s_setprio 1
	s_waitcnt lgkmcnt(0)
	v_mfma_f32_16x16x32_bf16 v[28:31], v[142:145], v[180:183], v[28:31]
	v_mfma_f32_16x16x32_bf16 v[24:27], v[156:159], v[180:183], v[24:27]
	v_mfma_f32_16x16x32_bf16 v[20:23], v[142:145], v[188:191], v[20:23]
	v_mfma_f32_16x16x32_bf16 v[16:19], v[156:159], v[188:191], v[16:19]
	v_mfma_f32_16x16x32_bf16 v[12:15], v[142:145], v[196:199], v[12:15]
	v_mfma_f32_16x16x32_bf16 v[8:11], v[156:159], v[196:199], v[8:11]
	v_mfma_f32_16x16x32_bf16 v[4:7], v[142:145], v[204:207], v[4:7]
	v_mfma_f32_16x16x32_bf16 v[0:3], v[156:159], v[204:207], v[0:3]
	v_mfma_f32_16x16x32_bf16 v[28:31], v[152:155], v[184:187], v[28:31]
	v_mfma_f32_16x16x32_bf16 v[24:27], v[160:163], v[184:187], v[24:27]
	v_mfma_f32_16x16x32_bf16 v[20:23], v[152:155], v[192:195], v[20:23]
	v_mfma_f32_16x16x32_bf16 v[16:19], v[160:163], v[192:195], v[16:19]
	v_mfma_f32_16x16x32_bf16 v[12:15], v[152:155], v[200:203], v[12:15]
	v_mfma_f32_16x16x32_bf16 v[8:11], v[160:163], v[200:203], v[8:11]
	v_mfma_f32_16x16x32_bf16 v[4:7], v[152:155], v[208:211], v[4:7]
	v_mfma_f32_16x16x32_bf16 v[0:3], v[160:163], v[208:211], v[0:3]
	s_setprio 0
	s_setprio 1
	v_mfma_f32_16x16x32_bf16 v[92:95], v[164:167], v[180:183], v[92:95]
	v_mfma_f32_16x16x32_bf16 v[88:91], v[172:175], v[180:183], v[88:91]
	v_mfma_f32_16x16x32_bf16 v[84:87], v[164:167], v[188:191], v[84:87]
	v_mfma_f32_16x16x32_bf16 v[80:83], v[172:175], v[188:191], v[80:83]
	v_mfma_f32_16x16x32_bf16 v[60:63], v[164:167], v[196:199], v[60:63]
	v_mfma_f32_16x16x32_bf16 v[48:51], v[172:175], v[196:199], v[48:51]
	v_mfma_f32_16x16x32_bf16 v[36:39], v[164:167], v[204:207], v[36:39]
	v_mfma_f32_16x16x32_bf16 v[32:35], v[172:175], v[204:207], v[32:35]
	v_mfma_f32_16x16x32_bf16 v[92:95], v[168:171], v[184:187], v[92:95]
	v_mfma_f32_16x16x32_bf16 v[88:91], v[176:179], v[184:187], v[88:91]
	v_mfma_f32_16x16x32_bf16 v[84:87], v[168:171], v[192:195], v[84:87]
	v_mfma_f32_16x16x32_bf16 v[80:83], v[176:179], v[192:195], v[80:83]
	v_mfma_f32_16x16x32_bf16 v[60:63], v[168:171], v[200:203], v[60:63]
	v_mfma_f32_16x16x32_bf16 v[48:51], v[176:179], v[200:203], v[48:51]
	s_setprio 2
	s_barrier
	v_mfma_f32_16x16x32_bf16 v[36:39], v[168:171], v[208:211], v[36:39]
	v_mfma_f32_16x16x32_bf16 v[32:35], v[176:179], v[208:211], v[32:35]
	s_setprio 0
	s_add_i32 s93, 0, 0x18000
	v_add_u32_e32 v151, s93, v146
	s_add_i32 s94, 0, 0x1c000
	ds_read_b128 v[142:145], v151
	ds_read_b128 v[152:155], v151 offset:1024
	ds_read_b128 v[156:159], v151 offset:2048
	ds_read_b128 v[160:163], v151 offset:3072
	v_add_u32_e32 v151, s94, v146
	ds_read_b128 v[164:167], v151
	ds_read_b128 v[168:171], v151 offset:1024
	ds_read_b128 v[172:175], v151 offset:2048
	ds_read_b128 v[176:179], v151 offset:3072
	s_add_u32 s62, s62, 0x100000
	s_addc_u32 s63, s63, 0
	s_mov_b32 m0, s73
	v_lshl_add_u64 v[220:221], s[62:63], 0, v[134:135]
	ds_read_b128 v[180:183], v150 offset:32768
	ds_read_b128 v[184:187], v150 offset:33792
	ds_read_b128 v[188:191], v150 offset:34816
	ds_read_b128 v[192:195], v150 offset:35840
	ds_read_b128 v[196:199], v150 offset:36864
	ds_read_b128 v[200:203], v150 offset:37888
	ds_read_b128 v[204:207], v150 offset:38912
	ds_read_b128 v[208:211], v150 offset:39936
	global_load_lds_dwordx4 v[220:221], off
	v_lshl_add_u64 v[220:221], s[62:63], 0, v[130:131]
	s_mov_b32 m0, s74
	s_nop 0
	global_load_lds_dwordx4 v[220:221], off
	s_waitcnt vmcnt(8)
	s_waitcnt lgkmcnt(0)
	s_barrier
	s_setprio 1
	s_waitcnt lgkmcnt(0)
	v_mfma_f32_16x16x32_bf16 v[76:79], v[142:145], v[180:183], v[76:79]
	v_mfma_f32_16x16x32_bf16 v[72:75], v[156:159], v[180:183], v[72:75]
	v_mfma_f32_16x16x32_bf16 v[68:71], v[142:145], v[188:191], v[68:71]
	v_mfma_f32_16x16x32_bf16 v[64:67], v[156:159], v[188:191], v[64:67]
	v_mfma_f32_16x16x32_bf16 v[56:59], v[142:145], v[196:199], v[56:59]
	v_mfma_f32_16x16x32_bf16 v[52:55], v[156:159], v[196:199], v[52:55]
	v_mfma_f32_16x16x32_bf16 v[44:47], v[142:145], v[204:207], v[44:47]
	v_mfma_f32_16x16x32_bf16 v[40:43], v[156:159], v[204:207], v[40:43]
	v_mfma_f32_16x16x32_bf16 v[76:79], v[152:155], v[184:187], v[76:79]
	v_mfma_f32_16x16x32_bf16 v[72:75], v[160:163], v[184:187], v[72:75]
	v_mfma_f32_16x16x32_bf16 v[68:71], v[152:155], v[192:195], v[68:71]
	v_mfma_f32_16x16x32_bf16 v[64:67], v[160:163], v[192:195], v[64:67]
	v_mfma_f32_16x16x32_bf16 v[56:59], v[152:155], v[200:203], v[56:59]
	v_mfma_f32_16x16x32_bf16 v[52:55], v[160:163], v[200:203], v[52:55]
	v_mfma_f32_16x16x32_bf16 v[44:47], v[152:155], v[208:211], v[44:47]
	v_mfma_f32_16x16x32_bf16 v[40:43], v[160:163], v[208:211], v[40:43]
	s_setprio 0
	s_setprio 1
	v_mfma_f32_16x16x32_bf16 v[124:127], v[164:167], v[180:183], v[124:127]
	v_mfma_f32_16x16x32_bf16 v[120:123], v[172:175], v[180:183], v[120:123]
	v_mfma_f32_16x16x32_bf16 v[116:119], v[164:167], v[188:191], v[116:119]
	v_mfma_f32_16x16x32_bf16 v[112:115], v[172:175], v[188:191], v[112:115]
	v_mfma_f32_16x16x32_bf16 v[108:111], v[164:167], v[196:199], v[108:111]
	v_mfma_f32_16x16x32_bf16 v[104:107], v[172:175], v[196:199], v[104:107]
	v_mfma_f32_16x16x32_bf16 v[100:103], v[164:167], v[204:207], v[100:103]
	v_mfma_f32_16x16x32_bf16 v[96:99], v[172:175], v[204:207], v[96:99]
	v_mfma_f32_16x16x32_bf16 v[124:127], v[168:171], v[184:187], v[124:127]
	v_mfma_f32_16x16x32_bf16 v[120:123], v[176:179], v[184:187], v[120:123]
	v_mfma_f32_16x16x32_bf16 v[116:119], v[168:171], v[192:195], v[116:119]
	v_mfma_f32_16x16x32_bf16 v[112:115], v[176:179], v[192:195], v[112:115]
	v_mfma_f32_16x16x32_bf16 v[108:111], v[168:171], v[200:203], v[108:111]
	v_mfma_f32_16x16x32_bf16 v[104:107], v[176:179], v[200:203], v[104:107]
	s_setprio 2
	s_barrier
; #define PG8_STAGE(bufoff, gbase, voff) do { _Pragma("unroll") for (int _i = 0; _i < 2; ++_i) \
;         __builtin_amdgcn_global_load_lds((const unsigned*)((const char*)(gbase) + (voff)[_i]), (PG8_LAS unsigned*)(lds + (bufoff) + ldsw + _i * 8192), 16, 0, 0); } while (0)
; #define PG8_LDA(dst, b, h) do { _Pragma("unroll") for (int m = 0; m < 4; ++m) _Pragma("unroll") for (int k = 0; k < 2; ++k) dst[m][k] = *(const PG8_LAS bf16x8*)(lds + PG8_SA(b, h) + aoff + m * 2048 + k * 1024); } while (0)
; #define PG8_MMA(ai, bj, At, Bt) do { __builtin_amdgcn_s_setprio(1); _Pragma("unroll") for (int m = 0; m < 4; ++m) _Pragma("unroll") for (int n = 0; n < 2; ++n) _Pragma("unroll") for (int k = 0; k < 2; ++k) \
;         acc[ai][bj][m][n] = __builtin_amdgcn_mfma_f32_16x16x32_bf16(Bt[n][k], At[m][k], acc[ai][bj][m][n], 0, 0, 0); __builtin_amdgcn_s_setprio(0); } while (0)
; #define PG8_WAIT_V(n) asm volatile("s_waitcnt vmcnt(" #n ")" ::: "memory")
; #define PG8_WAIT_L(n) asm volatile("s_waitcnt lgkmcnt(" #n ")" ::: "memory")
; #define PG8_BAR __builtin_amdgcn_s_barrier()
; #define PG8_SCHED __builtin_amdgcn_sched_barrier(0)
; template <class Epi, class Sched, bool ALIGN_EPI = false, bool SP2 = false>
; __device__ __forceinline__ void gemm_phase(PG8_LAS unsigned char* lds, const Gemm g, const Sched& S, const Epi& E, const int wv  ) {
;     ...
;             PG8_WAIT_V(8); PG8_WAIT_L(0); PG8_BAR; PG8_MMA(0, 0, At, B0); PG8_MMA(0, 1, At, B1); PG8_BAR; PG8_SCHED;
;             PG8_LDA(At, 1, 1); PG8_STAGE(PG8_SB(1, 0), b3, voffB); PG8_STAGE(PG8_SB(1, 1), b3 + hstepB, voffB); PG8_STAGE(PG8_SA(1, 0), a3, voffA);
;             PG8_WAIT_V(8); PG8_WAIT_L(0); PG8_BAR; PG8_MMA(1, 0, At, B0); PG8_MMA(1, 1, At, B1); PG8_BAR; PG8_SCHED;
;     ...
;         if constexpr (ALIGN_EPI) { if (wr == 0) PG8_BAR; }
	v_mfma_f32_16x16x32_bf16 v[100:103], v[168:171], v[208:211], v[100:103]
	v_mfma_f32_16x16x32_bf16 v[96:99], v[176:179], v[208:211], v[96:99]
	s_setprio 0
	s_add_i32 s62, s93, s69
	v_lshl_add_u64 v[212:213], v[212:213], 0, s[8:9]
	s_mov_b32 m0, s62
	ds_read_b128 v[180:183], v150 offset:49152
	ds_read_b128 v[184:187], v150 offset:50176
	ds_read_b128 v[188:191], v150 offset:51200
	ds_read_b128 v[192:195], v150 offset:52224
	ds_read_b128 v[196:199], v150 offset:53248
	ds_read_b128 v[200:203], v150 offset:54272
	ds_read_b128 v[204:207], v150 offset:55296
	ds_read_b128 v[208:211], v150 offset:56320
	global_load_lds_dwordx4 v[212:213], off
	s_add_i32 m0, s62, 0x2000
	s_add_u32 s60, s60, 0x100080
	v_lshl_add_u64 v[212:213], v[214:215], 0, s[8:9]
	s_addc_u32 s61, s61, 0
	s_add_i32 s62, s94, s69
	global_load_lds_dwordx4 v[212:213], off
	v_lshl_add_u64 v[212:213], s[60:61], 0, v[132:133]
	s_mov_b32 m0, s62
	s_nop 0
	global_load_lds_dwordx4 v[212:213], off
	v_lshl_add_u64 v[212:213], s[60:61], 0, v[128:129]
	s_add_i32 m0, s62, 0x2000
	s_nop 0
	global_load_lds_dwordx4 v[212:213], off
	v_lshl_add_u64 v[212:213], v[216:217], 0, s[8:9]
	s_mov_b32 m0, s81
	s_nop 0
	global_load_lds_dwordx4 v[212:213], off
	v_lshl_add_u64 v[212:213], v[218:219], 0, s[8:9]
	s_mov_b32 m0, s82
	s_nop 0
	global_load_lds_dwordx4 v[212:213], off
	s_waitcnt vmcnt(8)
	s_waitcnt lgkmcnt(0)
	s_barrier
	s_setprio 1
	s_waitcnt lgkmcnt(0)
	v_mfma_f32_16x16x32_bf16 v[28:31], v[142:145], v[180:183], v[28:31]
	v_mfma_f32_16x16x32_bf16 v[24:27], v[156:159], v[180:183], v[24:27]
	v_mfma_f32_16x16x32_bf16 v[20:23], v[142:145], v[188:191], v[20:23]
	v_mfma_f32_16x16x32_bf16 v[16:19], v[156:159], v[188:191], v[16:19]
	v_mfma_f32_16x16x32_bf16 v[12:15], v[142:145], v[196:199], v[12:15]
	v_mfma_f32_16x16x32_bf16 v[8:11], v[156:159], v[196:199], v[8:11]
	v_mfma_f32_16x16x32_bf16 v[4:7], v[142:145], v[204:207], v[4:7]
	v_mfma_f32_16x16x32_bf16 v[0:3], v[156:159], v[204:207], v[0:3]
	v_mfma_f32_16x16x32_bf16 v[28:31], v[152:155], v[184:187], v[28:31]
	v_mfma_f32_16x16x32_bf16 v[24:27], v[160:163], v[184:187], v[24:27]
	v_mfma_f32_16x16x32_bf16 v[20:23], v[152:155], v[192:195], v[20:23]
	v_mfma_f32_16x16x32_bf16 v[16:19], v[160:163], v[192:195], v[16:19]
	v_mfma_f32_16x16x32_bf16 v[12:15], v[152:155], v[200:203], v[12:15]
	v_mfma_f32_16x16x32_bf16 v[8:11], v[160:163], v[200:203], v[8:11]
	v_mfma_f32_16x16x32_bf16 v[4:7], v[152:155], v[208:211], v[4:7]
	v_mfma_f32_16x16x32_bf16 v[0:3], v[160:163], v[208:211], v[0:3]
	s_setprio 0
	s_setprio 1
	v_mfma_f32_16x16x32_bf16 v[92:95], v[164:167], v[180:183], v[92:95]
	v_mfma_f32_16x16x32_bf16 v[88:91], v[172:175], v[180:183], v[88:91]
	v_mfma_f32_16x16x32_bf16 v[84:87], v[164:167], v[188:191], v[84:87]
	v_mfma_f32_16x16x32_bf16 v[80:83], v[172:175], v[188:191], v[80:83]
	v_mfma_f32_16x16x32_bf16 v[60:63], v[164:167], v[196:199], v[60:63]
	v_mfma_f32_16x16x32_bf16 v[48:51], v[172:175], v[196:199], v[48:51]
	v_mfma_f32_16x16x32_bf16 v[36:39], v[164:167], v[204:207], v[36:39]
	v_mfma_f32_16x16x32_bf16 v[32:35], v[172:175], v[204:207], v[32:35]
	v_mfma_f32_16x16x32_bf16 v[92:95], v[168:171], v[184:187], v[92:95]
	v_mfma_f32_16x16x32_bf16 v[88:91], v[176:179], v[184:187], v[88:91]
	v_mfma_f32_16x16x32_bf16 v[84:87], v[168:171], v[192:195], v[84:87]
	v_mfma_f32_16x16x32_bf16 v[80:83], v[176:179], v[192:195], v[80:83]
	v_mfma_f32_16x16x32_bf16 v[60:63], v[168:171], v[200:203], v[60:63]
	v_mfma_f32_16x16x32_bf16 v[48:51], v[176:179], v[200:203], v[48:51]
	s_setprio 2
	s_barrier
	v_mfma_f32_16x16x32_bf16 v[36:39], v[168:171], v[208:211], v[36:39]
	v_mfma_f32_16x16x32_bf16 v[32:35], v[176:179], v[208:211], v[32:35]
	s_setprio 0
	s_add_i32 s92, s92, 2
	s_add_u32 s58, s58, 0x100
	s_addc_u32 s59, s59, 0
	s_add_u32 s90, s90, 0x100
	s_addc_u32 s91, s91, 0
	s_cmp_gt_u32 s92, 61
	s_cbranch_scc0 .LBB0_892
	s_and_b64 vcc, exec, s[10:11]
	s_cbranch_vccz .LBB0_895
	s_barrier

; #define PG8_STAGE(bufoff, gbase, voff) do { _Pragma("unroll") for (int _i = 0; _i < 2; ++_i) \
;         __builtin_amdgcn_global_load_lds((const unsigned*)((const char*)(gbase) + (voff)[_i]), (PG8_LAS unsigned*)(lds + (bufoff) + ldsw + _i * 8192), 16, 0, 0); } while (0)
; #define PG8_LDA(dst, b, h) do { _Pragma("unroll") for (int m = 0; m < 4; ++m) _Pragma("unroll") for (int k = 0; k < 2; ++k) dst[m][k] = *(const PG8_LAS bf16x8*)(lds + PG8_SA(b, h) + aoff + m * 2048 + k * 1024); } while (0)
; #define PG8_LDB(dst, b, h) do { _Pragma("unroll") for (int n = 0; n < 2; ++n) _Pragma("unroll") for (int k = 0; k < 2; ++k) dst[n][k] = *(const PG8_LAS bf16x8*)(lds + PG8_SB(b, h) + boff + n * 2048 + k * 1024); } while (0)
; #define PG8_MMA(ai, bj, At, Bt) do { __builtin_amdgcn_s_setprio(1); _Pragma("unroll") for (int m = 0; m < 4; ++m) _Pragma("unroll") for (int n = 0; n < 2; ++n) _Pragma("unroll") for (int k = 0; k < 2; ++k) \
;         acc[ai][bj][m][n] = __builtin_amdgcn_mfma_f32_16x16x32_bf16(Bt[n][k], At[m][k], acc[ai][bj][m][n], 0, 0, 0); __builtin_amdgcn_s_setprio(0); } while (0)
; #define PG8_WAIT_V(n) asm volatile("s_waitcnt vmcnt(" #n ")" ::: "memory")
; #define PG8_BAR __builtin_amdgcn_s_barrier()
; template <class Epi, class Sched, bool ALIGN_EPI = false, bool SP2 = false>
; __device__ __forceinline__ void gemm_phase(PG8_LAS unsigned char* lds, const Gemm g, const Sched& S, const Epi& E, const int wv  ) {
;     ...
;         for (int t = 0; t < nt; t += 2) {
;             const bool last = (t == nt - 2);
;             const char* a1 = cA + (size_t)(t + 1) * kstep;
;             const char* a2 = last ? nA : cA + (size_t)(t + 2) * kstep; const char* b2 = last ? nB : cB + (size_t)(t + 2) * kstep;
;             const char* a3 = a2 + kstep; const char* b3 = b2 + kstep;
;             if (last && has_next) S.a_ready(nxt);
;             if constexpr (SP2) {
;             PG8_LDB(B0, 0, 0); PG8_LDB(B1, 0, 1); PG8_SCHED; PG8_LDA(At, 0, 0); PG8_STAGE(PG8_SA(1, 1), a1 + hstepA, voffA);
;             PG8_WAIT_V(8); PG8_WAIT_L(0); PG8_BAR; PG8_MMA(0, 0, At, B0); PG8_MMA(0, 1, At, B1); PG8_BAR; PG8_SCHED;
;             PG8_LDA(At, 0, 1); PG8_STAGE(PG8_SB(0, 0), b2, voffB); PG8_STAGE(PG8_SB(0, 1), b2 + hstepB, voffB); PG8_STAGE(PG8_SA(0, 0), a2, voffA);
;             PG8_WAIT_V(8); PG8_WAIT_L(0); PG8_BAR; PG8_MMA(1, 0, At, B0); PG8_MMA(1, 1, At, B1); PG8_BAR; PG8_SCHED;
.LBB0_1049:
	ds_read_b128 v[146:149], v152
	ds_read_b128 v[156:159], v152 offset:1024
	ds_read_b128 v[160:163], v152 offset:2048
	ds_read_b128 v[164:167], v152 offset:3072
	ds_read_b128 v[168:171], v153
	ds_read_b128 v[172:175], v153 offset:1024
	ds_read_b128 v[176:179], v153 offset:2048
	ds_read_b128 v[180:183], v153 offset:3072
	s_add_u32 s60, s58, 0xfffc0080
	s_addc_u32 s61, s59, -1
	s_cmp_eq_u32 s87, 12
	s_cselect_b32 s63, s51, s61
	s_cselect_b32 s62, s83, s60
	s_cselect_b32 s61, s49, s86
	s_cselect_b32 s60, s84, s85
	v_lshl_add_u64 v[216:217], s[58:59], 0, v[138:139]
	s_add_i32 m0, s68, 0xc000
	ds_read_b128 v[184:187], v154
	ds_read_b128 v[188:191], v154 offset:1024
	ds_read_b128 v[192:195], v154 offset:2048
	ds_read_b128 v[196:199], v154 offset:3072
	ds_read_b128 v[200:203], v154 offset:4096
	ds_read_b128 v[204:207], v154 offset:5120
	ds_read_b128 v[208:211], v154 offset:6144
	ds_read_b128 v[212:215], v154 offset:7168
	global_load_lds_dwordx4 v[216:217], off
	v_lshl_add_u64 v[216:217], s[58:59], 0, v[140:141]
	s_add_i32 m0, s68, 0xe000
	s_nop 0
	global_load_lds_dwordx4 v[216:217], off
	s_waitcnt vmcnt(8)
	s_waitcnt lgkmcnt(0)
	s_barrier
	s_setprio 1
	s_waitcnt lgkmcnt(0)
	v_mfma_f32_16x16x32_bf16 v[76:79], v[146:149], v[184:187], v[76:79]
	v_mfma_f32_16x16x32_bf16 v[72:75], v[160:163], v[184:187], v[72:75]
	v_mfma_f32_16x16x32_bf16 v[68:71], v[146:149], v[192:195], v[68:71]
	v_mfma_f32_16x16x32_bf16 v[64:67], v[160:163], v[192:195], v[64:67]
	v_mfma_f32_16x16x32_bf16 v[56:59], v[146:149], v[200:203], v[56:59]
	v_mfma_f32_16x16x32_bf16 v[52:55], v[160:163], v[200:203], v[52:55]
	v_mfma_f32_16x16x32_bf16 v[44:47], v[146:149], v[208:211], v[44:47]
	v_mfma_f32_16x16x32_bf16 v[40:43], v[160:163], v[208:211], v[40:43]
	v_mfma_f32_16x16x32_bf16 v[76:79], v[156:159], v[188:191], v[76:79]
	v_mfma_f32_16x16x32_bf16 v[72:75], v[164:167], v[188:191], v[72:75]
	v_mfma_f32_16x16x32_bf16 v[68:71], v[156:159], v[196:199], v[68:71]
	v_mfma_f32_16x16x32_bf16 v[64:67], v[164:167], v[196:199], v[64:67]
	v_mfma_f32_16x16x32_bf16 v[56:59], v[156:159], v[204:207], v[56:59]
	v_mfma_f32_16x16x32_bf16 v[52:55], v[164:167], v[204:207], v[52:55]
	v_mfma_f32_16x16x32_bf16 v[44:47], v[156:159], v[212:215], v[44:47]
	v_mfma_f32_16x16x32_bf16 v[40:43], v[164:167], v[212:215], v[40:43]
	s_setprio 0
	s_setprio 1
	v_mfma_f32_16x16x32_bf16 v[124:127], v[168:171], v[184:187], v[124:127]
	v_mfma_f32_16x16x32_bf16 v[120:123], v[176:179], v[184:187], v[120:123]
	v_mfma_f32_16x16x32_bf16 v[116:119], v[168:171], v[192:195], v[116:119]
	v_mfma_f32_16x16x32_bf16 v[112:115], v[176:179], v[192:195], v[112:115]
	v_mfma_f32_16x16x32_bf16 v[108:111], v[168:171], v[200:203], v[108:111]
	v_mfma_f32_16x16x32_bf16 v[104:107], v[176:179], v[200:203], v[104:107]
	v_mfma_f32_16x16x32_bf16 v[100:103], v[168:171], v[208:211], v[100:103]
	v_mfma_f32_16x16x32_bf16 v[96:99], v[176:179], v[208:211], v[96:99]
	v_mfma_f32_16x16x32_bf16 v[124:127], v[172:175], v[188:191], v[124:127]
	v_mfma_f32_16x16x32_bf16 v[120:123], v[180:183], v[188:191], v[120:123]
	v_mfma_f32_16x16x32_bf16 v[116:119], v[172:175], v[196:199], v[116:119]
	v_mfma_f32_16x16x32_bf16 v[112:115], v[180:183], v[196:199], v[112:115]
	v_mfma_f32_16x16x32_bf16 v[108:111], v[172:175], v[204:207], v[108:111]
	v_mfma_f32_16x16x32_bf16 v[104:107], v[180:183], v[204:207], v[104:107]
	s_setprio 2
	s_barrier
	v_mfma_f32_16x16x32_bf16 v[100:103], v[172:175], v[212:215], v[100:103]
	v_mfma_f32_16x16x32_bf16 v[96:99], v[180:183], v[212:215], v[96:99]
	s_setprio 0
	s_add_i32 s90, s77, s67
	v_lshl_add_u64 v[216:217], s[60:61], 0, v[130:131]
	s_mov_b32 m0, s90
	ds_read_b128 v[184:187], v154 offset:16384
	ds_read_b128 v[188:191], v154 offset:17408
	ds_read_b128 v[192:195], v154 offset:18432
	ds_read_b128 v[196:199], v154 offset:19456
	ds_read_b128 v[200:203], v154 offset:20480
	ds_read_b128 v[204:207], v154 offset:21504
	ds_read_b128 v[208:211], v154 offset:22528
	ds_read_b128 v[212:215], v154 offset:23552
	global_load_lds_dwordx4 v[216:217], off
	s_add_i32 m0, s90, 0x2000
	s_add_u32 s90, s60, 0x40000
	v_lshl_add_u64 v[218:219], s[60:61], 0, v[134:135]
	s_addc_u32 s91, s61, 0
	s_add_i32 s92, s78, s67
	global_load_lds_dwordx4 v[218:219], off
	v_lshl_add_u64 v[220:221], s[90:91], 0, v[130:131]
	s_mov_b32 m0, s92
	v_lshl_add_u64 v[222:223], s[62:63], 0, v[132:133]
	global_load_lds_dwordx4 v[220:221], off
	v_lshl_add_u64 v[220:221], s[90:91], 0, v[134:135]
	s_add_i32 m0, s92, 0x2000
	s_nop 0
	global_load_lds_dwordx4 v[220:221], off
	v_lshl_add_u64 v[220:221], s[62:63], 0, v[128:129]
	s_mov_b32 m0, s68
	s_nop 0
	global_load_lds_dwordx4 v[220:221], off
	s_mov_b32 m0, s69
	s_nop 0
	global_load_lds_dwordx4 v[222:223], off
	s_waitcnt vmcnt(8)
	s_waitcnt lgkmcnt(0)
	s_barrier
; #define PG8_STAGE(bufoff, gbase, voff) do { _Pragma("unroll") for (int _i = 0; _i < 2; ++_i) \
;         __builtin_amdgcn_global_load_lds((const unsigned*)((const char*)(gbase) + (voff)[_i]), (PG8_LAS unsigned*)(lds + (bufoff) + ldsw + _i * 8192), 16, 0, 0); } while (0)
; #define PG8_LDA(dst, b, h) do { _Pragma("unroll") for (int m = 0; m < 4; ++m) _Pragma("unroll") for (int k = 0; k < 2; ++k) dst[m][k] = *(const PG8_LAS bf16x8*)(lds + PG8_SA(b, h) + aoff + m * 2048 + k * 1024); } while (0)
; #define PG8_LDB(dst, b, h) do { _Pragma("unroll") for (int n = 0; n < 2; ++n) _Pragma("unroll") for (int k = 0; k < 2; ++k) dst[n][k] = *(const PG8_LAS bf16x8*)(lds + PG8_SB(b, h) + boff + n * 2048 + k * 1024); } while (0)
; #define PG8_MMA(ai, bj, At, Bt) do { __builtin_amdgcn_s_setprio(1); _Pragma("unroll") for (int m = 0; m < 4; ++m) _Pragma("unroll") for (int n = 0; n < 2; ++n) _Pragma("unroll") for (int k = 0; k < 2; ++k) \
;         acc[ai][bj][m][n] = __builtin_amdgcn_mfma_f32_16x16x32_bf16(Bt[n][k], At[m][k], acc[ai][bj][m][n], 0, 0, 0); __builtin_amdgcn_s_setprio(0); } while (0)
; #define PG8_WAIT_V(n) asm volatile("s_waitcnt vmcnt(" #n ")" ::: "memory")
; #define PG8_WAIT_L(n) asm volatile("s_waitcnt lgkmcnt(" #n ")" ::: "memory")
; #define PG8_BAR __builtin_amdgcn_s_barrier()
; #define PG8_SCHED __builtin_amdgcn_sched_barrier(0)
; template <class Epi, class Sched, bool ALIGN_EPI = false, bool SP2 = false>
; __device__ __forceinline__ void gemm_phase(PG8_LAS unsigned char* lds, const Gemm g, const Sched& S, const Epi& E, const int wv  ) {
;     ...
;             PG8_WAIT_V(8); PG8_WAIT_L(0); PG8_BAR; PG8_MMA(1, 0, At, B0); PG8_MMA(1, 1, At, B1); PG8_BAR; PG8_SCHED;
;             PG8_LDB(B0, 1, 0); PG8_LDB(B1, 1, 1); PG8_SCHED; PG8_LDA(At, 1, 0); PG8_STAGE(PG8_SA(0, 1), a2 + hstepA, voffA);
;             PG8_WAIT_V(8); PG8_WAIT_L(0); PG8_BAR; PG8_MMA(0, 0, At, B0); PG8_MMA(0, 1, At, B1); PG8_BAR; PG8_SCHED;
	s_setprio 1
	s_waitcnt lgkmcnt(0)
	v_mfma_f32_16x16x32_bf16 v[28:31], v[146:149], v[184:187], v[28:31]
	v_mfma_f32_16x16x32_bf16 v[24:27], v[160:163], v[184:187], v[24:27]
	v_mfma_f32_16x16x32_bf16 v[20:23], v[146:149], v[192:195], v[20:23]
	v_mfma_f32_16x16x32_bf16 v[16:19], v[160:163], v[192:195], v[16:19]
	v_mfma_f32_16x16x32_bf16 v[12:15], v[146:149], v[200:203], v[12:15]
	v_mfma_f32_16x16x32_bf16 v[8:11], v[160:163], v[200:203], v[8:11]
	v_mfma_f32_16x16x32_bf16 v[4:7], v[146:149], v[208:211], v[4:7]
	v_mfma_f32_16x16x32_bf16 v[0:3], v[160:163], v[208:211], v[0:3]
	v_mfma_f32_16x16x32_bf16 v[28:31], v[156:159], v[188:191], v[28:31]
	v_mfma_f32_16x16x32_bf16 v[24:27], v[164:167], v[188:191], v[24:27]
	v_mfma_f32_16x16x32_bf16 v[20:23], v[156:159], v[196:199], v[20:23]
	v_mfma_f32_16x16x32_bf16 v[16:19], v[164:167], v[196:199], v[16:19]
	v_mfma_f32_16x16x32_bf16 v[12:15], v[156:159], v[204:207], v[12:15]
	v_mfma_f32_16x16x32_bf16 v[8:11], v[164:167], v[204:207], v[8:11]
	v_mfma_f32_16x16x32_bf16 v[4:7], v[156:159], v[212:215], v[4:7]
	v_mfma_f32_16x16x32_bf16 v[0:3], v[164:167], v[212:215], v[0:3]
	s_setprio 0
	s_setprio 1
	v_mfma_f32_16x16x32_bf16 v[92:95], v[168:171], v[184:187], v[92:95]
	v_mfma_f32_16x16x32_bf16 v[88:91], v[176:179], v[184:187], v[88:91]
	v_mfma_f32_16x16x32_bf16 v[84:87], v[168:171], v[192:195], v[84:87]
	v_mfma_f32_16x16x32_bf16 v[80:83], v[176:179], v[192:195], v[80:83]
	v_mfma_f32_16x16x32_bf16 v[60:63], v[168:171], v[200:203], v[60:63]
	v_mfma_f32_16x16x32_bf16 v[48:51], v[176:179], v[200:203], v[48:51]
	v_mfma_f32_16x16x32_bf16 v[36:39], v[168:171], v[208:211], v[36:39]
	v_mfma_f32_16x16x32_bf16 v[32:35], v[176:179], v[208:211], v[32:35]
	v_mfma_f32_16x16x32_bf16 v[92:95], v[172:175], v[188:191], v[92:95]
	v_mfma_f32_16x16x32_bf16 v[88:91], v[180:183], v[188:191], v[88:91]
	v_mfma_f32_16x16x32_bf16 v[84:87], v[172:175], v[196:199], v[84:87]
	v_mfma_f32_16x16x32_bf16 v[80:83], v[180:183], v[196:199], v[80:83]
	v_mfma_f32_16x16x32_bf16 v[60:63], v[172:175], v[204:207], v[60:63]
	v_mfma_f32_16x16x32_bf16 v[48:51], v[180:183], v[204:207], v[48:51]
	s_setprio 2
	s_barrier
	v_mfma_f32_16x16x32_bf16 v[36:39], v[172:175], v[212:215], v[36:39]
	v_mfma_f32_16x16x32_bf16 v[32:35], v[180:183], v[212:215], v[32:35]
	s_setprio 0
	s_add_i32 s90, 0, 0x18000
	v_add_u32_e32 v155, s90, v150
	s_add_i32 s91, 0, 0x1c000
	ds_read_b128 v[146:149], v155
	ds_read_b128 v[156:159], v155 offset:1024
	ds_read_b128 v[160:163], v155 offset:2048
	ds_read_b128 v[164:167], v155 offset:3072
	v_add_u32_e32 v155, s91, v150
	ds_read_b128 v[168:171], v155
	ds_read_b128 v[172:175], v155 offset:1024
	ds_read_b128 v[176:179], v155 offset:2048
	ds_read_b128 v[180:183], v155 offset:3072
	s_add_u32 s62, s62, 0x40000
	s_addc_u32 s63, s63, 0
	s_mov_b32 m0, s70
	v_lshl_add_u64 v[224:225], s[62:63], 0, v[128:129]
	ds_read_b128 v[184:187], v154 offset:32768
	ds_read_b128 v[188:191], v154 offset:33792
	ds_read_b128 v[192:195], v154 offset:34816
	ds_read_b128 v[196:199], v154 offset:35840
	ds_read_b128 v[200:203], v154 offset:36864
	ds_read_b128 v[204:207], v154 offset:37888
	ds_read_b128 v[208:211], v154 offset:38912
	ds_read_b128 v[212:215], v154 offset:39936
	global_load_lds_dwordx4 v[224:225], off
	v_lshl_add_u64 v[224:225], s[62:63], 0, v[132:133]
	s_mov_b32 m0, s71
	s_nop 0
	global_load_lds_dwordx4 v[224:225], off
	s_waitcnt vmcnt(8)
	s_waitcnt lgkmcnt(0)
	s_barrier
	s_setprio 1
	s_waitcnt lgkmcnt(0)
	v_mfma_f32_16x16x32_bf16 v[76:79], v[146:149], v[184:187], v[76:79]
	v_mfma_f32_16x16x32_bf16 v[72:75], v[160:163], v[184:187], v[72:75]
	v_mfma_f32_16x16x32_bf16 v[68:71], v[146:149], v[192:195], v[68:71]
	v_mfma_f32_16x16x32_bf16 v[64:67], v[160:163], v[192:195], v[64:67]
	v_mfma_f32_16x16x32_bf16 v[56:59], v[146:149], v[200:203], v[56:59]
	v_mfma_f32_16x16x32_bf16 v[52:55], v[160:163], v[200:203], v[52:55]
	v_mfma_f32_16x16x32_bf16 v[44:47], v[146:149], v[208:211], v[44:47]
	v_mfma_f32_16x16x32_bf16 v[40:43], v[160:163], v[208:211], v[40:43]
	v_mfma_f32_16x16x32_bf16 v[76:79], v[156:159], v[188:191], v[76:79]
	v_mfma_f32_16x16x32_bf16 v[72:75], v[164:167], v[188:191], v[72:75]
	v_mfma_f32_16x16x32_bf16 v[68:71], v[156:159], v[196:199], v[68:71]
	v_mfma_f32_16x16x32_bf16 v[64:67], v[164:167], v[196:199], v[64:67]
	v_mfma_f32_16x16x32_bf16 v[56:59], v[156:159], v[204:207], v[56:59]
	v_mfma_f32_16x16x32_bf16 v[52:55], v[164:167], v[204:207], v[52:55]
	v_mfma_f32_16x16x32_bf16 v[44:47], v[156:159], v[212:215], v[44:47]
	v_mfma_f32_16x16x32_bf16 v[40:43], v[164:167], v[212:215], v[40:43]
	s_setprio 0
	s_setprio 1
	v_mfma_f32_16x16x32_bf16 v[124:127], v[168:171], v[184:187], v[124:127]
	v_mfma_f32_16x16x32_bf16 v[120:123], v[176:179], v[184:187], v[120:123]
	v_mfma_f32_16x16x32_bf16 v[116:119], v[168:171], v[192:195], v[116:119]
	v_mfma_f32_16x16x32_bf16 v[112:115], v[176:179], v[192:195], v[112:115]
	v_mfma_f32_16x16x32_bf16 v[108:111], v[168:171], v[200:203], v[108:111]
	v_mfma_f32_16x16x32_bf16 v[104:107], v[176:179], v[200:203], v[104:107]
	v_mfma_f32_16x16x32_bf16 v[100:103], v[168:171], v[208:211], v[100:103]
	v_mfma_f32_16x16x32_bf16 v[96:99], v[176:179], v[208:211], v[96:99]
	v_mfma_f32_16x16x32_bf16 v[124:127], v[172:175], v[188:191], v[124:127]
	v_mfma_f32_16x16x32_bf16 v[120:123], v[180:183], v[188:191], v[120:123]
	v_mfma_f32_16x16x32_bf16 v[116:119], v[172:175], v[196:199], v[116:119]
	v_mfma_f32_16x16x32_bf16 v[112:115], v[180:183], v[196:199], v[112:115]
	v_mfma_f32_16x16x32_bf16 v[108:111], v[172:175], v[204:207], v[108:111]
	v_mfma_f32_16x16x32_bf16 v[104:107], v[180:183], v[204:207], v[104:107]
	s_setprio 2
	s_barrier
; #define PG8_STAGE(bufoff, gbase, voff) do { _Pragma("unroll") for (int _i = 0; _i < 2; ++_i) \
;         __builtin_amdgcn_global_load_lds((const unsigned*)((const char*)(gbase) + (voff)[_i]), (PG8_LAS unsigned*)(lds + (bufoff) + ldsw + _i * 8192), 16, 0, 0); } while (0)
; #define PG8_LDA(dst, b, h) do { _Pragma("unroll") for (int m = 0; m < 4; ++m) _Pragma("unroll") for (int k = 0; k < 2; ++k) dst[m][k] = *(const PG8_LAS bf16x8*)(lds + PG8_SA(b, h) + aoff + m * 2048 + k * 1024); } while (0)
; #define PG8_MMA(ai, bj, At, Bt) do { __builtin_amdgcn_s_setprio(1); _Pragma("unroll") for (int m = 0; m < 4; ++m) _Pragma("unroll") for (int n = 0; n < 2; ++n) _Pragma("unroll") for (int k = 0; k < 2; ++k) \
;         acc[ai][bj][m][n] = __builtin_amdgcn_mfma_f32_16x16x32_bf16(Bt[n][k], At[m][k], acc[ai][bj][m][n], 0, 0, 0); __builtin_amdgcn_s_setprio(0); } while (0)
; #define PG8_WAIT_V(n) asm volatile("s_waitcnt vmcnt(" #n ")" ::: "memory")
; #define PG8_WAIT_L(n) asm volatile("s_waitcnt lgkmcnt(" #n ")" ::: "memory")
; #define PG8_BAR __builtin_amdgcn_s_barrier()
; #define PG8_SCHED __builtin_amdgcn_sched_barrier(0)
; template <class Epi, class Sched, bool ALIGN_EPI = false, bool SP2 = false>
; __device__ __forceinline__ void gemm_phase(PG8_LAS unsigned char* lds, const Gemm g, const Sched& S, const Epi& E, const int wv  ) {
;     ...
;             PG8_WAIT_V(8); PG8_WAIT_L(0); PG8_BAR; PG8_MMA(0, 0, At, B0); PG8_MMA(0, 1, At, B1); PG8_BAR; PG8_SCHED;
;             PG8_LDA(At, 1, 1); PG8_STAGE(PG8_SB(1, 0), b3, voffB); PG8_STAGE(PG8_SB(1, 1), b3 + hstepB, voffB); PG8_STAGE(PG8_SA(1, 0), a3, voffA);
;             PG8_WAIT_V(8); PG8_WAIT_L(0); PG8_BAR; PG8_MMA(1, 0, At, B0); PG8_MMA(1, 1, At, B1); PG8_BAR; PG8_SCHED;
;     ...
;         if constexpr (ALIGN_EPI) { if (wr == 0) PG8_BAR; }
	v_mfma_f32_16x16x32_bf16 v[100:103], v[172:175], v[212:215], v[100:103]
	v_mfma_f32_16x16x32_bf16 v[96:99], v[180:183], v[212:215], v[96:99]
	s_setprio 0
	s_add_i32 s62, s90, s67
	v_lshl_add_u64 v[216:217], v[216:217], 0, s[10:11]
	s_mov_b32 m0, s62
	ds_read_b128 v[184:187], v154 offset:49152
	ds_read_b128 v[188:191], v154 offset:50176
	ds_read_b128 v[192:195], v154 offset:51200
	ds_read_b128 v[196:199], v154 offset:52224
	ds_read_b128 v[200:203], v154 offset:53248
	ds_read_b128 v[204:207], v154 offset:54272
	ds_read_b128 v[208:211], v154 offset:55296
	ds_read_b128 v[212:215], v154 offset:56320
	global_load_lds_dwordx4 v[216:217], off
	s_add_i32 m0, s62, 0x2000
	s_add_u32 s60, s60, 0x40080
	v_lshl_add_u64 v[216:217], v[218:219], 0, s[10:11]
	s_addc_u32 s61, s61, 0
	s_add_i32 s62, s91, s67
	global_load_lds_dwordx4 v[216:217], off
	v_lshl_add_u64 v[216:217], s[60:61], 0, v[130:131]
	s_mov_b32 m0, s62
	s_nop 0
	global_load_lds_dwordx4 v[216:217], off
	v_lshl_add_u64 v[216:217], s[60:61], 0, v[134:135]
	s_add_i32 m0, s62, 0x2000
	s_nop 0
	global_load_lds_dwordx4 v[216:217], off
	v_lshl_add_u64 v[216:217], v[220:221], 0, s[10:11]
	s_mov_b32 m0, s74
	s_nop 0
	global_load_lds_dwordx4 v[216:217], off
	v_lshl_add_u64 v[216:217], v[222:223], 0, s[10:11]
	s_mov_b32 m0, s75
	s_nop 0
	global_load_lds_dwordx4 v[216:217], off
	s_waitcnt vmcnt(8)
	s_waitcnt lgkmcnt(0)
	s_barrier
	s_setprio 1
	s_waitcnt lgkmcnt(0)
	v_mfma_f32_16x16x32_bf16 v[28:31], v[146:149], v[184:187], v[28:31]
	v_mfma_f32_16x16x32_bf16 v[24:27], v[160:163], v[184:187], v[24:27]
	v_mfma_f32_16x16x32_bf16 v[20:23], v[146:149], v[192:195], v[20:23]
	v_mfma_f32_16x16x32_bf16 v[16:19], v[160:163], v[192:195], v[16:19]
	v_mfma_f32_16x16x32_bf16 v[12:15], v[146:149], v[200:203], v[12:15]
	v_mfma_f32_16x16x32_bf16 v[8:11], v[160:163], v[200:203], v[8:11]
	v_mfma_f32_16x16x32_bf16 v[4:7], v[146:149], v[208:211], v[4:7]
	v_mfma_f32_16x16x32_bf16 v[0:3], v[160:163], v[208:211], v[0:3]
	v_mfma_f32_16x16x32_bf16 v[28:31], v[156:159], v[188:191], v[28:31]
	v_mfma_f32_16x16x32_bf16 v[24:27], v[164:167], v[188:191], v[24:27]
	v_mfma_f32_16x16x32_bf16 v[20:23], v[156:159], v[196:199], v[20:23]
	v_mfma_f32_16x16x32_bf16 v[16:19], v[164:167], v[196:199], v[16:19]
	v_mfma_f32_16x16x32_bf16 v[12:15], v[156:159], v[204:207], v[12:15]
	v_mfma_f32_16x16x32_bf16 v[8:11], v[164:167], v[204:207], v[8:11]
	v_mfma_f32_16x16x32_bf16 v[4:7], v[156:159], v[212:215], v[4:7]
	v_mfma_f32_16x16x32_bf16 v[0:3], v[164:167], v[212:215], v[0:3]
	s_setprio 0
	s_setprio 1
	v_mfma_f32_16x16x32_bf16 v[92:95], v[168:171], v[184:187], v[92:95]
	v_mfma_f32_16x16x32_bf16 v[88:91], v[176:179], v[184:187], v[88:91]
	v_mfma_f32_16x16x32_bf16 v[84:87], v[168:171], v[192:195], v[84:87]
	v_mfma_f32_16x16x32_bf16 v[80:83], v[176:179], v[192:195], v[80:83]
	v_mfma_f32_16x16x32_bf16 v[60:63], v[168:171], v[200:203], v[60:63]
	v_mfma_f32_16x16x32_bf16 v[48:51], v[176:179], v[200:203], v[48:51]
	v_mfma_f32_16x16x32_bf16 v[36:39], v[168:171], v[208:211], v[36:39]
	v_mfma_f32_16x16x32_bf16 v[32:35], v[176:179], v[208:211], v[32:35]
	v_mfma_f32_16x16x32_bf16 v[92:95], v[172:175], v[188:191], v[92:95]
	v_mfma_f32_16x16x32_bf16 v[88:91], v[180:183], v[188:191], v[88:91]
	v_mfma_f32_16x16x32_bf16 v[84:87], v[172:175], v[196:199], v[84:87]
	v_mfma_f32_16x16x32_bf16 v[80:83], v[180:183], v[196:199], v[80:83]
	v_mfma_f32_16x16x32_bf16 v[60:63], v[172:175], v[204:207], v[60:63]
	v_mfma_f32_16x16x32_bf16 v[48:51], v[180:183], v[204:207], v[48:51]
	s_setprio 2
	s_barrier
	v_mfma_f32_16x16x32_bf16 v[36:39], v[172:175], v[212:215], v[36:39]
	v_mfma_f32_16x16x32_bf16 v[32:35], v[180:183], v[212:215], v[32:35]
	s_setprio 0
	s_add_i32 s87, s87, 2
	s_add_u32 s58, s58, 0x100
	s_addc_u32 s59, s59, 0
	s_add_u32 s85, s85, 0x100
	s_addc_u32 s86, s86, 0
	s_cmp_gt_u32 s87, 13
	s_cbranch_scc0 .LBB0_1049
	s_and_b64 vcc, exec, s[12:13]
	s_cbranch_vccz .LBB0_1052
	s_barrier

; #define PG8_STAGE(bufoff, gbase, voff) do { _Pragma("unroll") for (int _i = 0; _i < 2; ++_i) \
;         __builtin_amdgcn_global_load_lds((const unsigned*)((const char*)(gbase) + (voff)[_i]), (PG8_LAS unsigned*)(lds + (bufoff) + ldsw + _i * 8192), 16, 0, 0); } while (0)
; #define PG8_LDA(dst, b, h) do { _Pragma("unroll") for (int m = 0; m < 4; ++m) _Pragma("unroll") for (int k = 0; k < 2; ++k) dst[m][k] = *(const PG8_LAS bf16x8*)(lds + PG8_SA(b, h) + aoff + m * 2048 + k * 1024); } while (0)
; #define PG8_LDB(dst, b, h) do { _Pragma("unroll") for (int n = 0; n < 2; ++n) _Pragma("unroll") for (int k = 0; k < 2; ++k) dst[n][k] = *(const PG8_LAS bf16x8*)(lds + PG8_SB(b, h) + boff + n * 2048 + k * 1024); } while (0)
; #define PG8_MMA(ai, bj, At, Bt) do { __builtin_amdgcn_s_setprio(1); _Pragma("unroll") for (int m = 0; m < 4; ++m) _Pragma("unroll") for (int n = 0; n < 2; ++n) _Pragma("unroll") for (int k = 0; k < 2; ++k) \
;         acc[ai][bj][m][n] = __builtin_amdgcn_mfma_f32_16x16x32_bf16(Bt[n][k], At[m][k], acc[ai][bj][m][n], 0, 0, 0); __builtin_amdgcn_s_setprio(0); } while (0)
; #define PG8_WAIT_V(n) asm volatile("s_waitcnt vmcnt(" #n ")" ::: "memory")
; #define PG8_BAR __builtin_amdgcn_s_barrier()
; template <class Epi, class Sched, bool ALIGN_EPI = false, bool SP2 = false>
; __device__ __forceinline__ void gemm_phase(PG8_LAS unsigned char* lds, const Gemm g, const Sched& S, const Epi& E, const int wv  ) {
;     ...
;         for (int t = 0; t < nt; t += 2) {
;             const bool last = (t == nt - 2);
;             const char* a1 = cA + (size_t)(t + 1) * kstep;
;             const char* a2 = last ? nA : cA + (size_t)(t + 2) * kstep; const char* b2 = last ? nB : cB + (size_t)(t + 2) * kstep;
;             const char* a3 = a2 + kstep; const char* b3 = b2 + kstep;
;             if (last && has_next) S.a_ready(nxt);
;             if constexpr (SP2) {
;             PG8_LDB(B0, 0, 0); PG8_LDB(B1, 0, 1); PG8_SCHED; PG8_LDA(At, 0, 0); PG8_STAGE(PG8_SA(1, 1), a1 + hstepA, voffA);
;             PG8_WAIT_V(8); PG8_WAIT_L(0); PG8_BAR; PG8_MMA(0, 0, At, B0); PG8_MMA(0, 1, At, B1); PG8_BAR; PG8_SCHED;
;             PG8_LDA(At, 0, 1); PG8_STAGE(PG8_SB(0, 0), b2, voffB); PG8_STAGE(PG8_SB(0, 1), b2 + hstepB, voffB); PG8_STAGE(PG8_SA(0, 0), a2, voffA);
;             PG8_WAIT_V(8); PG8_WAIT_L(0); PG8_BAR; PG8_MMA(1, 0, At, B0); PG8_MMA(1, 1, At, B1); PG8_BAR; PG8_SCHED;
.LBB0_1187:
	ds_read_b128 v[44:47], v196
	ds_read_b128 v[48:51], v196 offset:1024
	ds_read_b128 v[52:55], v196 offset:2048
	ds_read_b128 v[56:59], v196 offset:3072
	ds_read_b128 v[60:63], v197
	ds_read_b128 v[68:71], v197 offset:1024
	ds_read_b128 v[72:75], v197 offset:2048
	ds_read_b128 v[76:79], v197 offset:3072
	s_add_u32 s68, s66, 0xfff00080
	s_addc_u32 s69, s67, -1
	s_cmp_eq_u32 s94, 60
	s_cselect_b32 s71, s57, s69
	s_cselect_b32 s70, s63, s68
	s_cselect_b32 s69, s55, s93
	s_cselect_b32 s68, s65, s92
	v_lshl_add_u64 v[224:225], s[66:67], 0, v[172:173]
	s_add_i32 m0, s75, 0xc000
	ds_read_b128 v[180:183], v198
	ds_read_b128 v[184:187], v198 offset:1024
	ds_read_b128 v[200:203], v198 offset:2048
	ds_read_b128 v[204:207], v198 offset:3072
	ds_read_b128 v[208:211], v198 offset:4096
	ds_read_b128 v[212:215], v198 offset:5120
	ds_read_b128 v[216:219], v198 offset:6144
	ds_read_b128 v[220:223], v198 offset:7168
	global_load_lds_dwordx4 v[224:225], off
	v_lshl_add_u64 v[224:225], s[66:67], 0, v[174:175]
	s_add_i32 m0, s75, 0xe000
	s_nop 0
	global_load_lds_dwordx4 v[224:225], off
	s_waitcnt vmcnt(8)
	s_waitcnt lgkmcnt(0)
	s_barrier
	s_setprio 1
	s_waitcnt lgkmcnt(0)
	v_mfma_f32_16x16x32_bf16 v[104:107], v[44:47], v[180:183], v[104:107]
	v_mfma_f32_16x16x32_bf16 v[100:103], v[52:55], v[180:183], v[100:103]
	v_mfma_f32_16x16x32_bf16 v[156:159], v[44:47], v[200:203], v[156:159]
	v_mfma_f32_16x16x32_bf16 v[148:151], v[52:55], v[200:203], v[148:151]
	v_mfma_f32_16x16x32_bf16 v[140:143], v[44:47], v[208:211], v[140:143]
	v_mfma_f32_16x16x32_bf16 v[132:135], v[52:55], v[208:211], v[132:135]
	v_mfma_f32_16x16x32_bf16 v[124:127], v[44:47], v[216:219], v[124:127]
	v_mfma_f32_16x16x32_bf16 v[120:123], v[52:55], v[216:219], v[120:123]
	v_mfma_f32_16x16x32_bf16 v[104:107], v[48:51], v[184:187], v[104:107]
	v_mfma_f32_16x16x32_bf16 v[100:103], v[56:59], v[184:187], v[100:103]
	v_mfma_f32_16x16x32_bf16 v[156:159], v[48:51], v[204:207], v[156:159]
	v_mfma_f32_16x16x32_bf16 v[148:151], v[56:59], v[204:207], v[148:151]
	v_mfma_f32_16x16x32_bf16 v[140:143], v[48:51], v[212:215], v[140:143]
	v_mfma_f32_16x16x32_bf16 v[132:135], v[56:59], v[212:215], v[132:135]
	v_mfma_f32_16x16x32_bf16 v[124:127], v[48:51], v[220:223], v[124:127]
	v_mfma_f32_16x16x32_bf16 v[120:123], v[56:59], v[220:223], v[120:123]
	s_setprio 0
	s_setprio 1
	v_mfma_f32_16x16x32_bf16 v[92:95], v[60:63], v[180:183], v[92:95]
	v_mfma_f32_16x16x32_bf16 v[88:91], v[72:75], v[180:183], v[88:91]
	v_mfma_f32_16x16x32_bf16 v[152:155], v[60:63], v[200:203], v[152:155]
	v_mfma_f32_16x16x32_bf16 v[144:147], v[72:75], v[200:203], v[144:147]
	v_mfma_f32_16x16x32_bf16 v[136:139], v[60:63], v[208:211], v[136:139]
	v_mfma_f32_16x16x32_bf16 v[128:131], v[72:75], v[208:211], v[128:131]
	v_mfma_f32_16x16x32_bf16 v[116:119], v[60:63], v[216:219], v[116:119]
	v_mfma_f32_16x16x32_bf16 v[112:115], v[72:75], v[216:219], v[112:115]
	v_mfma_f32_16x16x32_bf16 v[92:95], v[68:71], v[184:187], v[92:95]
	v_mfma_f32_16x16x32_bf16 v[88:91], v[76:79], v[184:187], v[88:91]
	v_mfma_f32_16x16x32_bf16 v[152:155], v[68:71], v[204:207], v[152:155]
	v_mfma_f32_16x16x32_bf16 v[144:147], v[76:79], v[204:207], v[144:147]
	v_mfma_f32_16x16x32_bf16 v[136:139], v[68:71], v[212:215], v[136:139]
	v_mfma_f32_16x16x32_bf16 v[128:131], v[76:79], v[212:215], v[128:131]
	s_setprio 2
	s_barrier
	v_mfma_f32_16x16x32_bf16 v[116:119], v[68:71], v[220:223], v[116:119]
	v_mfma_f32_16x16x32_bf16 v[112:115], v[76:79], v[220:223], v[112:115]
	s_setprio 0
	s_add_i32 s95, s87, s74
	v_lshl_add_u64 v[228:229], s[68:69], 0, v[162:163]
	s_mov_b32 m0, s95
	ds_read_b128 v[180:183], v198 offset:16384
	ds_read_b128 v[184:187], v198 offset:17408
	ds_read_b128 v[200:203], v198 offset:18432
	ds_read_b128 v[204:207], v198 offset:19456
	ds_read_b128 v[208:211], v198 offset:20480
	ds_read_b128 v[212:215], v198 offset:21504
	ds_read_b128 v[216:219], v198 offset:22528
	ds_read_b128 v[220:223], v198 offset:23552
	global_load_lds_dwordx4 v[228:229], off
	s_add_i32 m0, s95, 0x2000
	s_add_u32 s96, s68, 0x100000
	v_lshl_add_u64 v[230:231], s[68:69], 0, v[166:167]
	s_addc_u32 s97, s69, 0
	s_add_i32 s95, s90, s74
	global_load_lds_dwordx4 v[230:231], off
	v_lshl_add_u64 v[224:225], s[96:97], 0, v[162:163]
	s_mov_b32 m0, s95
	v_lshl_add_u64 v[232:233], s[70:71], 0, v[160:161]
	global_load_lds_dwordx4 v[224:225], off
	v_lshl_add_u64 v[224:225], s[96:97], 0, v[166:167]
	s_add_i32 m0, s95, 0x2000
	v_lshl_add_u64 v[234:235], s[70:71], 0, v[164:165]
	global_load_lds_dwordx4 v[224:225], off
	s_mov_b32 m0, s75
	s_nop 0
	global_load_lds_dwordx4 v[232:233], off
	s_mov_b32 m0, s76
	s_nop 0
	global_load_lds_dwordx4 v[234:235], off
	s_waitcnt vmcnt(8)
	s_waitcnt lgkmcnt(0)
	s_barrier
; #define PG8_STAGE(bufoff, gbase, voff) do { _Pragma("unroll") for (int _i = 0; _i < 2; ++_i) \
;         __builtin_amdgcn_global_load_lds((const unsigned*)((const char*)(gbase) + (voff)[_i]), (PG8_LAS unsigned*)(lds + (bufoff) + ldsw + _i * 8192), 16, 0, 0); } while (0)
; #define PG8_LDA(dst, b, h) do { _Pragma("unroll") for (int m = 0; m < 4; ++m) _Pragma("unroll") for (int k = 0; k < 2; ++k) dst[m][k] = *(const PG8_LAS bf16x8*)(lds + PG8_SA(b, h) + aoff + m * 2048 + k * 1024); } while (0)
; #define PG8_LDB(dst, b, h) do { _Pragma("unroll") for (int n = 0; n < 2; ++n) _Pragma("unroll") for (int k = 0; k < 2; ++k) dst[n][k] = *(const PG8_LAS bf16x8*)(lds + PG8_SB(b, h) + boff + n * 2048 + k * 1024); } while (0)
; #define PG8_MMA(ai, bj, At, Bt) do { __builtin_amdgcn_s_setprio(1); _Pragma("unroll") for (int m = 0; m < 4; ++m) _Pragma("unroll") for (int n = 0; n < 2; ++n) _Pragma("unroll") for (int k = 0; k < 2; ++k) \
;         acc[ai][bj][m][n] = __builtin_amdgcn_mfma_f32_16x16x32_bf16(Bt[n][k], At[m][k], acc[ai][bj][m][n], 0, 0, 0); __builtin_amdgcn_s_setprio(0); } while (0)
; #define PG8_WAIT_V(n) asm volatile("s_waitcnt vmcnt(" #n ")" ::: "memory")
; #define PG8_WAIT_L(n) asm volatile("s_waitcnt lgkmcnt(" #n ")" ::: "memory")
; #define PG8_BAR __builtin_amdgcn_s_barrier()
; #define PG8_SCHED __builtin_amdgcn_sched_barrier(0)
; template <class Epi, class Sched, bool ALIGN_EPI = false, bool SP2 = false>
; __device__ __forceinline__ void gemm_phase(PG8_LAS unsigned char* lds, const Gemm g, const Sched& S, const Epi& E, const int wv  ) {
;     ...
;             PG8_WAIT_V(8); PG8_WAIT_L(0); PG8_BAR; PG8_MMA(1, 0, At, B0); PG8_MMA(1, 1, At, B1); PG8_BAR; PG8_SCHED;
;             PG8_LDB(B0, 1, 0); PG8_LDB(B1, 1, 1); PG8_SCHED; PG8_LDA(At, 1, 0); PG8_STAGE(PG8_SA(0, 1), a2 + hstepA, voffA);
;             PG8_WAIT_V(8); PG8_WAIT_L(0); PG8_BAR; PG8_MMA(0, 0, At, B0); PG8_MMA(0, 1, At, B1); PG8_BAR; PG8_SCHED;
	s_setprio 1
	s_waitcnt lgkmcnt(0)
	v_mfma_f32_16x16x32_bf16 v[108:111], v[44:47], v[180:183], v[108:111]
	v_mfma_f32_16x16x32_bf16 v[96:99], v[52:55], v[180:183], v[96:99]
	v_mfma_f32_16x16x32_bf16 v[64:67], v[44:47], v[200:203], v[64:67]
	v_mfma_f32_16x16x32_bf16 v[36:39], v[52:55], v[200:203], v[36:39]
	v_mfma_f32_16x16x32_bf16 v[28:31], v[44:47], v[208:211], v[28:31]
	v_mfma_f32_16x16x32_bf16 v[20:23], v[52:55], v[208:211], v[20:23]
	v_mfma_f32_16x16x32_bf16 v[12:15], v[44:47], v[216:219], v[12:15]
	v_mfma_f32_16x16x32_bf16 v[4:7], v[52:55], v[216:219], v[4:7]
	v_mfma_f32_16x16x32_bf16 v[108:111], v[48:51], v[184:187], v[108:111]
	v_mfma_f32_16x16x32_bf16 v[96:99], v[56:59], v[184:187], v[96:99]
	v_mfma_f32_16x16x32_bf16 v[64:67], v[48:51], v[204:207], v[64:67]
	v_mfma_f32_16x16x32_bf16 v[36:39], v[56:59], v[204:207], v[36:39]
	v_mfma_f32_16x16x32_bf16 v[28:31], v[48:51], v[212:215], v[28:31]
	v_mfma_f32_16x16x32_bf16 v[20:23], v[56:59], v[212:215], v[20:23]
	v_mfma_f32_16x16x32_bf16 v[12:15], v[48:51], v[220:223], v[12:15]
	v_mfma_f32_16x16x32_bf16 v[4:7], v[56:59], v[220:223], v[4:7]
	s_setprio 0
	s_setprio 1
	v_mfma_f32_16x16x32_bf16 v[40:43], v[60:63], v[200:203], v[40:43]
	v_mfma_f32_16x16x32_bf16 v[32:35], v[72:75], v[200:203], v[32:35]
	v_mfma_f32_16x16x32_bf16 v[24:27], v[60:63], v[208:211], v[24:27]
	v_mfma_f32_16x16x32_bf16 v[16:19], v[72:75], v[208:211], v[16:19]
	v_mfma_f32_16x16x32_bf16 v[8:11], v[60:63], v[216:219], v[8:11]
	v_mfma_f32_16x16x32_bf16 v[0:3], v[72:75], v[216:219], v[0:3]
	v_mfma_f32_16x16x32_bf16 v[44:47], v[60:63], v[180:183], v[84:87]
	v_mfma_f32_16x16x32_bf16 v[48:51], v[72:75], v[180:183], v[80:83]
	v_mfma_f32_16x16x32_bf16 v[40:43], v[68:71], v[204:207], v[40:43]
	v_mfma_f32_16x16x32_bf16 v[32:35], v[76:79], v[204:207], v[32:35]
	v_mfma_f32_16x16x32_bf16 v[24:27], v[68:71], v[212:215], v[24:27]
	v_mfma_f32_16x16x32_bf16 v[16:19], v[76:79], v[212:215], v[16:19]
	v_mfma_f32_16x16x32_bf16 v[8:11], v[68:71], v[220:223], v[8:11]
	v_mfma_f32_16x16x32_bf16 v[0:3], v[76:79], v[220:223], v[0:3]
	s_setprio 2
	s_barrier
	v_mfma_f32_16x16x32_bf16 v[44:47], v[68:71], v[184:187], v[44:47]
	v_mfma_f32_16x16x32_bf16 v[48:51], v[76:79], v[184:187], v[48:51]
	s_setprio 0
	s_add_i32 s95, 0, 0x18000
	s_add_i32 s96, 0, 0x1c000
	v_add_u32_e32 v68, s95, v190
	v_add_u32_e32 v80, s96, v190
	ds_read_b128 v[52:55], v68
	ds_read_b128 v[56:59], v68 offset:1024
	ds_read_b128 v[60:63], v68 offset:2048
	ds_read_b128 v[68:71], v68 offset:3072
	ds_read_b128 v[72:75], v80
	ds_read_b128 v[76:79], v80 offset:1024
	ds_read_b128 v[180:183], v80 offset:2048
	ds_read_b128 v[184:187], v80 offset:3072
	s_add_u32 s70, s70, 0x100000
	s_addc_u32 s71, s71, 0
	s_mov_b32 m0, s77
	v_lshl_add_u64 v[224:225], s[70:71], 0, v[160:161]
	ds_read_b128 v[80:83], v198 offset:32768
	ds_read_b128 v[84:87], v198 offset:33792
	ds_read_b128 v[200:203], v198 offset:34816
	ds_read_b128 v[204:207], v198 offset:35840
	ds_read_b128 v[208:211], v198 offset:36864
	ds_read_b128 v[212:215], v198 offset:37888
	ds_read_b128 v[216:219], v198 offset:38912
	ds_read_b128 v[220:223], v198 offset:39936
	global_load_lds_dwordx4 v[224:225], off
	v_lshl_add_u64 v[224:225], s[70:71], 0, v[164:165]
	s_mov_b32 m0, s78
	s_nop 0
	global_load_lds_dwordx4 v[224:225], off
	s_waitcnt vmcnt(8)
	s_waitcnt lgkmcnt(0)
	s_barrier
	s_setprio 1
	s_waitcnt lgkmcnt(0)
	v_mfma_f32_16x16x32_bf16 v[104:107], v[52:55], v[80:83], v[104:107]
	v_mfma_f32_16x16x32_bf16 v[100:103], v[60:63], v[80:83], v[100:103]
	v_mfma_f32_16x16x32_bf16 v[156:159], v[52:55], v[200:203], v[156:159]
	v_mfma_f32_16x16x32_bf16 v[148:151], v[60:63], v[200:203], v[148:151]
	v_mfma_f32_16x16x32_bf16 v[140:143], v[52:55], v[208:211], v[140:143]
	v_mfma_f32_16x16x32_bf16 v[132:135], v[60:63], v[208:211], v[132:135]
	v_mfma_f32_16x16x32_bf16 v[124:127], v[52:55], v[216:219], v[124:127]
	v_mfma_f32_16x16x32_bf16 v[120:123], v[60:63], v[216:219], v[120:123]
	v_mfma_f32_16x16x32_bf16 v[104:107], v[56:59], v[84:87], v[104:107]
	v_mfma_f32_16x16x32_bf16 v[100:103], v[68:71], v[84:87], v[100:103]
	v_mfma_f32_16x16x32_bf16 v[156:159], v[56:59], v[204:207], v[156:159]
	v_mfma_f32_16x16x32_bf16 v[148:151], v[68:71], v[204:207], v[148:151]
	v_mfma_f32_16x16x32_bf16 v[140:143], v[56:59], v[212:215], v[140:143]
	v_mfma_f32_16x16x32_bf16 v[132:135], v[68:71], v[212:215], v[132:135]
	v_mfma_f32_16x16x32_bf16 v[124:127], v[56:59], v[220:223], v[124:127]
	v_mfma_f32_16x16x32_bf16 v[120:123], v[68:71], v[220:223], v[120:123]
	s_setprio 0
	s_setprio 1
	v_mfma_f32_16x16x32_bf16 v[92:95], v[72:75], v[80:83], v[92:95]
	v_mfma_f32_16x16x32_bf16 v[80:83], v[180:183], v[80:83], v[88:91]
	v_mfma_f32_16x16x32_bf16 v[88:91], v[184:187], v[84:87], v[80:83]
	v_mfma_f32_16x16x32_bf16 v[80:83], v[72:75], v[200:203], v[152:155]
	v_mfma_f32_16x16x32_bf16 v[152:155], v[76:79], v[204:207], v[80:83]
	v_mfma_f32_16x16x32_bf16 v[80:83], v[180:183], v[200:203], v[144:147]
	v_mfma_f32_16x16x32_bf16 v[144:147], v[184:187], v[204:207], v[80:83]
	v_mfma_f32_16x16x32_bf16 v[80:83], v[72:75], v[208:211], v[136:139]
	v_mfma_f32_16x16x32_bf16 v[136:139], v[76:79], v[212:215], v[80:83]
	v_mfma_f32_16x16x32_bf16 v[80:83], v[180:183], v[208:211], v[128:131]
	v_mfma_f32_16x16x32_bf16 v[128:131], v[184:187], v[212:215], v[80:83]
	v_mfma_f32_16x16x32_bf16 v[80:83], v[72:75], v[216:219], v[116:119]
	v_mfma_f32_16x16x32_bf16 v[116:119], v[76:79], v[220:223], v[80:83]
	v_mfma_f32_16x16x32_bf16 v[80:83], v[180:183], v[216:219], v[112:115]
	s_setprio 2
	s_barrier
; #define PG8_STAGE(bufoff, gbase, voff) do { _Pragma("unroll") for (int _i = 0; _i < 2; ++_i) \
;         __builtin_amdgcn_global_load_lds((const unsigned*)((const char*)(gbase) + (voff)[_i]), (PG8_LAS unsigned*)(lds + (bufoff) + ldsw + _i * 8192), 16, 0, 0); } while (0)
; #define PG8_LDA(dst, b, h) do { _Pragma("unroll") for (int m = 0; m < 4; ++m) _Pragma("unroll") for (int k = 0; k < 2; ++k) dst[m][k] = *(const PG8_LAS bf16x8*)(lds + PG8_SA(b, h) + aoff + m * 2048 + k * 1024); } while (0)
; #define PG8_MMA(ai, bj, At, Bt) do { __builtin_amdgcn_s_setprio(1); _Pragma("unroll") for (int m = 0; m < 4; ++m) _Pragma("unroll") for (int n = 0; n < 2; ++n) _Pragma("unroll") for (int k = 0; k < 2; ++k) \
;         acc[ai][bj][m][n] = __builtin_amdgcn_mfma_f32_16x16x32_bf16(Bt[n][k], At[m][k], acc[ai][bj][m][n], 0, 0, 0); __builtin_amdgcn_s_setprio(0); } while (0)
; #define PG8_WAIT_V(n) asm volatile("s_waitcnt vmcnt(" #n ")" ::: "memory")
; #define PG8_WAIT_L(n) asm volatile("s_waitcnt lgkmcnt(" #n ")" ::: "memory")
; #define PG8_BAR __builtin_amdgcn_s_barrier()
; #define PG8_SCHED __builtin_amdgcn_sched_barrier(0)
; template <class Epi, class Sched, bool ALIGN_EPI = false, bool SP2 = false>
; __device__ __forceinline__ void gemm_phase(PG8_LAS unsigned char* lds, const Gemm g, const Sched& S, const Epi& E, const int wv  ) {
;     ...
;             PG8_WAIT_V(8); PG8_WAIT_L(0); PG8_BAR; PG8_MMA(0, 0, At, B0); PG8_MMA(0, 1, At, B1); PG8_BAR; PG8_SCHED;
;             PG8_LDA(At, 1, 1); PG8_STAGE(PG8_SB(1, 0), b3, voffB); PG8_STAGE(PG8_SB(1, 1), b3 + hstepB, voffB); PG8_STAGE(PG8_SA(1, 0), a3, voffA);
;             PG8_WAIT_V(8); PG8_WAIT_L(0); PG8_BAR; PG8_MMA(1, 0, At, B0); PG8_MMA(1, 1, At, B1); PG8_BAR; PG8_SCHED;
;     ...
;         if constexpr (ALIGN_EPI) { if (wr == 0) PG8_BAR; }
	v_mfma_f32_16x16x32_bf16 v[92:95], v[76:79], v[84:87], v[92:95]
	v_mfma_f32_16x16x32_bf16 v[112:115], v[184:187], v[220:223], v[80:83]
	s_setprio 0
	s_add_i32 s70, s95, s74
	v_lshl_add_u64 v[84:85], v[228:229], 0, s[18:19]
	s_mov_b32 m0, s70
	s_nop 0
	ds_read_b128 v[80:83], v198 offset:49152
	ds_read_b128 v[200:203], v198 offset:50176
	ds_read_b128 v[204:207], v198 offset:51200
	ds_read_b128 v[208:211], v198 offset:52224
	ds_read_b128 v[212:215], v198 offset:53248
	ds_read_b128 v[216:219], v198 offset:54272
	ds_read_b128 v[220:223], v198 offset:55296
	ds_read_b128 v[224:227], v198 offset:56320
	global_load_lds_dwordx4 v[84:85], off
	s_add_i32 m0, s70, 0x2000
	s_add_u32 s68, s68, 0x100080
	v_lshl_add_u64 v[84:85], v[230:231], 0, s[18:19]
	s_addc_u32 s69, s69, 0
	s_add_i32 s70, s96, s74
	global_load_lds_dwordx4 v[84:85], off
	v_lshl_add_u64 v[84:85], s[68:69], 0, v[162:163]
	s_mov_b32 m0, s70
	s_nop 0
	global_load_lds_dwordx4 v[84:85], off
	v_lshl_add_u64 v[84:85], s[68:69], 0, v[166:167]
	s_add_i32 m0, s70, 0x2000
	s_nop 0
	global_load_lds_dwordx4 v[84:85], off
	v_lshl_add_u64 v[84:85], v[232:233], 0, s[18:19]
	s_mov_b32 m0, s82
	s_nop 0
	global_load_lds_dwordx4 v[84:85], off
	v_lshl_add_u64 v[84:85], v[234:235], 0, s[18:19]
	s_mov_b32 m0, s83
	s_nop 0
	global_load_lds_dwordx4 v[84:85], off
	s_waitcnt vmcnt(8)
	s_waitcnt lgkmcnt(0)
	s_barrier
	s_setprio 1
	s_waitcnt lgkmcnt(0)
	v_mfma_f32_16x16x32_bf16 v[84:87], v[52:55], v[80:83], v[108:111]
	v_mfma_f32_16x16x32_bf16 v[108:111], v[56:59], v[200:203], v[84:87]
	v_mfma_f32_16x16x32_bf16 v[84:87], v[60:63], v[80:83], v[96:99]
	v_mfma_f32_16x16x32_bf16 v[64:67], v[52:55], v[204:207], v[64:67]
	v_mfma_f32_16x16x32_bf16 v[36:39], v[60:63], v[204:207], v[36:39]
	v_mfma_f32_16x16x32_bf16 v[28:31], v[52:55], v[212:215], v[28:31]
	v_mfma_f32_16x16x32_bf16 v[20:23], v[60:63], v[212:215], v[20:23]
	v_mfma_f32_16x16x32_bf16 v[12:15], v[52:55], v[220:223], v[12:15]
	v_mfma_f32_16x16x32_bf16 v[4:7], v[60:63], v[220:223], v[4:7]
	v_mfma_f32_16x16x32_bf16 v[96:99], v[68:71], v[200:203], v[84:87]
	v_mfma_f32_16x16x32_bf16 v[64:67], v[56:59], v[208:211], v[64:67]
	v_mfma_f32_16x16x32_bf16 v[36:39], v[68:71], v[208:211], v[36:39]
	v_mfma_f32_16x16x32_bf16 v[28:31], v[56:59], v[216:219], v[28:31]
	v_mfma_f32_16x16x32_bf16 v[20:23], v[68:71], v[216:219], v[20:23]
	v_mfma_f32_16x16x32_bf16 v[12:15], v[56:59], v[224:227], v[12:15]
	v_mfma_f32_16x16x32_bf16 v[4:7], v[68:71], v[224:227], v[4:7]
	s_setprio 0
	s_setprio 1
	v_mfma_f32_16x16x32_bf16 v[44:47], v[72:75], v[80:83], v[44:47]
	v_mfma_f32_16x16x32_bf16 v[84:87], v[76:79], v[200:203], v[44:47]
	v_mfma_f32_16x16x32_bf16 v[44:47], v[180:183], v[80:83], v[48:51]
	v_mfma_f32_16x16x32_bf16 v[40:43], v[72:75], v[204:207], v[40:43]
	v_mfma_f32_16x16x32_bf16 v[32:35], v[180:183], v[204:207], v[32:35]
	v_mfma_f32_16x16x32_bf16 v[24:27], v[72:75], v[212:215], v[24:27]
	v_mfma_f32_16x16x32_bf16 v[16:19], v[180:183], v[212:215], v[16:19]
	v_mfma_f32_16x16x32_bf16 v[8:11], v[72:75], v[220:223], v[8:11]
	v_mfma_f32_16x16x32_bf16 v[0:3], v[180:183], v[220:223], v[0:3]
	v_mfma_f32_16x16x32_bf16 v[80:83], v[184:187], v[200:203], v[44:47]
	v_mfma_f32_16x16x32_bf16 v[40:43], v[76:79], v[208:211], v[40:43]
	v_mfma_f32_16x16x32_bf16 v[32:35], v[184:187], v[208:211], v[32:35]
	v_mfma_f32_16x16x32_bf16 v[24:27], v[76:79], v[216:219], v[24:27]
	v_mfma_f32_16x16x32_bf16 v[16:19], v[184:187], v[216:219], v[16:19]
	s_setprio 2
	s_barrier
	v_mfma_f32_16x16x32_bf16 v[8:11], v[76:79], v[224:227], v[8:11]
	v_mfma_f32_16x16x32_bf16 v[0:3], v[184:187], v[224:227], v[0:3]
	s_setprio 0
	s_add_i32 s94, s94, 2
	s_add_u32 s66, s66, 0x100
	s_addc_u32 s67, s67, 0
	s_add_u32 s92, s92, 0x100
	s_addc_u32 s93, s93, 0
	s_cmp_gt_u32 s94, 61
	s_cbranch_scc0 .LBB0_1187
	s_and_b64 vcc, exec, s[20:21]
	s_cbranch_vccz .LBB0_1190
	s_barrier

; #define PG8_STAGE(bufoff, gbase, voff) do { _Pragma("unroll") for (int _i = 0; _i < 2; ++_i) \
;         __builtin_amdgcn_global_load_lds((const unsigned*)((const char*)(gbase) + (voff)[_i]), (PG8_LAS unsigned*)(lds + (bufoff) + ldsw + _i * 8192), 16, 0, 0); } while (0)
; #define PG8_LDA(dst, b, h) do { _Pragma("unroll") for (int m = 0; m < 4; ++m) _Pragma("unroll") for (int k = 0; k < 2; ++k) dst[m][k] = *(const PG8_LAS bf16x8*)(lds + PG8_SA(b, h) + aoff + m * 2048 + k * 1024); } while (0)
; #define PG8_LDB(dst, b, h) do { _Pragma("unroll") for (int n = 0; n < 2; ++n) _Pragma("unroll") for (int k = 0; k < 2; ++k) dst[n][k] = *(const PG8_LAS bf16x8*)(lds + PG8_SB(b, h) + boff + n * 2048 + k * 1024); } while (0)
; #define PG8_MMA(ai, bj, At, Bt) do { __builtin_amdgcn_s_setprio(1); _Pragma("unroll") for (int m = 0; m < 4; ++m) _Pragma("unroll") for (int n = 0; n < 2; ++n) _Pragma("unroll") for (int k = 0; k < 2; ++k) \
;         acc[ai][bj][m][n] = __builtin_amdgcn_mfma_f32_16x16x32_bf16(Bt[n][k], At[m][k], acc[ai][bj][m][n], 0, 0, 0); __builtin_amdgcn_s_setprio(0); } while (0)
; #define PG8_WAIT_V(n) asm volatile("s_waitcnt vmcnt(" #n ")" ::: "memory")
; #define PG8_BAR __builtin_amdgcn_s_barrier()
; template <class Epi, class Sched, bool ALIGN_EPI = false, bool SP2 = false>
; __device__ __forceinline__ void gemm_phase(PG8_LAS unsigned char* lds, const Gemm g, const Sched& S, const Epi& E, const int wv  ) {
;     ...
;         for (int t = 0; t < nt; t += 2) {
;             const bool last = (t == nt - 2);
;             const char* a1 = cA + (size_t)(t + 1) * kstep;
;             const char* a2 = last ? nA : cA + (size_t)(t + 2) * kstep; const char* b2 = last ? nB : cB + (size_t)(t + 2) * kstep;
;             const char* a3 = a2 + kstep; const char* b3 = b2 + kstep;
;             if (last && has_next) S.a_ready(nxt);
;             if constexpr (SP2) {
;             PG8_LDB(B0, 0, 0); PG8_LDB(B1, 0, 1); PG8_SCHED; PG8_LDA(At, 0, 0); PG8_STAGE(PG8_SA(1, 1), a1 + hstepA, voffA);
;             PG8_WAIT_V(8); PG8_WAIT_L(0); PG8_BAR; PG8_MMA(0, 0, At, B0); PG8_MMA(0, 1, At, B1); PG8_BAR; PG8_SCHED;
;             PG8_LDA(At, 0, 1); PG8_STAGE(PG8_SB(0, 0), b2, voffB); PG8_STAGE(PG8_SB(0, 1), b2 + hstepB, voffB); PG8_STAGE(PG8_SA(0, 0), a2, voffA);
;             PG8_WAIT_V(8); PG8_WAIT_L(0); PG8_BAR; PG8_MMA(1, 0, At, B0); PG8_MMA(1, 1, At, B1); PG8_BAR; PG8_SCHED;
.LBB0_1544:
	ds_read_b128 v[146:149], v152
	ds_read_b128 v[156:159], v152 offset:1024
	ds_read_b128 v[160:163], v152 offset:2048
	ds_read_b128 v[164:167], v152 offset:3072
	ds_read_b128 v[168:171], v153
	ds_read_b128 v[172:175], v153 offset:1024
	ds_read_b128 v[176:179], v153 offset:2048
	ds_read_b128 v[180:183], v153 offset:3072
	s_add_u32 s54, s52, 0x100
	s_addc_u32 s55, s53, 0
	s_cmpk_eq_i32 s85, 0xa8
	s_cselect_b32 s59, s7, s55
	s_cselect_b32 s58, s6, s54
	s_cselect_b32 s57, s51, s84
	s_cselect_b32 s56, s50, s83
	v_lshl_add_u64 v[216:217], s[52:53], 0, v[138:139]
	s_add_i32 m0, s64, 0xc000
	ds_read_b128 v[184:187], v154
	ds_read_b128 v[188:191], v154 offset:1024
	ds_read_b128 v[192:195], v154 offset:2048
	ds_read_b128 v[196:199], v154 offset:3072
	ds_read_b128 v[200:203], v154 offset:4096
	ds_read_b128 v[204:207], v154 offset:5120
	ds_read_b128 v[208:211], v154 offset:6144
	ds_read_b128 v[212:215], v154 offset:7168
	global_load_lds_dwordx4 v[216:217], off
	v_lshl_add_u64 v[216:217], s[52:53], 0, v[140:141]
	s_add_i32 m0, s64, 0xe000
	s_nop 0
	global_load_lds_dwordx4 v[216:217], off
	s_waitcnt vmcnt(8)
	s_waitcnt lgkmcnt(0)
	s_barrier
	s_setprio 1
	s_waitcnt lgkmcnt(0)
	v_mfma_f32_16x16x32_bf16 v[76:79], v[146:149], v[184:187], v[76:79]
	v_mfma_f32_16x16x32_bf16 v[72:75], v[160:163], v[184:187], v[72:75]
	v_mfma_f32_16x16x32_bf16 v[68:71], v[146:149], v[192:195], v[68:71]
	v_mfma_f32_16x16x32_bf16 v[64:67], v[160:163], v[192:195], v[64:67]
	v_mfma_f32_16x16x32_bf16 v[56:59], v[146:149], v[200:203], v[56:59]
	v_mfma_f32_16x16x32_bf16 v[52:55], v[160:163], v[200:203], v[52:55]
	v_mfma_f32_16x16x32_bf16 v[44:47], v[146:149], v[208:211], v[44:47]
	v_mfma_f32_16x16x32_bf16 v[40:43], v[160:163], v[208:211], v[40:43]
	v_mfma_f32_16x16x32_bf16 v[76:79], v[156:159], v[188:191], v[76:79]
	v_mfma_f32_16x16x32_bf16 v[72:75], v[164:167], v[188:191], v[72:75]
	v_mfma_f32_16x16x32_bf16 v[68:71], v[156:159], v[196:199], v[68:71]
	v_mfma_f32_16x16x32_bf16 v[64:67], v[164:167], v[196:199], v[64:67]
	v_mfma_f32_16x16x32_bf16 v[56:59], v[156:159], v[204:207], v[56:59]
	v_mfma_f32_16x16x32_bf16 v[52:55], v[164:167], v[204:207], v[52:55]
	v_mfma_f32_16x16x32_bf16 v[44:47], v[156:159], v[212:215], v[44:47]
	v_mfma_f32_16x16x32_bf16 v[40:43], v[164:167], v[212:215], v[40:43]
	s_setprio 0
	s_setprio 1
	v_mfma_f32_16x16x32_bf16 v[124:127], v[168:171], v[184:187], v[124:127]
	v_mfma_f32_16x16x32_bf16 v[120:123], v[176:179], v[184:187], v[120:123]
	v_mfma_f32_16x16x32_bf16 v[116:119], v[168:171], v[192:195], v[116:119]
	v_mfma_f32_16x16x32_bf16 v[112:115], v[176:179], v[192:195], v[112:115]
	v_mfma_f32_16x16x32_bf16 v[108:111], v[168:171], v[200:203], v[108:111]
	v_mfma_f32_16x16x32_bf16 v[104:107], v[176:179], v[200:203], v[104:107]
	v_mfma_f32_16x16x32_bf16 v[100:103], v[168:171], v[208:211], v[100:103]
	v_mfma_f32_16x16x32_bf16 v[96:99], v[176:179], v[208:211], v[96:99]
	v_mfma_f32_16x16x32_bf16 v[124:127], v[172:175], v[188:191], v[124:127]
	v_mfma_f32_16x16x32_bf16 v[120:123], v[180:183], v[188:191], v[120:123]
	v_mfma_f32_16x16x32_bf16 v[116:119], v[172:175], v[196:199], v[116:119]
	v_mfma_f32_16x16x32_bf16 v[112:115], v[180:183], v[196:199], v[112:115]
	v_mfma_f32_16x16x32_bf16 v[108:111], v[172:175], v[204:207], v[108:111]
	v_mfma_f32_16x16x32_bf16 v[104:107], v[180:183], v[204:207], v[104:107]
	s_setprio 2
	s_barrier
	v_mfma_f32_16x16x32_bf16 v[100:103], v[172:175], v[212:215], v[100:103]
	v_mfma_f32_16x16x32_bf16 v[96:99], v[180:183], v[212:215], v[96:99]
	s_setprio 0
	s_add_i32 s52, s73, s63
	v_lshl_add_u64 v[216:217], s[56:57], 0, v[130:131]
	s_mov_b32 m0, s52
	ds_read_b128 v[184:187], v154 offset:16384
	ds_read_b128 v[188:191], v154 offset:17408
	ds_read_b128 v[192:195], v154 offset:18432
	ds_read_b128 v[196:199], v154 offset:19456
	ds_read_b128 v[200:203], v154 offset:20480
	ds_read_b128 v[204:207], v154 offset:21504
	ds_read_b128 v[208:211], v154 offset:22528
	ds_read_b128 v[212:215], v154 offset:23552
	global_load_lds_dwordx4 v[216:217], off
	s_add_i32 m0, s52, 0x2000
	s_add_u32 s52, s56, 0x2b0000
	v_lshl_add_u64 v[218:219], s[56:57], 0, v[134:135]
	s_addc_u32 s53, s57, 0
	s_add_i32 s86, s74, s63
	global_load_lds_dwordx4 v[218:219], off
	v_lshl_add_u64 v[220:221], s[52:53], 0, v[130:131]
	s_mov_b32 m0, s86
	v_lshl_add_u64 v[222:223], s[58:59], 0, v[132:133]
	global_load_lds_dwordx4 v[220:221], off
	v_lshl_add_u64 v[220:221], s[52:53], 0, v[134:135]
	s_add_i32 m0, s86, 0x2000
	s_nop 0
	global_load_lds_dwordx4 v[220:221], off
	v_lshl_add_u64 v[220:221], s[58:59], 0, v[128:129]
	s_mov_b32 m0, s64
	s_nop 0
	global_load_lds_dwordx4 v[220:221], off
	s_mov_b32 m0, s65
	s_nop 0
	global_load_lds_dwordx4 v[222:223], off
	s_waitcnt vmcnt(8)
	s_waitcnt lgkmcnt(0)
	s_barrier
; #define PG8_STAGE(bufoff, gbase, voff) do { _Pragma("unroll") for (int _i = 0; _i < 2; ++_i) \
;         __builtin_amdgcn_global_load_lds((const unsigned*)((const char*)(gbase) + (voff)[_i]), (PG8_LAS unsigned*)(lds + (bufoff) + ldsw + _i * 8192), 16, 0, 0); } while (0)
; #define PG8_LDA(dst, b, h) do { _Pragma("unroll") for (int m = 0; m < 4; ++m) _Pragma("unroll") for (int k = 0; k < 2; ++k) dst[m][k] = *(const PG8_LAS bf16x8*)(lds + PG8_SA(b, h) + aoff + m * 2048 + k * 1024); } while (0)
; #define PG8_LDB(dst, b, h) do { _Pragma("unroll") for (int n = 0; n < 2; ++n) _Pragma("unroll") for (int k = 0; k < 2; ++k) dst[n][k] = *(const PG8_LAS bf16x8*)(lds + PG8_SB(b, h) + boff + n * 2048 + k * 1024); } while (0)
; #define PG8_MMA(ai, bj, At, Bt) do { __builtin_amdgcn_s_setprio(1); _Pragma("unroll") for (int m = 0; m < 4; ++m) _Pragma("unroll") for (int n = 0; n < 2; ++n) _Pragma("unroll") for (int k = 0; k < 2; ++k) \
;         acc[ai][bj][m][n] = __builtin_amdgcn_mfma_f32_16x16x32_bf16(Bt[n][k], At[m][k], acc[ai][bj][m][n], 0, 0, 0); __builtin_amdgcn_s_setprio(0); } while (0)
; #define PG8_WAIT_V(n) asm volatile("s_waitcnt vmcnt(" #n ")" ::: "memory")
; #define PG8_WAIT_L(n) asm volatile("s_waitcnt lgkmcnt(" #n ")" ::: "memory")
; #define PG8_BAR __builtin_amdgcn_s_barrier()
; #define PG8_SCHED __builtin_amdgcn_sched_barrier(0)
; template <class Epi, class Sched, bool ALIGN_EPI = false, bool SP2 = false>
; __device__ __forceinline__ void gemm_phase(PG8_LAS unsigned char* lds, const Gemm g, const Sched& S, const Epi& E, const int wv  ) {
;     ...
;             PG8_WAIT_V(8); PG8_WAIT_L(0); PG8_BAR; PG8_MMA(1, 0, At, B0); PG8_MMA(1, 1, At, B1); PG8_BAR; PG8_SCHED;
;             PG8_LDB(B0, 1, 0); PG8_LDB(B1, 1, 1); PG8_SCHED; PG8_LDA(At, 1, 0); PG8_STAGE(PG8_SA(0, 1), a2 + hstepA, voffA);
;             PG8_WAIT_V(8); PG8_WAIT_L(0); PG8_BAR; PG8_MMA(0, 0, At, B0); PG8_MMA(0, 1, At, B1); PG8_BAR; PG8_SCHED;
	s_setprio 1
	s_waitcnt lgkmcnt(0)
	v_mfma_f32_16x16x32_bf16 v[28:31], v[146:149], v[184:187], v[28:31]
	v_mfma_f32_16x16x32_bf16 v[24:27], v[160:163], v[184:187], v[24:27]
	v_mfma_f32_16x16x32_bf16 v[20:23], v[146:149], v[192:195], v[20:23]
	v_mfma_f32_16x16x32_bf16 v[16:19], v[160:163], v[192:195], v[16:19]
	v_mfma_f32_16x16x32_bf16 v[12:15], v[146:149], v[200:203], v[12:15]
	v_mfma_f32_16x16x32_bf16 v[8:11], v[160:163], v[200:203], v[8:11]
	v_mfma_f32_16x16x32_bf16 v[4:7], v[146:149], v[208:211], v[4:7]
	v_mfma_f32_16x16x32_bf16 v[0:3], v[160:163], v[208:211], v[0:3]
	v_mfma_f32_16x16x32_bf16 v[28:31], v[156:159], v[188:191], v[28:31]
	v_mfma_f32_16x16x32_bf16 v[24:27], v[164:167], v[188:191], v[24:27]
	v_mfma_f32_16x16x32_bf16 v[20:23], v[156:159], v[196:199], v[20:23]
	v_mfma_f32_16x16x32_bf16 v[16:19], v[164:167], v[196:199], v[16:19]
	v_mfma_f32_16x16x32_bf16 v[12:15], v[156:159], v[204:207], v[12:15]
	v_mfma_f32_16x16x32_bf16 v[8:11], v[164:167], v[204:207], v[8:11]
	v_mfma_f32_16x16x32_bf16 v[4:7], v[156:159], v[212:215], v[4:7]
	v_mfma_f32_16x16x32_bf16 v[0:3], v[164:167], v[212:215], v[0:3]
	s_setprio 0
	s_setprio 1
	v_mfma_f32_16x16x32_bf16 v[92:95], v[168:171], v[184:187], v[92:95]
	v_mfma_f32_16x16x32_bf16 v[88:91], v[176:179], v[184:187], v[88:91]
	v_mfma_f32_16x16x32_bf16 v[84:87], v[168:171], v[192:195], v[84:87]
	v_mfma_f32_16x16x32_bf16 v[80:83], v[176:179], v[192:195], v[80:83]
	v_mfma_f32_16x16x32_bf16 v[60:63], v[168:171], v[200:203], v[60:63]
	v_mfma_f32_16x16x32_bf16 v[48:51], v[176:179], v[200:203], v[48:51]
	v_mfma_f32_16x16x32_bf16 v[36:39], v[168:171], v[208:211], v[36:39]
	v_mfma_f32_16x16x32_bf16 v[32:35], v[176:179], v[208:211], v[32:35]
	v_mfma_f32_16x16x32_bf16 v[92:95], v[172:175], v[188:191], v[92:95]
	v_mfma_f32_16x16x32_bf16 v[88:91], v[180:183], v[188:191], v[88:91]
	v_mfma_f32_16x16x32_bf16 v[84:87], v[172:175], v[196:199], v[84:87]
	v_mfma_f32_16x16x32_bf16 v[80:83], v[180:183], v[196:199], v[80:83]
	v_mfma_f32_16x16x32_bf16 v[60:63], v[172:175], v[204:207], v[60:63]
	v_mfma_f32_16x16x32_bf16 v[48:51], v[180:183], v[204:207], v[48:51]
	s_setprio 2
	s_barrier
	v_mfma_f32_16x16x32_bf16 v[36:39], v[172:175], v[212:215], v[36:39]
	v_mfma_f32_16x16x32_bf16 v[32:35], v[180:183], v[212:215], v[32:35]
	s_setprio 0
	s_add_i32 s86, 0, 0x18000
	v_add_u32_e32 v155, s86, v150
	s_add_i32 s87, 0, 0x1c000
	ds_read_b128 v[146:149], v155
	ds_read_b128 v[156:159], v155 offset:1024
	ds_read_b128 v[160:163], v155 offset:2048
	ds_read_b128 v[164:167], v155 offset:3072
	v_add_u32_e32 v155, s87, v150
	ds_read_b128 v[168:171], v155
	ds_read_b128 v[172:175], v155 offset:1024
	ds_read_b128 v[176:179], v155 offset:2048
	ds_read_b128 v[180:183], v155 offset:3072
	s_add_u32 s52, s58, 0x2b0000
	s_addc_u32 s53, s59, 0
	s_mov_b32 m0, s66
	v_lshl_add_u64 v[224:225], s[52:53], 0, v[128:129]
	ds_read_b128 v[184:187], v154 offset:32768
	ds_read_b128 v[188:191], v154 offset:33792
	ds_read_b128 v[192:195], v154 offset:34816
	ds_read_b128 v[196:199], v154 offset:35840
	ds_read_b128 v[200:203], v154 offset:36864
	ds_read_b128 v[204:207], v154 offset:37888
	ds_read_b128 v[208:211], v154 offset:38912
	ds_read_b128 v[212:215], v154 offset:39936
	global_load_lds_dwordx4 v[224:225], off
	v_lshl_add_u64 v[224:225], s[52:53], 0, v[132:133]
	s_mov_b32 m0, s67
	s_nop 0
	global_load_lds_dwordx4 v[224:225], off
	s_waitcnt vmcnt(8)
	s_waitcnt lgkmcnt(0)
	s_barrier
	s_setprio 1
	s_waitcnt lgkmcnt(0)
	v_mfma_f32_16x16x32_bf16 v[76:79], v[146:149], v[184:187], v[76:79]
	v_mfma_f32_16x16x32_bf16 v[72:75], v[160:163], v[184:187], v[72:75]
	v_mfma_f32_16x16x32_bf16 v[68:71], v[146:149], v[192:195], v[68:71]
	v_mfma_f32_16x16x32_bf16 v[64:67], v[160:163], v[192:195], v[64:67]
	v_mfma_f32_16x16x32_bf16 v[56:59], v[146:149], v[200:203], v[56:59]
	v_mfma_f32_16x16x32_bf16 v[52:55], v[160:163], v[200:203], v[52:55]
	v_mfma_f32_16x16x32_bf16 v[44:47], v[146:149], v[208:211], v[44:47]
	v_mfma_f32_16x16x32_bf16 v[40:43], v[160:163], v[208:211], v[40:43]
	v_mfma_f32_16x16x32_bf16 v[76:79], v[156:159], v[188:191], v[76:79]
	v_mfma_f32_16x16x32_bf16 v[72:75], v[164:167], v[188:191], v[72:75]
	v_mfma_f32_16x16x32_bf16 v[68:71], v[156:159], v[196:199], v[68:71]
	v_mfma_f32_16x16x32_bf16 v[64:67], v[164:167], v[196:199], v[64:67]
	v_mfma_f32_16x16x32_bf16 v[56:59], v[156:159], v[204:207], v[56:59]
	v_mfma_f32_16x16x32_bf16 v[52:55], v[164:167], v[204:207], v[52:55]
	v_mfma_f32_16x16x32_bf16 v[44:47], v[156:159], v[212:215], v[44:47]
	v_mfma_f32_16x16x32_bf16 v[40:43], v[164:167], v[212:215], v[40:43]
	s_setprio 0
	s_setprio 1
	v_mfma_f32_16x16x32_bf16 v[124:127], v[168:171], v[184:187], v[124:127]
	v_mfma_f32_16x16x32_bf16 v[120:123], v[176:179], v[184:187], v[120:123]
	v_mfma_f32_16x16x32_bf16 v[116:119], v[168:171], v[192:195], v[116:119]
	v_mfma_f32_16x16x32_bf16 v[112:115], v[176:179], v[192:195], v[112:115]
	v_mfma_f32_16x16x32_bf16 v[108:111], v[168:171], v[200:203], v[108:111]
	v_mfma_f32_16x16x32_bf16 v[104:107], v[176:179], v[200:203], v[104:107]
	v_mfma_f32_16x16x32_bf16 v[100:103], v[168:171], v[208:211], v[100:103]
	v_mfma_f32_16x16x32_bf16 v[96:99], v[176:179], v[208:211], v[96:99]
	v_mfma_f32_16x16x32_bf16 v[124:127], v[172:175], v[188:191], v[124:127]
	v_mfma_f32_16x16x32_bf16 v[120:123], v[180:183], v[188:191], v[120:123]
	v_mfma_f32_16x16x32_bf16 v[116:119], v[172:175], v[196:199], v[116:119]
	v_mfma_f32_16x16x32_bf16 v[112:115], v[180:183], v[196:199], v[112:115]
	v_mfma_f32_16x16x32_bf16 v[108:111], v[172:175], v[204:207], v[108:111]
	v_mfma_f32_16x16x32_bf16 v[104:107], v[180:183], v[204:207], v[104:107]
	s_setprio 2
	s_barrier
; #define PG8_STAGE(bufoff, gbase, voff) do { _Pragma("unroll") for (int _i = 0; _i < 2; ++_i) \
;         __builtin_amdgcn_global_load_lds((const unsigned*)((const char*)(gbase) + (voff)[_i]), (PG8_LAS unsigned*)(lds + (bufoff) + ldsw + _i * 8192), 16, 0, 0); } while (0)
; #define PG8_LDA(dst, b, h) do { _Pragma("unroll") for (int m = 0; m < 4; ++m) _Pragma("unroll") for (int k = 0; k < 2; ++k) dst[m][k] = *(const PG8_LAS bf16x8*)(lds + PG8_SA(b, h) + aoff + m * 2048 + k * 1024); } while (0)
; #define PG8_MMA(ai, bj, At, Bt) do { __builtin_amdgcn_s_setprio(1); _Pragma("unroll") for (int m = 0; m < 4; ++m) _Pragma("unroll") for (int n = 0; n < 2; ++n) _Pragma("unroll") for (int k = 0; k < 2; ++k) \
;         acc[ai][bj][m][n] = __builtin_amdgcn_mfma_f32_16x16x32_bf16(Bt[n][k], At[m][k], acc[ai][bj][m][n], 0, 0, 0); __builtin_amdgcn_s_setprio(0); } while (0)
; #define PG8_WAIT_V(n) asm volatile("s_waitcnt vmcnt(" #n ")" ::: "memory")
; #define PG8_WAIT_L(n) asm volatile("s_waitcnt lgkmcnt(" #n ")" ::: "memory")
; #define PG8_BAR __builtin_amdgcn_s_barrier()
; #define PG8_SCHED __builtin_amdgcn_sched_barrier(0)
; template <class Epi, class Sched, bool ALIGN_EPI = false, bool SP2 = false>
; __device__ __forceinline__ void gemm_phase(PG8_LAS unsigned char* lds, const Gemm g, const Sched& S, const Epi& E, const int wv  ) {
;     ...
;             PG8_WAIT_V(8); PG8_WAIT_L(0); PG8_BAR; PG8_MMA(0, 0, At, B0); PG8_MMA(0, 1, At, B1); PG8_BAR; PG8_SCHED;
;             PG8_LDA(At, 1, 1); PG8_STAGE(PG8_SB(1, 0), b3, voffB); PG8_STAGE(PG8_SB(1, 1), b3 + hstepB, voffB); PG8_STAGE(PG8_SA(1, 0), a3, voffA);
;             PG8_WAIT_V(8); PG8_WAIT_L(0); PG8_BAR; PG8_MMA(1, 0, At, B0); PG8_MMA(1, 1, At, B1); PG8_BAR; PG8_SCHED;
;     ...
;         if constexpr (ALIGN_EPI) { if (wr == 0) PG8_BAR; }
	v_mfma_f32_16x16x32_bf16 v[100:103], v[172:175], v[212:215], v[100:103]
	v_mfma_f32_16x16x32_bf16 v[96:99], v[180:183], v[212:215], v[96:99]
	s_setprio 0
	s_add_i32 s52, s86, s63
	v_lshl_add_u64 v[216:217], v[216:217], 0, s[12:13]
	s_mov_b32 m0, s52
	ds_read_b128 v[184:187], v154 offset:49152
	ds_read_b128 v[188:191], v154 offset:50176
	ds_read_b128 v[192:195], v154 offset:51200
	ds_read_b128 v[196:199], v154 offset:52224
	ds_read_b128 v[200:203], v154 offset:53248
	ds_read_b128 v[204:207], v154 offset:54272
	ds_read_b128 v[208:211], v154 offset:55296
	ds_read_b128 v[212:215], v154 offset:56320
	global_load_lds_dwordx4 v[216:217], off
	s_add_i32 m0, s52, 0x2000
	s_add_u32 s52, s56, 0x2b0080
	v_lshl_add_u64 v[216:217], v[218:219], 0, s[12:13]
	s_addc_u32 s53, s57, 0
	s_add_i32 s56, s87, s63
	global_load_lds_dwordx4 v[216:217], off
	v_lshl_add_u64 v[216:217], s[52:53], 0, v[130:131]
	s_mov_b32 m0, s56
	s_nop 0
	global_load_lds_dwordx4 v[216:217], off
	v_lshl_add_u64 v[216:217], s[52:53], 0, v[134:135]
	s_add_i32 m0, s56, 0x2000
	s_nop 0
	global_load_lds_dwordx4 v[216:217], off
	v_lshl_add_u64 v[216:217], v[220:221], 0, s[12:13]
	s_mov_b32 m0, s70
	s_nop 0
	global_load_lds_dwordx4 v[216:217], off
	v_lshl_add_u64 v[216:217], v[222:223], 0, s[12:13]
	s_mov_b32 m0, s71
	s_nop 0
	global_load_lds_dwordx4 v[216:217], off
	s_waitcnt vmcnt(8)
	s_waitcnt lgkmcnt(0)
	s_barrier
	s_setprio 1
	s_waitcnt lgkmcnt(0)
	v_mfma_f32_16x16x32_bf16 v[28:31], v[146:149], v[184:187], v[28:31]
	v_mfma_f32_16x16x32_bf16 v[24:27], v[160:163], v[184:187], v[24:27]
	v_mfma_f32_16x16x32_bf16 v[20:23], v[146:149], v[192:195], v[20:23]
	v_mfma_f32_16x16x32_bf16 v[16:19], v[160:163], v[192:195], v[16:19]
	v_mfma_f32_16x16x32_bf16 v[12:15], v[146:149], v[200:203], v[12:15]
	v_mfma_f32_16x16x32_bf16 v[8:11], v[160:163], v[200:203], v[8:11]
	v_mfma_f32_16x16x32_bf16 v[4:7], v[146:149], v[208:211], v[4:7]
	v_mfma_f32_16x16x32_bf16 v[0:3], v[160:163], v[208:211], v[0:3]
	v_mfma_f32_16x16x32_bf16 v[28:31], v[156:159], v[188:191], v[28:31]
	v_mfma_f32_16x16x32_bf16 v[24:27], v[164:167], v[188:191], v[24:27]
	v_mfma_f32_16x16x32_bf16 v[20:23], v[156:159], v[196:199], v[20:23]
	v_mfma_f32_16x16x32_bf16 v[16:19], v[164:167], v[196:199], v[16:19]
	v_mfma_f32_16x16x32_bf16 v[12:15], v[156:159], v[204:207], v[12:15]
	v_mfma_f32_16x16x32_bf16 v[8:11], v[164:167], v[204:207], v[8:11]
	v_mfma_f32_16x16x32_bf16 v[4:7], v[156:159], v[212:215], v[4:7]
	v_mfma_f32_16x16x32_bf16 v[0:3], v[164:167], v[212:215], v[0:3]
	s_setprio 0
	s_setprio 1
	v_mfma_f32_16x16x32_bf16 v[92:95], v[168:171], v[184:187], v[92:95]
	v_mfma_f32_16x16x32_bf16 v[88:91], v[176:179], v[184:187], v[88:91]
	v_mfma_f32_16x16x32_bf16 v[84:87], v[168:171], v[192:195], v[84:87]
	v_mfma_f32_16x16x32_bf16 v[80:83], v[176:179], v[192:195], v[80:83]
	v_mfma_f32_16x16x32_bf16 v[60:63], v[168:171], v[200:203], v[60:63]
	v_mfma_f32_16x16x32_bf16 v[48:51], v[176:179], v[200:203], v[48:51]
	v_mfma_f32_16x16x32_bf16 v[36:39], v[168:171], v[208:211], v[36:39]
	v_mfma_f32_16x16x32_bf16 v[32:35], v[176:179], v[208:211], v[32:35]
	v_mfma_f32_16x16x32_bf16 v[92:95], v[172:175], v[188:191], v[92:95]
	v_mfma_f32_16x16x32_bf16 v[88:91], v[180:183], v[188:191], v[88:91]
	v_mfma_f32_16x16x32_bf16 v[84:87], v[172:175], v[196:199], v[84:87]
	v_mfma_f32_16x16x32_bf16 v[80:83], v[180:183], v[196:199], v[80:83]
	v_mfma_f32_16x16x32_bf16 v[60:63], v[172:175], v[204:207], v[60:63]
	v_mfma_f32_16x16x32_bf16 v[48:51], v[180:183], v[204:207], v[48:51]
	s_setprio 2
	s_barrier
	v_mfma_f32_16x16x32_bf16 v[36:39], v[172:175], v[212:215], v[36:39]
	v_mfma_f32_16x16x32_bf16 v[32:35], v[180:183], v[212:215], v[32:35]
	s_setprio 0
	s_add_i32 s85, s85, 2
	s_add_u32 s83, s83, 0x100
	s_addc_u32 s84, s84, 0
	s_cmpk_gt_u32 s85, 0xa9
	s_mov_b64 s[52:53], s[54:55]
	s_cbranch_scc0 .LBB0_1544
	s_and_b64 vcc, exec, s[14:15]
	s_cbranch_vccz .LBB0_1547
	s_barrier

; #define PG8_STAGE(bufoff, gbase, voff) do { _Pragma("unroll") for (int _i = 0; _i < 2; ++_i) \
;         __builtin_amdgcn_global_load_lds((const unsigned*)((const char*)(gbase) + (voff)[_i]), (PG8_LAS unsigned*)(lds + (bufoff) + ldsw + _i * 8192), 16, 0, 0); } while (0)
; #define PG8_LDA(dst, b, h) do { _Pragma("unroll") for (int m = 0; m < 4; ++m) _Pragma("unroll") for (int k = 0; k < 2; ++k) dst[m][k] = *(const PG8_LAS bf16x8*)(lds + PG8_SA(b, h) + aoff + m * 2048 + k * 1024); } while (0)
; #define PG8_LDB(dst, b, h) do { _Pragma("unroll") for (int n = 0; n < 2; ++n) _Pragma("unroll") for (int k = 0; k < 2; ++k) dst[n][k] = *(const PG8_LAS bf16x8*)(lds + PG8_SB(b, h) + boff + n * 2048 + k * 1024); } while (0)
; #define PG8_MMA(ai, bj, At, Bt) do { __builtin_amdgcn_s_setprio(1); _Pragma("unroll") for (int m = 0; m < 4; ++m) _Pragma("unroll") for (int n = 0; n < 2; ++n) _Pragma("unroll") for (int k = 0; k < 2; ++k) \
;         acc[ai][bj][m][n] = __builtin_amdgcn_mfma_f32_16x16x32_bf16(Bt[n][k], At[m][k], acc[ai][bj][m][n], 0, 0, 0); __builtin_amdgcn_s_setprio(0); } while (0)
; #define PG8_WAIT_V(n) asm volatile("s_waitcnt vmcnt(" #n ")" ::: "memory")
; #define PG8_BAR __builtin_amdgcn_s_barrier()
; template <class Epi, class Sched, bool ALIGN_EPI = false, bool SP2 = false>
; __device__ __forceinline__ void gemm_phase(PG8_LAS unsigned char* lds, const Gemm g, const Sched& S, const Epi& E, const int wv  ) {
;     ...
;         for (int t = 0; t < nt; t += 2) {
;             const bool last = (t == nt - 2);
;             const char* a1 = cA + (size_t)(t + 1) * kstep;
;             const char* a2 = last ? nA : cA + (size_t)(t + 2) * kstep; const char* b2 = last ? nB : cB + (size_t)(t + 2) * kstep;
;             const char* a3 = a2 + kstep; const char* b3 = b2 + kstep;
;             if (last && has_next) S.a_ready(nxt);
;             if constexpr (SP2) {
;             PG8_LDB(B0, 0, 0); PG8_LDB(B1, 0, 1); PG8_SCHED; PG8_LDA(At, 0, 0); PG8_STAGE(PG8_SA(1, 1), a1 + hstepA, voffA);
;             PG8_WAIT_V(8); PG8_WAIT_L(0); PG8_BAR; PG8_MMA(0, 0, At, B0); PG8_MMA(0, 1, At, B1); PG8_BAR; PG8_SCHED;
;             PG8_LDA(At, 0, 1); PG8_STAGE(PG8_SB(0, 0), b2, voffB); PG8_STAGE(PG8_SB(0, 1), b2 + hstepB, voffB); PG8_STAGE(PG8_SA(0, 0), a2, voffA);
;             PG8_WAIT_V(8); PG8_WAIT_L(0); PG8_BAR; PG8_MMA(1, 0, At, B0); PG8_MMA(1, 1, At, B1); PG8_BAR; PG8_SCHED;
.LBB0_1717:
	ds_read_b128 v[146:149], v152
	ds_read_b128 v[156:159], v152 offset:1024
	ds_read_b128 v[160:163], v152 offset:2048
	ds_read_b128 v[164:167], v152 offset:3072
	ds_read_b128 v[168:171], v153
	ds_read_b128 v[172:175], v153 offset:1024
	ds_read_b128 v[176:179], v153 offset:2048
	ds_read_b128 v[180:183], v153 offset:3072
	s_add_u32 s60, s58, 0xfff00080
	s_addc_u32 s61, s59, -1
	s_cmp_eq_u32 s87, 60
	s_cselect_b32 s63, s51, s61
	s_cselect_b32 s62, s83, s60
	s_cselect_b32 s61, s49, s86
	s_cselect_b32 s60, s84, s85
	v_lshl_add_u64 v[216:217], s[58:59], 0, v[138:139]
	s_add_i32 m0, s70, 0xc000
	ds_read_b128 v[184:187], v154
	ds_read_b128 v[188:191], v154 offset:1024
	ds_read_b128 v[192:195], v154 offset:2048
	ds_read_b128 v[196:199], v154 offset:3072
	ds_read_b128 v[200:203], v154 offset:4096
	ds_read_b128 v[204:207], v154 offset:5120
	ds_read_b128 v[208:211], v154 offset:6144
	ds_read_b128 v[212:215], v154 offset:7168
	global_load_lds_dwordx4 v[216:217], off
	v_lshl_add_u64 v[216:217], s[58:59], 0, v[140:141]
	s_add_i32 m0, s70, 0xe000
	s_nop 0
	global_load_lds_dwordx4 v[216:217], off
	s_waitcnt vmcnt(8)
	s_waitcnt lgkmcnt(0)
	s_barrier
	s_setprio 1
	s_waitcnt lgkmcnt(0)
	v_mfma_f32_16x16x32_bf16 v[76:79], v[146:149], v[184:187], v[76:79]
	v_mfma_f32_16x16x32_bf16 v[72:75], v[160:163], v[184:187], v[72:75]
	v_mfma_f32_16x16x32_bf16 v[68:71], v[146:149], v[192:195], v[68:71]
	v_mfma_f32_16x16x32_bf16 v[64:67], v[160:163], v[192:195], v[64:67]
	v_mfma_f32_16x16x32_bf16 v[56:59], v[146:149], v[200:203], v[56:59]
	v_mfma_f32_16x16x32_bf16 v[52:55], v[160:163], v[200:203], v[52:55]
	v_mfma_f32_16x16x32_bf16 v[44:47], v[146:149], v[208:211], v[44:47]
	v_mfma_f32_16x16x32_bf16 v[40:43], v[160:163], v[208:211], v[40:43]
	v_mfma_f32_16x16x32_bf16 v[76:79], v[156:159], v[188:191], v[76:79]
	v_mfma_f32_16x16x32_bf16 v[72:75], v[164:167], v[188:191], v[72:75]
	v_mfma_f32_16x16x32_bf16 v[68:71], v[156:159], v[196:199], v[68:71]
	v_mfma_f32_16x16x32_bf16 v[64:67], v[164:167], v[196:199], v[64:67]
	v_mfma_f32_16x16x32_bf16 v[56:59], v[156:159], v[204:207], v[56:59]
	v_mfma_f32_16x16x32_bf16 v[52:55], v[164:167], v[204:207], v[52:55]
	v_mfma_f32_16x16x32_bf16 v[44:47], v[156:159], v[212:215], v[44:47]
	v_mfma_f32_16x16x32_bf16 v[40:43], v[164:167], v[212:215], v[40:43]
	s_setprio 0
	s_setprio 1
	v_mfma_f32_16x16x32_bf16 v[124:127], v[168:171], v[184:187], v[124:127]
	v_mfma_f32_16x16x32_bf16 v[120:123], v[176:179], v[184:187], v[120:123]
	v_mfma_f32_16x16x32_bf16 v[116:119], v[168:171], v[192:195], v[116:119]
	v_mfma_f32_16x16x32_bf16 v[112:115], v[176:179], v[192:195], v[112:115]
	v_mfma_f32_16x16x32_bf16 v[108:111], v[168:171], v[200:203], v[108:111]
	v_mfma_f32_16x16x32_bf16 v[104:107], v[176:179], v[200:203], v[104:107]
	v_mfma_f32_16x16x32_bf16 v[100:103], v[168:171], v[208:211], v[100:103]
	v_mfma_f32_16x16x32_bf16 v[96:99], v[176:179], v[208:211], v[96:99]
	v_mfma_f32_16x16x32_bf16 v[124:127], v[172:175], v[188:191], v[124:127]
	v_mfma_f32_16x16x32_bf16 v[120:123], v[180:183], v[188:191], v[120:123]
	v_mfma_f32_16x16x32_bf16 v[116:119], v[172:175], v[196:199], v[116:119]
	v_mfma_f32_16x16x32_bf16 v[112:115], v[180:183], v[196:199], v[112:115]
	v_mfma_f32_16x16x32_bf16 v[108:111], v[172:175], v[204:207], v[108:111]
	v_mfma_f32_16x16x32_bf16 v[104:107], v[180:183], v[204:207], v[104:107]
	s_setprio 2
	s_barrier
	v_mfma_f32_16x16x32_bf16 v[100:103], v[172:175], v[212:215], v[100:103]
	v_mfma_f32_16x16x32_bf16 v[96:99], v[180:183], v[212:215], v[96:99]
	s_setprio 0
	s_add_i32 s90, s77, s69
	v_lshl_add_u64 v[216:217], s[60:61], 0, v[130:131]
	s_mov_b32 m0, s90
	ds_read_b128 v[184:187], v154 offset:16384
	ds_read_b128 v[188:191], v154 offset:17408
	ds_read_b128 v[192:195], v154 offset:18432
	ds_read_b128 v[196:199], v154 offset:19456
	ds_read_b128 v[200:203], v154 offset:20480
	ds_read_b128 v[204:207], v154 offset:21504
	ds_read_b128 v[208:211], v154 offset:22528
	ds_read_b128 v[212:215], v154 offset:23552
	global_load_lds_dwordx4 v[216:217], off
	s_add_i32 m0, s90, 0x2000
	s_add_u32 s90, s60, 0x100000
	v_lshl_add_u64 v[218:219], s[60:61], 0, v[134:135]
	s_addc_u32 s91, s61, 0
	s_add_i32 s92, s78, s69
	global_load_lds_dwordx4 v[218:219], off
	v_lshl_add_u64 v[220:221], s[90:91], 0, v[130:131]
	s_mov_b32 m0, s92
	v_lshl_add_u64 v[222:223], s[62:63], 0, v[132:133]
	global_load_lds_dwordx4 v[220:221], off
	v_lshl_add_u64 v[220:221], s[90:91], 0, v[134:135]
	s_add_i32 m0, s92, 0x2000
	s_nop 0
	global_load_lds_dwordx4 v[220:221], off
	v_lshl_add_u64 v[220:221], s[62:63], 0, v[128:129]
	s_mov_b32 m0, s70
	s_nop 0
	global_load_lds_dwordx4 v[220:221], off
	s_mov_b32 m0, s71
	s_nop 0
	global_load_lds_dwordx4 v[222:223], off
	s_waitcnt vmcnt(8)
	s_waitcnt lgkmcnt(0)
	s_barrier
; #define PG8_STAGE(bufoff, gbase, voff) do { _Pragma("unroll") for (int _i = 0; _i < 2; ++_i) \
;         __builtin_amdgcn_global_load_lds((const unsigned*)((const char*)(gbase) + (voff)[_i]), (PG8_LAS unsigned*)(lds + (bufoff) + ldsw + _i * 8192), 16, 0, 0); } while (0)
; #define PG8_LDA(dst, b, h) do { _Pragma("unroll") for (int m = 0; m < 4; ++m) _Pragma("unroll") for (int k = 0; k < 2; ++k) dst[m][k] = *(const PG8_LAS bf16x8*)(lds + PG8_SA(b, h) + aoff + m * 2048 + k * 1024); } while (0)
; #define PG8_LDB(dst, b, h) do { _Pragma("unroll") for (int n = 0; n < 2; ++n) _Pragma("unroll") for (int k = 0; k < 2; ++k) dst[n][k] = *(const PG8_LAS bf16x8*)(lds + PG8_SB(b, h) + boff + n * 2048 + k * 1024); } while (0)
; #define PG8_MMA(ai, bj, At, Bt) do { __builtin_amdgcn_s_setprio(1); _Pragma("unroll") for (int m = 0; m < 4; ++m) _Pragma("unroll") for (int n = 0; n < 2; ++n) _Pragma("unroll") for (int k = 0; k < 2; ++k) \
;         acc[ai][bj][m][n] = __builtin_amdgcn_mfma_f32_16x16x32_bf16(Bt[n][k], At[m][k], acc[ai][bj][m][n], 0, 0, 0); __builtin_amdgcn_s_setprio(0); } while (0)
; #define PG8_WAIT_V(n) asm volatile("s_waitcnt vmcnt(" #n ")" ::: "memory")
; #define PG8_WAIT_L(n) asm volatile("s_waitcnt lgkmcnt(" #n ")" ::: "memory")
; #define PG8_BAR __builtin_amdgcn_s_barrier()
; #define PG8_SCHED __builtin_amdgcn_sched_barrier(0)
; template <class Epi, class Sched, bool ALIGN_EPI = false, bool SP2 = false>
; __device__ __forceinline__ void gemm_phase(PG8_LAS unsigned char* lds, const Gemm g, const Sched& S, const Epi& E, const int wv  ) {
;     ...
;             PG8_WAIT_V(8); PG8_WAIT_L(0); PG8_BAR; PG8_MMA(0, 0, At, B0); PG8_MMA(0, 1, At, B1); PG8_BAR; PG8_SCHED;
;             PG8_LDA(At, 0, 1); PG8_STAGE(PG8_SB(0, 0), b2, voffB); PG8_STAGE(PG8_SB(0, 1), b2 + hstepB, voffB); PG8_STAGE(PG8_SA(0, 0), a2, voffA);
;             PG8_WAIT_V(8); PG8_WAIT_L(0); PG8_BAR; PG8_MMA(1, 0, At, B0); PG8_MMA(1, 1, At, B1); PG8_BAR; PG8_SCHED;
;             PG8_LDB(B0, 1, 0); PG8_LDB(B1, 1, 1); PG8_SCHED; PG8_LDA(At, 1, 0); PG8_STAGE(PG8_SA(0, 1), a2 + hstepA, voffA);
;             PG8_WAIT_V(8); PG8_WAIT_L(0); PG8_BAR; PG8_MMA(0, 0, At, B0); PG8_MMA(0, 1, At, B1); PG8_BAR; PG8_SCHED;
	s_setprio 1
	s_waitcnt lgkmcnt(0)
	v_mfma_f32_16x16x32_bf16 v[28:31], v[146:149], v[184:187], v[28:31]
	v_mfma_f32_16x16x32_bf16 v[24:27], v[160:163], v[184:187], v[24:27]
	v_mfma_f32_16x16x32_bf16 v[20:23], v[146:149], v[192:195], v[20:23]
	v_mfma_f32_16x16x32_bf16 v[16:19], v[160:163], v[192:195], v[16:19]
	v_mfma_f32_16x16x32_bf16 v[12:15], v[146:149], v[200:203], v[12:15]
	v_mfma_f32_16x16x32_bf16 v[8:11], v[160:163], v[200:203], v[8:11]
	v_mfma_f32_16x16x32_bf16 v[4:7], v[146:149], v[208:211], v[4:7]
	v_mfma_f32_16x16x32_bf16 v[0:3], v[160:163], v[208:211], v[0:3]
	v_mfma_f32_16x16x32_bf16 v[28:31], v[156:159], v[188:191], v[28:31]
	v_mfma_f32_16x16x32_bf16 v[24:27], v[164:167], v[188:191], v[24:27]
	v_mfma_f32_16x16x32_bf16 v[20:23], v[156:159], v[196:199], v[20:23]
	v_mfma_f32_16x16x32_bf16 v[16:19], v[164:167], v[196:199], v[16:19]
	v_mfma_f32_16x16x32_bf16 v[12:15], v[156:159], v[204:207], v[12:15]
	v_mfma_f32_16x16x32_bf16 v[8:11], v[164:167], v[204:207], v[8:11]
	v_mfma_f32_16x16x32_bf16 v[4:7], v[156:159], v[212:215], v[4:7]
	v_mfma_f32_16x16x32_bf16 v[0:3], v[164:167], v[212:215], v[0:3]
	s_setprio 0
	s_setprio 1
	v_mfma_f32_16x16x32_bf16 v[92:95], v[168:171], v[184:187], v[92:95]
	v_mfma_f32_16x16x32_bf16 v[88:91], v[176:179], v[184:187], v[88:91]
	v_mfma_f32_16x16x32_bf16 v[84:87], v[168:171], v[192:195], v[84:87]
	v_mfma_f32_16x16x32_bf16 v[80:83], v[176:179], v[192:195], v[80:83]
	v_mfma_f32_16x16x32_bf16 v[60:63], v[168:171], v[200:203], v[60:63]
	v_mfma_f32_16x16x32_bf16 v[48:51], v[176:179], v[200:203], v[48:51]
	v_mfma_f32_16x16x32_bf16 v[36:39], v[168:171], v[208:211], v[36:39]
	v_mfma_f32_16x16x32_bf16 v[32:35], v[176:179], v[208:211], v[32:35]
	v_mfma_f32_16x16x32_bf16 v[92:95], v[172:175], v[188:191], v[92:95]
	v_mfma_f32_16x16x32_bf16 v[88:91], v[180:183], v[188:191], v[88:91]
	v_mfma_f32_16x16x32_bf16 v[84:87], v[172:175], v[196:199], v[84:87]
	v_mfma_f32_16x16x32_bf16 v[80:83], v[180:183], v[196:199], v[80:83]
	v_mfma_f32_16x16x32_bf16 v[60:63], v[172:175], v[204:207], v[60:63]
	v_mfma_f32_16x16x32_bf16 v[48:51], v[180:183], v[204:207], v[48:51]
	s_setprio 2
	s_barrier
	v_mfma_f32_16x16x32_bf16 v[36:39], v[172:175], v[212:215], v[36:39]
	v_mfma_f32_16x16x32_bf16 v[32:35], v[180:183], v[212:215], v[32:35]
	s_setprio 0
	s_add_i32 s90, 0, 0x18000
	v_add_u32_e32 v155, s90, v150
	s_add_i32 s91, 0, 0x1c000
	ds_read_b128 v[146:149], v155
	ds_read_b128 v[156:159], v155 offset:1024
	ds_read_b128 v[160:163], v155 offset:2048
	ds_read_b128 v[164:167], v155 offset:3072
	v_add_u32_e32 v155, s91, v150
	ds_read_b128 v[168:171], v155
	ds_read_b128 v[172:175], v155 offset:1024
	ds_read_b128 v[176:179], v155 offset:2048
	ds_read_b128 v[180:183], v155 offset:3072
	s_add_u32 s62, s62, 0x100000
	s_addc_u32 s63, s63, 0
	s_mov_b32 m0, s72
	v_lshl_add_u64 v[224:225], s[62:63], 0, v[128:129]
	ds_read_b128 v[184:187], v154 offset:32768
	ds_read_b128 v[188:191], v154 offset:33792
	ds_read_b128 v[192:195], v154 offset:34816
	ds_read_b128 v[196:199], v154 offset:35840
	ds_read_b128 v[200:203], v154 offset:36864
	ds_read_b128 v[204:207], v154 offset:37888
	ds_read_b128 v[208:211], v154 offset:38912
	ds_read_b128 v[212:215], v154 offset:39936
	global_load_lds_dwordx4 v[224:225], off
	v_lshl_add_u64 v[224:225], s[62:63], 0, v[132:133]
	s_mov_b32 m0, s73
	s_nop 0
	global_load_lds_dwordx4 v[224:225], off
	s_waitcnt vmcnt(8)
	s_waitcnt lgkmcnt(0)
	s_barrier
	s_setprio 1
	s_waitcnt lgkmcnt(0)
	v_mfma_f32_16x16x32_bf16 v[76:79], v[146:149], v[184:187], v[76:79]
	v_mfma_f32_16x16x32_bf16 v[72:75], v[160:163], v[184:187], v[72:75]
	v_mfma_f32_16x16x32_bf16 v[68:71], v[146:149], v[192:195], v[68:71]
	v_mfma_f32_16x16x32_bf16 v[64:67], v[160:163], v[192:195], v[64:67]
	v_mfma_f32_16x16x32_bf16 v[56:59], v[146:149], v[200:203], v[56:59]
	v_mfma_f32_16x16x32_bf16 v[52:55], v[160:163], v[200:203], v[52:55]
	v_mfma_f32_16x16x32_bf16 v[44:47], v[146:149], v[208:211], v[44:47]
	v_mfma_f32_16x16x32_bf16 v[40:43], v[160:163], v[208:211], v[40:43]
	v_mfma_f32_16x16x32_bf16 v[76:79], v[156:159], v[188:191], v[76:79]
	v_mfma_f32_16x16x32_bf16 v[72:75], v[164:167], v[188:191], v[72:75]
	v_mfma_f32_16x16x32_bf16 v[68:71], v[156:159], v[196:199], v[68:71]
	v_mfma_f32_16x16x32_bf16 v[64:67], v[164:167], v[196:199], v[64:67]
	v_mfma_f32_16x16x32_bf16 v[56:59], v[156:159], v[204:207], v[56:59]
	v_mfma_f32_16x16x32_bf16 v[52:55], v[164:167], v[204:207], v[52:55]
	v_mfma_f32_16x16x32_bf16 v[44:47], v[156:159], v[212:215], v[44:47]
	v_mfma_f32_16x16x32_bf16 v[40:43], v[164:167], v[212:215], v[40:43]
	s_setprio 0
	s_setprio 1
	v_mfma_f32_16x16x32_bf16 v[124:127], v[168:171], v[184:187], v[124:127]
	v_mfma_f32_16x16x32_bf16 v[120:123], v[176:179], v[184:187], v[120:123]
	v_mfma_f32_16x16x32_bf16 v[116:119], v[168:171], v[192:195], v[116:119]
	v_mfma_f32_16x16x32_bf16 v[112:115], v[176:179], v[192:195], v[112:115]
	v_mfma_f32_16x16x32_bf16 v[108:111], v[168:171], v[200:203], v[108:111]
	v_mfma_f32_16x16x32_bf16 v[104:107], v[176:179], v[200:203], v[104:107]
	v_mfma_f32_16x16x32_bf16 v[100:103], v[168:171], v[208:211], v[100:103]
	v_mfma_f32_16x16x32_bf16 v[96:99], v[176:179], v[208:211], v[96:99]
	v_mfma_f32_16x16x32_bf16 v[124:127], v[172:175], v[188:191], v[124:127]
	v_mfma_f32_16x16x32_bf16 v[120:123], v[180:183], v[188:191], v[120:123]
	v_mfma_f32_16x16x32_bf16 v[116:119], v[172:175], v[196:199], v[116:119]
	v_mfma_f32_16x16x32_bf16 v[112:115], v[180:183], v[196:199], v[112:115]
	v_mfma_f32_16x16x32_bf16 v[108:111], v[172:175], v[204:207], v[108:111]
	v_mfma_f32_16x16x32_bf16 v[104:107], v[180:183], v[204:207], v[104:107]
	s_setprio 2
	s_barrier
; #define PG8_STAGE(bufoff, gbase, voff) do { _Pragma("unroll") for (int _i = 0; _i < 2; ++_i) \
;         __builtin_amdgcn_global_load_lds((const unsigned*)((const char*)(gbase) + (voff)[_i]), (PG8_LAS unsigned*)(lds + (bufoff) + ldsw + _i * 8192), 16, 0, 0); } while (0)
; #define PG8_LDA(dst, b, h) do { _Pragma("unroll") for (int m = 0; m < 4; ++m) _Pragma("unroll") for (int k = 0; k < 2; ++k) dst[m][k] = *(const PG8_LAS bf16x8*)(lds + PG8_SA(b, h) + aoff + m * 2048 + k * 1024); } while (0)
; #define PG8_MMA(ai, bj, At, Bt) do { __builtin_amdgcn_s_setprio(1); _Pragma("unroll") for (int m = 0; m < 4; ++m) _Pragma("unroll") for (int n = 0; n < 2; ++n) _Pragma("unroll") for (int k = 0; k < 2; ++k) \
;         acc[ai][bj][m][n] = __builtin_amdgcn_mfma_f32_16x16x32_bf16(Bt[n][k], At[m][k], acc[ai][bj][m][n], 0, 0, 0); __builtin_amdgcn_s_setprio(0); } while (0)
; #define PG8_WAIT_V(n) asm volatile("s_waitcnt vmcnt(" #n ")" ::: "memory")
; #define PG8_WAIT_L(n) asm volatile("s_waitcnt lgkmcnt(" #n ")" ::: "memory")
; #define PG8_BAR __builtin_amdgcn_s_barrier()
; #define PG8_SCHED __builtin_amdgcn_sched_barrier(0)
; template <class Epi, class Sched, bool ALIGN_EPI = false, bool SP2 = false>
; __device__ __forceinline__ void gemm_phase(PG8_LAS unsigned char* lds, const Gemm g, const Sched& S, const Epi& E, const int wv  ) {
;     ...
;             PG8_WAIT_V(8); PG8_WAIT_L(0); PG8_BAR; PG8_MMA(0, 0, At, B0); PG8_MMA(0, 1, At, B1); PG8_BAR; PG8_SCHED;
;             PG8_LDA(At, 1, 1); PG8_STAGE(PG8_SB(1, 0), b3, voffB); PG8_STAGE(PG8_SB(1, 1), b3 + hstepB, voffB); PG8_STAGE(PG8_SA(1, 0), a3, voffA);
;             PG8_WAIT_V(8); PG8_WAIT_L(0); PG8_BAR; PG8_MMA(1, 0, At, B0); PG8_MMA(1, 1, At, B1); PG8_BAR; PG8_SCHED;
;     ...
;         if constexpr (ALIGN_EPI) { if (wr == 0) PG8_BAR; }
	v_mfma_f32_16x16x32_bf16 v[100:103], v[172:175], v[212:215], v[100:103]
	v_mfma_f32_16x16x32_bf16 v[96:99], v[180:183], v[212:215], v[96:99]
	s_setprio 0
	s_add_i32 s62, s90, s69
	v_lshl_add_u64 v[216:217], v[216:217], 0, s[10:11]
	s_mov_b32 m0, s62
	ds_read_b128 v[184:187], v154 offset:49152
	ds_read_b128 v[188:191], v154 offset:50176
	ds_read_b128 v[192:195], v154 offset:51200
	ds_read_b128 v[196:199], v154 offset:52224
	ds_read_b128 v[200:203], v154 offset:53248
	ds_read_b128 v[204:207], v154 offset:54272
	ds_read_b128 v[208:211], v154 offset:55296
	ds_read_b128 v[212:215], v154 offset:56320
	global_load_lds_dwordx4 v[216:217], off
	s_add_i32 m0, s62, 0x2000
	s_add_u32 s60, s60, 0x100080
	v_lshl_add_u64 v[216:217], v[218:219], 0, s[10:11]
	s_addc_u32 s61, s61, 0
	s_add_i32 s62, s91, s69
	global_load_lds_dwordx4 v[216:217], off
	v_lshl_add_u64 v[216:217], s[60:61], 0, v[130:131]
	s_mov_b32 m0, s62
	s_nop 0
	global_load_lds_dwordx4 v[216:217], off
	v_lshl_add_u64 v[216:217], s[60:61], 0, v[134:135]
	s_add_i32 m0, s62, 0x2000
	s_nop 0
	global_load_lds_dwordx4 v[216:217], off
	v_lshl_add_u64 v[216:217], v[220:221], 0, s[10:11]
	s_mov_b32 m0, s64
	s_nop 0
	global_load_lds_dwordx4 v[216:217], off
	v_lshl_add_u64 v[216:217], v[222:223], 0, s[10:11]
	s_mov_b32 m0, s65
	s_nop 0
	global_load_lds_dwordx4 v[216:217], off
	s_waitcnt vmcnt(8)
	s_waitcnt lgkmcnt(0)
	s_barrier
	s_setprio 1
	s_waitcnt lgkmcnt(0)
	v_mfma_f32_16x16x32_bf16 v[28:31], v[146:149], v[184:187], v[28:31]
	v_mfma_f32_16x16x32_bf16 v[24:27], v[160:163], v[184:187], v[24:27]
	v_mfma_f32_16x16x32_bf16 v[20:23], v[146:149], v[192:195], v[20:23]
	v_mfma_f32_16x16x32_bf16 v[16:19], v[160:163], v[192:195], v[16:19]
	v_mfma_f32_16x16x32_bf16 v[12:15], v[146:149], v[200:203], v[12:15]
	v_mfma_f32_16x16x32_bf16 v[8:11], v[160:163], v[200:203], v[8:11]
	v_mfma_f32_16x16x32_bf16 v[4:7], v[146:149], v[208:211], v[4:7]
	v_mfma_f32_16x16x32_bf16 v[0:3], v[160:163], v[208:211], v[0:3]
	v_mfma_f32_16x16x32_bf16 v[28:31], v[156:159], v[188:191], v[28:31]
	v_mfma_f32_16x16x32_bf16 v[24:27], v[164:167], v[188:191], v[24:27]
	v_mfma_f32_16x16x32_bf16 v[20:23], v[156:159], v[196:199], v[20:23]
	v_mfma_f32_16x16x32_bf16 v[16:19], v[164:167], v[196:199], v[16:19]
	v_mfma_f32_16x16x32_bf16 v[12:15], v[156:159], v[204:207], v[12:15]
	v_mfma_f32_16x16x32_bf16 v[8:11], v[164:167], v[204:207], v[8:11]
	v_mfma_f32_16x16x32_bf16 v[4:7], v[156:159], v[212:215], v[4:7]
	v_mfma_f32_16x16x32_bf16 v[0:3], v[164:167], v[212:215], v[0:3]
	s_setprio 0
	s_setprio 1
	v_mfma_f32_16x16x32_bf16 v[92:95], v[168:171], v[184:187], v[92:95]
	v_mfma_f32_16x16x32_bf16 v[88:91], v[176:179], v[184:187], v[88:91]
	v_mfma_f32_16x16x32_bf16 v[84:87], v[168:171], v[192:195], v[84:87]
	v_mfma_f32_16x16x32_bf16 v[80:83], v[176:179], v[192:195], v[80:83]
	v_mfma_f32_16x16x32_bf16 v[60:63], v[168:171], v[200:203], v[60:63]
	v_mfma_f32_16x16x32_bf16 v[48:51], v[176:179], v[200:203], v[48:51]
	v_mfma_f32_16x16x32_bf16 v[36:39], v[168:171], v[208:211], v[36:39]
	v_mfma_f32_16x16x32_bf16 v[32:35], v[176:179], v[208:211], v[32:35]
	v_mfma_f32_16x16x32_bf16 v[92:95], v[172:175], v[188:191], v[92:95]
	v_mfma_f32_16x16x32_bf16 v[88:91], v[180:183], v[188:191], v[88:91]
	v_mfma_f32_16x16x32_bf16 v[84:87], v[172:175], v[196:199], v[84:87]
	v_mfma_f32_16x16x32_bf16 v[80:83], v[180:183], v[196:199], v[80:83]
	v_mfma_f32_16x16x32_bf16 v[60:63], v[172:175], v[204:207], v[60:63]
	v_mfma_f32_16x16x32_bf16 v[48:51], v[180:183], v[204:207], v[48:51]
	s_setprio 2
	s_barrier
	v_mfma_f32_16x16x32_bf16 v[36:39], v[172:175], v[212:215], v[36:39]
	v_mfma_f32_16x16x32_bf16 v[32:35], v[180:183], v[212:215], v[32:35]
	s_setprio 0
	s_add_i32 s87, s87, 2
	s_add_u32 s58, s58, 0x100
	s_addc_u32 s59, s59, 0
	s_add_u32 s85, s85, 0x100
	s_addc_u32 s86, s86, 0
	s_cmp_gt_u32 s87, 61
	s_cbranch_scc0 .LBB0_1717
	s_and_b64 vcc, exec, s[12:13]
	s_cbranch_vccz .LBB0_1720
	s_barrier

; #define PG8_STAGE(bufoff, gbase, voff) do { _Pragma("unroll") for (int _i = 0; _i < 2; ++_i) \
;         __builtin_amdgcn_global_load_lds((const unsigned*)((const char*)(gbase) + (voff)[_i]), (PG8_LAS unsigned*)(lds + (bufoff) + ldsw + _i * 8192), 16, 0, 0); } while (0)
; #define PG8_LDA(dst, b, h) do { _Pragma("unroll") for (int m = 0; m < 4; ++m) _Pragma("unroll") for (int k = 0; k < 2; ++k) dst[m][k] = *(const PG8_LAS bf16x8*)(lds + PG8_SA(b, h) + aoff + m * 2048 + k * 1024); } while (0)
; #define PG8_LDB(dst, b, h) do { _Pragma("unroll") for (int n = 0; n < 2; ++n) _Pragma("unroll") for (int k = 0; k < 2; ++k) dst[n][k] = *(const PG8_LAS bf16x8*)(lds + PG8_SB(b, h) + boff + n * 2048 + k * 1024); } while (0)
; #define PG8_MMA(ai, bj, At, Bt) do { __builtin_amdgcn_s_setprio(1); _Pragma("unroll") for (int m = 0; m < 4; ++m) _Pragma("unroll") for (int n = 0; n < 2; ++n) _Pragma("unroll") for (int k = 0; k < 2; ++k) \
;         acc[ai][bj][m][n] = __builtin_amdgcn_mfma_f32_16x16x32_bf16(Bt[n][k], At[m][k], acc[ai][bj][m][n], 0, 0, 0); __builtin_amdgcn_s_setprio(0); } while (0)
; #define PG8_WAIT_V(n) asm volatile("s_waitcnt vmcnt(" #n ")" ::: "memory")
; #define PG8_WAIT_L(n) asm volatile("s_waitcnt lgkmcnt(" #n ")" ::: "memory")
; #define PG8_BAR __builtin_amdgcn_s_barrier()
; template <class Epi, class Sched, bool ALIGN_EPI = false, bool SP2 = false>
; __device__ __forceinline__ void gemm_phase(PG8_LAS unsigned char* lds, const Gemm g, const Sched& S, const Epi& E, const int wv  ) {
;     ...
;         for (int t = 0; t < nt; t += 2) {
;             const bool last = (t == nt - 2);
;             const char* a1 = cA + (size_t)(t + 1) * kstep;
;             const char* a2 = last ? nA : cA + (size_t)(t + 2) * kstep; const char* b2 = last ? nB : cB + (size_t)(t + 2) * kstep;
;             const char* a3 = a2 + kstep; const char* b3 = b2 + kstep;
;             if (last && has_next) S.a_ready(nxt);
;             if constexpr (SP2) {
;             PG8_LDB(B0, 0, 0); PG8_LDB(B1, 0, 1); PG8_SCHED; PG8_LDA(At, 0, 0); PG8_STAGE(PG8_SA(1, 1), a1 + hstepA, voffA);
;             PG8_WAIT_V(8); PG8_WAIT_L(0); PG8_BAR; PG8_MMA(0, 0, At, B0); PG8_MMA(0, 1, At, B1); PG8_BAR; PG8_SCHED;
;             PG8_LDA(At, 0, 1); PG8_STAGE(PG8_SB(0, 0), b2, voffB); PG8_STAGE(PG8_SB(0, 1), b2 + hstepB, voffB); PG8_STAGE(PG8_SA(0, 0), a2, voffA);
.LBB0_2399:
	ds_read_b128 v[44:47], v196
	ds_read_b128 v[48:51], v196 offset:1024
	ds_read_b128 v[52:55], v196 offset:2048
	ds_read_b128 v[56:59], v196 offset:3072
	ds_read_b128 v[60:63], v197
	ds_read_b128 v[68:71], v197 offset:1024
	ds_read_b128 v[72:75], v197 offset:2048
	ds_read_b128 v[76:79], v197 offset:3072
	s_add_u32 s68, s66, 0xfff00080
	s_addc_u32 s69, s67, -1
	s_cmp_eq_u32 s94, 60
	s_cselect_b32 s71, s57, s69
	s_cselect_b32 s70, s63, s68
	s_cselect_b32 s69, s55, s93
	s_cselect_b32 s68, s65, s92
	v_lshl_add_u64 v[224:225], s[66:67], 0, v[172:173]
	s_add_i32 m0, s75, 0xc000
	ds_read_b128 v[180:183], v198
	ds_read_b128 v[184:187], v198 offset:1024
	ds_read_b128 v[200:203], v198 offset:2048
	ds_read_b128 v[204:207], v198 offset:3072
	ds_read_b128 v[208:211], v198 offset:4096
	ds_read_b128 v[212:215], v198 offset:5120
	ds_read_b128 v[216:219], v198 offset:6144
	ds_read_b128 v[220:223], v198 offset:7168
	global_load_lds_dwordx4 v[224:225], off
	v_lshl_add_u64 v[224:225], s[66:67], 0, v[174:175]
	s_add_i32 m0, s75, 0xe000
	s_nop 0
	global_load_lds_dwordx4 v[224:225], off
	s_waitcnt vmcnt(8)
	s_waitcnt lgkmcnt(0)
	s_barrier
	s_setprio 1
	s_waitcnt lgkmcnt(0)
	v_mfma_f32_16x16x32_bf16 v[104:107], v[44:47], v[180:183], v[104:107]
	v_mfma_f32_16x16x32_bf16 v[100:103], v[52:55], v[180:183], v[100:103]
	v_mfma_f32_16x16x32_bf16 v[156:159], v[44:47], v[200:203], v[156:159]
	v_mfma_f32_16x16x32_bf16 v[148:151], v[52:55], v[200:203], v[148:151]
	v_mfma_f32_16x16x32_bf16 v[140:143], v[44:47], v[208:211], v[140:143]
	v_mfma_f32_16x16x32_bf16 v[132:135], v[52:55], v[208:211], v[132:135]
	v_mfma_f32_16x16x32_bf16 v[124:127], v[44:47], v[216:219], v[124:127]
	v_mfma_f32_16x16x32_bf16 v[120:123], v[52:55], v[216:219], v[120:123]
	v_mfma_f32_16x16x32_bf16 v[104:107], v[48:51], v[184:187], v[104:107]
	v_mfma_f32_16x16x32_bf16 v[100:103], v[56:59], v[184:187], v[100:103]
	v_mfma_f32_16x16x32_bf16 v[156:159], v[48:51], v[204:207], v[156:159]
	v_mfma_f32_16x16x32_bf16 v[148:151], v[56:59], v[204:207], v[148:151]
	v_mfma_f32_16x16x32_bf16 v[140:143], v[48:51], v[212:215], v[140:143]
	v_mfma_f32_16x16x32_bf16 v[132:135], v[56:59], v[212:215], v[132:135]
	v_mfma_f32_16x16x32_bf16 v[124:127], v[48:51], v[220:223], v[124:127]
	v_mfma_f32_16x16x32_bf16 v[120:123], v[56:59], v[220:223], v[120:123]
	s_setprio 0
	s_setprio 1
	v_mfma_f32_16x16x32_bf16 v[92:95], v[60:63], v[180:183], v[92:95]
	v_mfma_f32_16x16x32_bf16 v[88:91], v[72:75], v[180:183], v[88:91]
	v_mfma_f32_16x16x32_bf16 v[152:155], v[60:63], v[200:203], v[152:155]
	v_mfma_f32_16x16x32_bf16 v[144:147], v[72:75], v[200:203], v[144:147]
	v_mfma_f32_16x16x32_bf16 v[136:139], v[60:63], v[208:211], v[136:139]
	v_mfma_f32_16x16x32_bf16 v[128:131], v[72:75], v[208:211], v[128:131]
	v_mfma_f32_16x16x32_bf16 v[116:119], v[60:63], v[216:219], v[116:119]
	v_mfma_f32_16x16x32_bf16 v[112:115], v[72:75], v[216:219], v[112:115]
	v_mfma_f32_16x16x32_bf16 v[92:95], v[68:71], v[184:187], v[92:95]
	v_mfma_f32_16x16x32_bf16 v[88:91], v[76:79], v[184:187], v[88:91]
	v_mfma_f32_16x16x32_bf16 v[152:155], v[68:71], v[204:207], v[152:155]
	v_mfma_f32_16x16x32_bf16 v[144:147], v[76:79], v[204:207], v[144:147]
	v_mfma_f32_16x16x32_bf16 v[136:139], v[68:71], v[212:215], v[136:139]
	v_mfma_f32_16x16x32_bf16 v[128:131], v[76:79], v[212:215], v[128:131]
	s_setprio 2
	s_barrier
	v_mfma_f32_16x16x32_bf16 v[116:119], v[68:71], v[220:223], v[116:119]
	v_mfma_f32_16x16x32_bf16 v[112:115], v[76:79], v[220:223], v[112:115]
	s_setprio 0
	s_add_i32 s95, s87, s74
	v_lshl_add_u64 v[228:229], s[68:69], 0, v[162:163]
	s_mov_b32 m0, s95
	ds_read_b128 v[180:183], v198 offset:16384
	ds_read_b128 v[184:187], v198 offset:17408
	ds_read_b128 v[200:203], v198 offset:18432
	ds_read_b128 v[204:207], v198 offset:19456
	ds_read_b128 v[208:211], v198 offset:20480
	ds_read_b128 v[212:215], v198 offset:21504
	ds_read_b128 v[216:219], v198 offset:22528
	ds_read_b128 v[220:223], v198 offset:23552
	global_load_lds_dwordx4 v[228:229], off
	s_add_i32 m0, s95, 0x2000
	s_add_u32 s96, s68, 0x100000
	v_lshl_add_u64 v[230:231], s[68:69], 0, v[166:167]
	s_addc_u32 s97, s69, 0
	s_add_i32 s95, s90, s74
	global_load_lds_dwordx4 v[230:231], off
	v_lshl_add_u64 v[224:225], s[96:97], 0, v[162:163]
	s_mov_b32 m0, s95
	v_lshl_add_u64 v[232:233], s[70:71], 0, v[160:161]
	global_load_lds_dwordx4 v[224:225], off
	v_lshl_add_u64 v[224:225], s[96:97], 0, v[166:167]
	s_add_i32 m0, s95, 0x2000
	v_lshl_add_u64 v[234:235], s[70:71], 0, v[164:165]
	global_load_lds_dwordx4 v[224:225], off
	s_mov_b32 m0, s75
	s_nop 0
	global_load_lds_dwordx4 v[232:233], off
	s_mov_b32 m0, s76
	s_nop 0
	global_load_lds_dwordx4 v[234:235], off
	s_waitcnt vmcnt(8)
	s_waitcnt lgkmcnt(0)
	s_barrier
; #define PG8_STAGE(bufoff, gbase, voff) do { _Pragma("unroll") for (int _i = 0; _i < 2; ++_i) \
;         __builtin_amdgcn_global_load_lds((const unsigned*)((const char*)(gbase) + (voff)[_i]), (PG8_LAS unsigned*)(lds + (bufoff) + ldsw + _i * 8192), 16, 0, 0); } while (0)
; #define PG8_LDA(dst, b, h) do { _Pragma("unroll") for (int m = 0; m < 4; ++m) _Pragma("unroll") for (int k = 0; k < 2; ++k) dst[m][k] = *(const PG8_LAS bf16x8*)(lds + PG8_SA(b, h) + aoff + m * 2048 + k * 1024); } while (0)
; #define PG8_LDB(dst, b, h) do { _Pragma("unroll") for (int n = 0; n < 2; ++n) _Pragma("unroll") for (int k = 0; k < 2; ++k) dst[n][k] = *(const PG8_LAS bf16x8*)(lds + PG8_SB(b, h) + boff + n * 2048 + k * 1024); } while (0)
; #define PG8_MMA(ai, bj, At, Bt) do { __builtin_amdgcn_s_setprio(1); _Pragma("unroll") for (int m = 0; m < 4; ++m) _Pragma("unroll") for (int n = 0; n < 2; ++n) _Pragma("unroll") for (int k = 0; k < 2; ++k) \
;         acc[ai][bj][m][n] = __builtin_amdgcn_mfma_f32_16x16x32_bf16(Bt[n][k], At[m][k], acc[ai][bj][m][n], 0, 0, 0); __builtin_amdgcn_s_setprio(0); } while (0)
; #define PG8_WAIT_V(n) asm volatile("s_waitcnt vmcnt(" #n ")" ::: "memory")
; #define PG8_WAIT_L(n) asm volatile("s_waitcnt lgkmcnt(" #n ")" ::: "memory")
; #define PG8_BAR __builtin_amdgcn_s_barrier()
; #define PG8_SCHED __builtin_amdgcn_sched_barrier(0)
; template <class Epi, class Sched, bool ALIGN_EPI = false, bool SP2 = false>
; __device__ __forceinline__ void gemm_phase(PG8_LAS unsigned char* lds, const Gemm g, const Sched& S, const Epi& E, const int wv  ) {
;     ...
;             PG8_WAIT_V(8); PG8_WAIT_L(0); PG8_BAR; PG8_MMA(1, 0, At, B0); PG8_MMA(1, 1, At, B1); PG8_BAR; PG8_SCHED;
;             PG8_LDB(B0, 1, 0); PG8_LDB(B1, 1, 1); PG8_SCHED; PG8_LDA(At, 1, 0); PG8_STAGE(PG8_SA(0, 1), a2 + hstepA, voffA);
;             PG8_WAIT_V(8); PG8_WAIT_L(0); PG8_BAR; PG8_MMA(0, 0, At, B0); PG8_MMA(0, 1, At, B1); PG8_BAR; PG8_SCHED;
	s_setprio 1
	s_waitcnt lgkmcnt(0)
	v_mfma_f32_16x16x32_bf16 v[108:111], v[44:47], v[180:183], v[108:111]
	v_mfma_f32_16x16x32_bf16 v[96:99], v[52:55], v[180:183], v[96:99]
	v_mfma_f32_16x16x32_bf16 v[64:67], v[44:47], v[200:203], v[64:67]
	v_mfma_f32_16x16x32_bf16 v[36:39], v[52:55], v[200:203], v[36:39]
	v_mfma_f32_16x16x32_bf16 v[28:31], v[44:47], v[208:211], v[28:31]
	v_mfma_f32_16x16x32_bf16 v[20:23], v[52:55], v[208:211], v[20:23]
	v_mfma_f32_16x16x32_bf16 v[12:15], v[44:47], v[216:219], v[12:15]
	v_mfma_f32_16x16x32_bf16 v[4:7], v[52:55], v[216:219], v[4:7]
	v_mfma_f32_16x16x32_bf16 v[108:111], v[48:51], v[184:187], v[108:111]
	v_mfma_f32_16x16x32_bf16 v[96:99], v[56:59], v[184:187], v[96:99]
	v_mfma_f32_16x16x32_bf16 v[64:67], v[48:51], v[204:207], v[64:67]
	v_mfma_f32_16x16x32_bf16 v[36:39], v[56:59], v[204:207], v[36:39]
	v_mfma_f32_16x16x32_bf16 v[28:31], v[48:51], v[212:215], v[28:31]
	v_mfma_f32_16x16x32_bf16 v[20:23], v[56:59], v[212:215], v[20:23]
	v_mfma_f32_16x16x32_bf16 v[12:15], v[48:51], v[220:223], v[12:15]
	v_mfma_f32_16x16x32_bf16 v[4:7], v[56:59], v[220:223], v[4:7]
	s_setprio 0
	s_setprio 1
	v_mfma_f32_16x16x32_bf16 v[40:43], v[60:63], v[200:203], v[40:43]
	v_mfma_f32_16x16x32_bf16 v[32:35], v[72:75], v[200:203], v[32:35]
	v_mfma_f32_16x16x32_bf16 v[24:27], v[60:63], v[208:211], v[24:27]
	v_mfma_f32_16x16x32_bf16 v[16:19], v[72:75], v[208:211], v[16:19]
	v_mfma_f32_16x16x32_bf16 v[8:11], v[60:63], v[216:219], v[8:11]
	v_mfma_f32_16x16x32_bf16 v[0:3], v[72:75], v[216:219], v[0:3]
	v_mfma_f32_16x16x32_bf16 v[44:47], v[60:63], v[180:183], v[84:87]
	v_mfma_f32_16x16x32_bf16 v[48:51], v[72:75], v[180:183], v[80:83]
	v_mfma_f32_16x16x32_bf16 v[40:43], v[68:71], v[204:207], v[40:43]
	v_mfma_f32_16x16x32_bf16 v[32:35], v[76:79], v[204:207], v[32:35]
	v_mfma_f32_16x16x32_bf16 v[24:27], v[68:71], v[212:215], v[24:27]
	v_mfma_f32_16x16x32_bf16 v[16:19], v[76:79], v[212:215], v[16:19]
	v_mfma_f32_16x16x32_bf16 v[8:11], v[68:71], v[220:223], v[8:11]
	v_mfma_f32_16x16x32_bf16 v[0:3], v[76:79], v[220:223], v[0:3]
	s_setprio 2
	s_barrier
	v_mfma_f32_16x16x32_bf16 v[44:47], v[68:71], v[184:187], v[44:47]
	v_mfma_f32_16x16x32_bf16 v[48:51], v[76:79], v[184:187], v[48:51]
	s_setprio 0
	s_add_i32 s95, 0, 0x18000
	s_add_i32 s96, 0, 0x1c000
	v_add_u32_e32 v68, s95, v190
	v_add_u32_e32 v80, s96, v190
	ds_read_b128 v[52:55], v68
	ds_read_b128 v[56:59], v68 offset:1024
	ds_read_b128 v[60:63], v68 offset:2048
	ds_read_b128 v[68:71], v68 offset:3072
	ds_read_b128 v[72:75], v80
	ds_read_b128 v[76:79], v80 offset:1024
	ds_read_b128 v[180:183], v80 offset:2048
	ds_read_b128 v[184:187], v80 offset:3072
	s_add_u32 s70, s70, 0x100000
	s_addc_u32 s71, s71, 0
	s_mov_b32 m0, s77
	v_lshl_add_u64 v[224:225], s[70:71], 0, v[160:161]
	ds_read_b128 v[80:83], v198 offset:32768
	ds_read_b128 v[84:87], v198 offset:33792
	ds_read_b128 v[200:203], v198 offset:34816
	ds_read_b128 v[204:207], v198 offset:35840
	ds_read_b128 v[208:211], v198 offset:36864
	ds_read_b128 v[212:215], v198 offset:37888
	ds_read_b128 v[216:219], v198 offset:38912
	ds_read_b128 v[220:223], v198 offset:39936
	global_load_lds_dwordx4 v[224:225], off
	v_lshl_add_u64 v[224:225], s[70:71], 0, v[164:165]
	s_mov_b32 m0, s78
	s_nop 0
	global_load_lds_dwordx4 v[224:225], off
	s_waitcnt vmcnt(8)
	s_waitcnt lgkmcnt(0)
	s_barrier
	s_setprio 1
	s_waitcnt lgkmcnt(0)
	v_mfma_f32_16x16x32_bf16 v[104:107], v[52:55], v[80:83], v[104:107]
	v_mfma_f32_16x16x32_bf16 v[100:103], v[60:63], v[80:83], v[100:103]
	v_mfma_f32_16x16x32_bf16 v[156:159], v[52:55], v[200:203], v[156:159]
	v_mfma_f32_16x16x32_bf16 v[148:151], v[60:63], v[200:203], v[148:151]
	v_mfma_f32_16x16x32_bf16 v[140:143], v[52:55], v[208:211], v[140:143]
	v_mfma_f32_16x16x32_bf16 v[132:135], v[60:63], v[208:211], v[132:135]
	v_mfma_f32_16x16x32_bf16 v[124:127], v[52:55], v[216:219], v[124:127]
	v_mfma_f32_16x16x32_bf16 v[120:123], v[60:63], v[216:219], v[120:123]
	v_mfma_f32_16x16x32_bf16 v[104:107], v[56:59], v[84:87], v[104:107]
	v_mfma_f32_16x16x32_bf16 v[100:103], v[68:71], v[84:87], v[100:103]
	v_mfma_f32_16x16x32_bf16 v[156:159], v[56:59], v[204:207], v[156:159]
	v_mfma_f32_16x16x32_bf16 v[148:151], v[68:71], v[204:207], v[148:151]
	v_mfma_f32_16x16x32_bf16 v[140:143], v[56:59], v[212:215], v[140:143]
	v_mfma_f32_16x16x32_bf16 v[132:135], v[68:71], v[212:215], v[132:135]
	v_mfma_f32_16x16x32_bf16 v[124:127], v[56:59], v[220:223], v[124:127]
	v_mfma_f32_16x16x32_bf16 v[120:123], v[68:71], v[220:223], v[120:123]
	s_setprio 0
	s_setprio 1
	v_mfma_f32_16x16x32_bf16 v[92:95], v[72:75], v[80:83], v[92:95]
	v_mfma_f32_16x16x32_bf16 v[80:83], v[180:183], v[80:83], v[88:91]
	v_mfma_f32_16x16x32_bf16 v[88:91], v[184:187], v[84:87], v[80:83]
	v_mfma_f32_16x16x32_bf16 v[80:83], v[72:75], v[200:203], v[152:155]
	v_mfma_f32_16x16x32_bf16 v[152:155], v[76:79], v[204:207], v[80:83]
	v_mfma_f32_16x16x32_bf16 v[80:83], v[180:183], v[200:203], v[144:147]
	v_mfma_f32_16x16x32_bf16 v[144:147], v[184:187], v[204:207], v[80:83]
	v_mfma_f32_16x16x32_bf16 v[80:83], v[72:75], v[208:211], v[136:139]
	v_mfma_f32_16x16x32_bf16 v[136:139], v[76:79], v[212:215], v[80:83]
	v_mfma_f32_16x16x32_bf16 v[80:83], v[180:183], v[208:211], v[128:131]
	v_mfma_f32_16x16x32_bf16 v[128:131], v[184:187], v[212:215], v[80:83]
	v_mfma_f32_16x16x32_bf16 v[80:83], v[72:75], v[216:219], v[116:119]
	v_mfma_f32_16x16x32_bf16 v[116:119], v[76:79], v[220:223], v[80:83]
	v_mfma_f32_16x16x32_bf16 v[80:83], v[180:183], v[216:219], v[112:115]
	s_setprio 2
	s_barrier
; #define PG8_STAGE(bufoff, gbase, voff) do { _Pragma("unroll") for (int _i = 0; _i < 2; ++_i) \
;         __builtin_amdgcn_global_load_lds((const unsigned*)((const char*)(gbase) + (voff)[_i]), (PG8_LAS unsigned*)(lds + (bufoff) + ldsw + _i * 8192), 16, 0, 0); } while (0)
; #define PG8_LDA(dst, b, h) do { _Pragma("unroll") for (int m = 0; m < 4; ++m) _Pragma("unroll") for (int k = 0; k < 2; ++k) dst[m][k] = *(const PG8_LAS bf16x8*)(lds + PG8_SA(b, h) + aoff + m * 2048 + k * 1024); } while (0)
; #define PG8_MMA(ai, bj, At, Bt) do { __builtin_amdgcn_s_setprio(1); _Pragma("unroll") for (int m = 0; m < 4; ++m) _Pragma("unroll") for (int n = 0; n < 2; ++n) _Pragma("unroll") for (int k = 0; k < 2; ++k) \
;         acc[ai][bj][m][n] = __builtin_amdgcn_mfma_f32_16x16x32_bf16(Bt[n][k], At[m][k], acc[ai][bj][m][n], 0, 0, 0); __builtin_amdgcn_s_setprio(0); } while (0)
; #define PG8_WAIT_V(n) asm volatile("s_waitcnt vmcnt(" #n ")" ::: "memory")
; #define PG8_WAIT_L(n) asm volatile("s_waitcnt lgkmcnt(" #n ")" ::: "memory")
; #define PG8_BAR __builtin_amdgcn_s_barrier()
; #define PG8_SCHED __builtin_amdgcn_sched_barrier(0)
; template <class Epi, class Sched, bool ALIGN_EPI = false, bool SP2 = false>
; __device__ __forceinline__ void gemm_phase(PG8_LAS unsigned char* lds, const Gemm g, const Sched& S, const Epi& E, const int wv  ) {
;     ...
;             PG8_WAIT_V(8); PG8_WAIT_L(0); PG8_BAR; PG8_MMA(0, 0, At, B0); PG8_MMA(0, 1, At, B1); PG8_BAR; PG8_SCHED;
;             PG8_LDA(At, 1, 1); PG8_STAGE(PG8_SB(1, 0), b3, voffB); PG8_STAGE(PG8_SB(1, 1), b3 + hstepB, voffB); PG8_STAGE(PG8_SA(1, 0), a3, voffA);
;             PG8_WAIT_V(8); PG8_WAIT_L(0); PG8_BAR; PG8_MMA(1, 0, At, B0); PG8_MMA(1, 1, At, B1); PG8_BAR; PG8_SCHED;
;     ...
;         if constexpr (ALIGN_EPI) { if (wr == 0) PG8_BAR; }
	v_mfma_f32_16x16x32_bf16 v[92:95], v[76:79], v[84:87], v[92:95]
	v_mfma_f32_16x16x32_bf16 v[112:115], v[184:187], v[220:223], v[80:83]
	s_setprio 0
	s_add_i32 s70, s95, s74
	v_lshl_add_u64 v[84:85], v[228:229], 0, s[20:21]
	s_mov_b32 m0, s70
	s_nop 0
	ds_read_b128 v[80:83], v198 offset:49152
	ds_read_b128 v[200:203], v198 offset:50176
	ds_read_b128 v[204:207], v198 offset:51200
	ds_read_b128 v[208:211], v198 offset:52224
	ds_read_b128 v[212:215], v198 offset:53248
	ds_read_b128 v[216:219], v198 offset:54272
	ds_read_b128 v[220:223], v198 offset:55296
	ds_read_b128 v[224:227], v198 offset:56320
	global_load_lds_dwordx4 v[84:85], off
	s_add_i32 m0, s70, 0x2000
	s_add_u32 s68, s68, 0x100080
	v_lshl_add_u64 v[84:85], v[230:231], 0, s[20:21]
	s_addc_u32 s69, s69, 0
	s_add_i32 s70, s96, s74
	global_load_lds_dwordx4 v[84:85], off
	v_lshl_add_u64 v[84:85], s[68:69], 0, v[162:163]
	s_mov_b32 m0, s70
	s_nop 0
	global_load_lds_dwordx4 v[84:85], off
	v_lshl_add_u64 v[84:85], s[68:69], 0, v[166:167]
	s_add_i32 m0, s70, 0x2000
	s_nop 0
	global_load_lds_dwordx4 v[84:85], off
	v_lshl_add_u64 v[84:85], v[232:233], 0, s[20:21]
	s_mov_b32 m0, s82
	s_nop 0
	global_load_lds_dwordx4 v[84:85], off
	v_lshl_add_u64 v[84:85], v[234:235], 0, s[20:21]
	s_mov_b32 m0, s83
	s_nop 0
	global_load_lds_dwordx4 v[84:85], off
	s_waitcnt vmcnt(8)
	s_waitcnt lgkmcnt(0)
	s_barrier
	s_setprio 1
	s_waitcnt lgkmcnt(0)
	v_mfma_f32_16x16x32_bf16 v[84:87], v[52:55], v[80:83], v[108:111]
	v_mfma_f32_16x16x32_bf16 v[108:111], v[56:59], v[200:203], v[84:87]
	v_mfma_f32_16x16x32_bf16 v[84:87], v[60:63], v[80:83], v[96:99]
	v_mfma_f32_16x16x32_bf16 v[64:67], v[52:55], v[204:207], v[64:67]
	v_mfma_f32_16x16x32_bf16 v[36:39], v[60:63], v[204:207], v[36:39]
	v_mfma_f32_16x16x32_bf16 v[28:31], v[52:55], v[212:215], v[28:31]
	v_mfma_f32_16x16x32_bf16 v[20:23], v[60:63], v[212:215], v[20:23]
	v_mfma_f32_16x16x32_bf16 v[12:15], v[52:55], v[220:223], v[12:15]
	v_mfma_f32_16x16x32_bf16 v[4:7], v[60:63], v[220:223], v[4:7]
	v_mfma_f32_16x16x32_bf16 v[96:99], v[68:71], v[200:203], v[84:87]
	v_mfma_f32_16x16x32_bf16 v[64:67], v[56:59], v[208:211], v[64:67]
	v_mfma_f32_16x16x32_bf16 v[36:39], v[68:71], v[208:211], v[36:39]
	v_mfma_f32_16x16x32_bf16 v[28:31], v[56:59], v[216:219], v[28:31]
	v_mfma_f32_16x16x32_bf16 v[20:23], v[68:71], v[216:219], v[20:23]
	v_mfma_f32_16x16x32_bf16 v[12:15], v[56:59], v[224:227], v[12:15]
	v_mfma_f32_16x16x32_bf16 v[4:7], v[68:71], v[224:227], v[4:7]
	s_setprio 0
	s_setprio 1
	v_mfma_f32_16x16x32_bf16 v[44:47], v[72:75], v[80:83], v[44:47]
	v_mfma_f32_16x16x32_bf16 v[84:87], v[76:79], v[200:203], v[44:47]
	v_mfma_f32_16x16x32_bf16 v[44:47], v[180:183], v[80:83], v[48:51]
	v_mfma_f32_16x16x32_bf16 v[40:43], v[72:75], v[204:207], v[40:43]
	v_mfma_f32_16x16x32_bf16 v[32:35], v[180:183], v[204:207], v[32:35]
	v_mfma_f32_16x16x32_bf16 v[24:27], v[72:75], v[212:215], v[24:27]
	v_mfma_f32_16x16x32_bf16 v[16:19], v[180:183], v[212:215], v[16:19]
	v_mfma_f32_16x16x32_bf16 v[8:11], v[72:75], v[220:223], v[8:11]
	v_mfma_f32_16x16x32_bf16 v[0:3], v[180:183], v[220:223], v[0:3]
	v_mfma_f32_16x16x32_bf16 v[80:83], v[184:187], v[200:203], v[44:47]
	v_mfma_f32_16x16x32_bf16 v[40:43], v[76:79], v[208:211], v[40:43]
	v_mfma_f32_16x16x32_bf16 v[32:35], v[184:187], v[208:211], v[32:35]
	v_mfma_f32_16x16x32_bf16 v[24:27], v[76:79], v[216:219], v[24:27]
	v_mfma_f32_16x16x32_bf16 v[16:19], v[184:187], v[216:219], v[16:19]
	s_setprio 2
	s_barrier
	v_mfma_f32_16x16x32_bf16 v[8:11], v[76:79], v[224:227], v[8:11]
	v_mfma_f32_16x16x32_bf16 v[0:3], v[184:187], v[224:227], v[0:3]
	s_setprio 0
	s_add_i32 s94, s94, 2
	s_add_u32 s66, s66, 0x100
	s_addc_u32 s67, s67, 0
	s_add_u32 s92, s92, 0x100
	s_addc_u32 s93, s93, 0
	s_cmp_gt_u32 s94, 61
	s_cbranch_scc0 .LBB0_2399
	s_and_b64 vcc, exec, s[22:23]
	s_cbranch_vccz .LBB0_2402
	s_barrier

; #define PG8_STAGE(bufoff, gbase, voff) do { _Pragma("unroll") for (int _i = 0; _i < 2; ++_i) \
;         __builtin_amdgcn_global_load_lds((const unsigned*)((const char*)(gbase) + (voff)[_i]), (PG8_LAS unsigned*)(lds + (bufoff) + ldsw + _i * 8192), 16, 0, 0); } while (0)
; #define PG8_LDA(dst, b, h) do { _Pragma("unroll") for (int m = 0; m < 4; ++m) _Pragma("unroll") for (int k = 0; k < 2; ++k) dst[m][k] = *(const PG8_LAS bf16x8*)(lds + PG8_SA(b, h) + aoff + m * 2048 + k * 1024); } while (0)
; #define PG8_LDB(dst, b, h) do { _Pragma("unroll") for (int n = 0; n < 2; ++n) _Pragma("unroll") for (int k = 0; k < 2; ++k) dst[n][k] = *(const PG8_LAS bf16x8*)(lds + PG8_SB(b, h) + boff + n * 2048 + k * 1024); } while (0)
; #define PG8_MMA(ai, bj, At, Bt) do { __builtin_amdgcn_s_setprio(1); _Pragma("unroll") for (int m = 0; m < 4; ++m) _Pragma("unroll") for (int n = 0; n < 2; ++n) _Pragma("unroll") for (int k = 0; k < 2; ++k) \
;         acc[ai][bj][m][n] = __builtin_amdgcn_mfma_f32_16x16x32_bf16(Bt[n][k], At[m][k], acc[ai][bj][m][n], 0, 0, 0); __builtin_amdgcn_s_setprio(0); } while (0)
; #define PG8_WAIT_V(n) asm volatile("s_waitcnt vmcnt(" #n ")" ::: "memory")
; #define PG8_WAIT_L(n) asm volatile("s_waitcnt lgkmcnt(" #n ")" ::: "memory")
; #define PG8_BAR __builtin_amdgcn_s_barrier()
; template <class Epi, class Sched, bool ALIGN_EPI = false, bool SP2 = false>
; __device__ __forceinline__ void gemm_phase(PG8_LAS unsigned char* lds, const Gemm g, const Sched& S, const Epi& E, const int wv  ) {
;     ...
;         for (int t = 0; t < nt; t += 2) {
;             const bool last = (t == nt - 2);
;             const char* a1 = cA + (size_t)(t + 1) * kstep;
;             const char* a2 = last ? nA : cA + (size_t)(t + 2) * kstep; const char* b2 = last ? nB : cB + (size_t)(t + 2) * kstep;
;             const char* a3 = a2 + kstep; const char* b3 = b2 + kstep;
;             if (last && has_next) S.a_ready(nxt);
;             if constexpr (SP2) {
;             PG8_LDB(B0, 0, 0); PG8_LDB(B1, 0, 1); PG8_SCHED; PG8_LDA(At, 0, 0); PG8_STAGE(PG8_SA(1, 1), a1 + hstepA, voffA);
;             PG8_WAIT_V(8); PG8_WAIT_L(0); PG8_BAR; PG8_MMA(0, 0, At, B0); PG8_MMA(0, 1, At, B1); PG8_BAR; PG8_SCHED;
;             PG8_LDA(At, 0, 1); PG8_STAGE(PG8_SB(0, 0), b2, voffB); PG8_STAGE(PG8_SB(0, 1), b2 + hstepB, voffB); PG8_STAGE(PG8_SA(0, 0), a2, voffA);
.LBB0_2756:
	ds_read_b128 v[146:149], v152
	ds_read_b128 v[156:159], v152 offset:1024
	ds_read_b128 v[160:163], v152 offset:2048
	ds_read_b128 v[164:167], v152 offset:3072
	ds_read_b128 v[168:171], v153
	ds_read_b128 v[172:175], v153 offset:1024
	ds_read_b128 v[176:179], v153 offset:2048
	ds_read_b128 v[180:183], v153 offset:3072
	s_add_u32 s54, s52, 0x100
	s_addc_u32 s55, s53, 0
	s_cmpk_eq_i32 s84, 0xa8
	s_cselect_b32 s59, s7, s55
	s_cselect_b32 s58, s6, s54
	s_cselect_b32 s57, s51, s83
	s_cselect_b32 s56, s50, s82
	v_lshl_add_u64 v[216:217], s[52:53], 0, v[138:139]
	s_add_i32 m0, s63, 0xc000
	ds_read_b128 v[184:187], v154
	ds_read_b128 v[188:191], v154 offset:1024
	ds_read_b128 v[192:195], v154 offset:2048
	ds_read_b128 v[196:199], v154 offset:3072
	ds_read_b128 v[200:203], v154 offset:4096
	ds_read_b128 v[204:207], v154 offset:5120
	ds_read_b128 v[208:211], v154 offset:6144
	ds_read_b128 v[212:215], v154 offset:7168
	global_load_lds_dwordx4 v[216:217], off
	v_lshl_add_u64 v[216:217], s[52:53], 0, v[140:141]
	s_add_i32 m0, s63, 0xe000
	s_nop 0
	global_load_lds_dwordx4 v[216:217], off
	s_waitcnt vmcnt(8)
	s_waitcnt lgkmcnt(0)
	s_barrier
	s_setprio 1
	s_waitcnt lgkmcnt(0)
	v_mfma_f32_16x16x32_bf16 v[76:79], v[146:149], v[184:187], v[76:79]
	v_mfma_f32_16x16x32_bf16 v[72:75], v[160:163], v[184:187], v[72:75]
	v_mfma_f32_16x16x32_bf16 v[68:71], v[146:149], v[192:195], v[68:71]
	v_mfma_f32_16x16x32_bf16 v[64:67], v[160:163], v[192:195], v[64:67]
	v_mfma_f32_16x16x32_bf16 v[56:59], v[146:149], v[200:203], v[56:59]
	v_mfma_f32_16x16x32_bf16 v[52:55], v[160:163], v[200:203], v[52:55]
	v_mfma_f32_16x16x32_bf16 v[44:47], v[146:149], v[208:211], v[44:47]
	v_mfma_f32_16x16x32_bf16 v[40:43], v[160:163], v[208:211], v[40:43]
	v_mfma_f32_16x16x32_bf16 v[76:79], v[156:159], v[188:191], v[76:79]
	v_mfma_f32_16x16x32_bf16 v[72:75], v[164:167], v[188:191], v[72:75]
	v_mfma_f32_16x16x32_bf16 v[68:71], v[156:159], v[196:199], v[68:71]
	v_mfma_f32_16x16x32_bf16 v[64:67], v[164:167], v[196:199], v[64:67]
	v_mfma_f32_16x16x32_bf16 v[56:59], v[156:159], v[204:207], v[56:59]
	v_mfma_f32_16x16x32_bf16 v[52:55], v[164:167], v[204:207], v[52:55]
	v_mfma_f32_16x16x32_bf16 v[44:47], v[156:159], v[212:215], v[44:47]
	v_mfma_f32_16x16x32_bf16 v[40:43], v[164:167], v[212:215], v[40:43]
	s_setprio 0
	s_setprio 1
	v_mfma_f32_16x16x32_bf16 v[124:127], v[168:171], v[184:187], v[124:127]
	v_mfma_f32_16x16x32_bf16 v[120:123], v[176:179], v[184:187], v[120:123]
	v_mfma_f32_16x16x32_bf16 v[116:119], v[168:171], v[192:195], v[116:119]
	v_mfma_f32_16x16x32_bf16 v[112:115], v[176:179], v[192:195], v[112:115]
	v_mfma_f32_16x16x32_bf16 v[108:111], v[168:171], v[200:203], v[108:111]
	v_mfma_f32_16x16x32_bf16 v[104:107], v[176:179], v[200:203], v[104:107]
	v_mfma_f32_16x16x32_bf16 v[100:103], v[168:171], v[208:211], v[100:103]
	v_mfma_f32_16x16x32_bf16 v[96:99], v[176:179], v[208:211], v[96:99]
	v_mfma_f32_16x16x32_bf16 v[124:127], v[172:175], v[188:191], v[124:127]
	v_mfma_f32_16x16x32_bf16 v[120:123], v[180:183], v[188:191], v[120:123]
	v_mfma_f32_16x16x32_bf16 v[116:119], v[172:175], v[196:199], v[116:119]
	v_mfma_f32_16x16x32_bf16 v[112:115], v[180:183], v[196:199], v[112:115]
	v_mfma_f32_16x16x32_bf16 v[108:111], v[172:175], v[204:207], v[108:111]
	v_mfma_f32_16x16x32_bf16 v[104:107], v[180:183], v[204:207], v[104:107]
	s_setprio 2
	s_barrier
	v_mfma_f32_16x16x32_bf16 v[100:103], v[172:175], v[212:215], v[100:103]
	v_mfma_f32_16x16x32_bf16 v[96:99], v[180:183], v[212:215], v[96:99]
	s_setprio 0
	s_add_i32 s52, s72, s62
	v_lshl_add_u64 v[216:217], s[56:57], 0, v[130:131]
	s_mov_b32 m0, s52
	ds_read_b128 v[184:187], v154 offset:16384
	ds_read_b128 v[188:191], v154 offset:17408
	ds_read_b128 v[192:195], v154 offset:18432
	ds_read_b128 v[196:199], v154 offset:19456
	ds_read_b128 v[200:203], v154 offset:20480
	ds_read_b128 v[204:207], v154 offset:21504
	ds_read_b128 v[208:211], v154 offset:22528
	ds_read_b128 v[212:215], v154 offset:23552
	global_load_lds_dwordx4 v[216:217], off
	s_add_i32 m0, s52, 0x2000
	s_add_u32 s52, s56, 0x2b0000
	v_lshl_add_u64 v[218:219], s[56:57], 0, v[134:135]
	s_addc_u32 s53, s57, 0
	s_add_i32 s85, s73, s62
	global_load_lds_dwordx4 v[218:219], off
	v_lshl_add_u64 v[220:221], s[52:53], 0, v[130:131]
	s_mov_b32 m0, s85
	v_lshl_add_u64 v[222:223], s[58:59], 0, v[132:133]
	global_load_lds_dwordx4 v[220:221], off
	v_lshl_add_u64 v[220:221], s[52:53], 0, v[134:135]
	s_add_i32 m0, s85, 0x2000
	s_nop 0
	global_load_lds_dwordx4 v[220:221], off
	v_lshl_add_u64 v[220:221], s[58:59], 0, v[128:129]
	s_mov_b32 m0, s63
	s_nop 0
	global_load_lds_dwordx4 v[220:221], off
	s_mov_b32 m0, s64
	s_nop 0
	global_load_lds_dwordx4 v[222:223], off
	s_waitcnt vmcnt(8)
	s_waitcnt lgkmcnt(0)
	s_barrier
; #define PG8_STAGE(bufoff, gbase, voff) do { _Pragma("unroll") for (int _i = 0; _i < 2; ++_i) \
;         __builtin_amdgcn_global_load_lds((const unsigned*)((const char*)(gbase) + (voff)[_i]), (PG8_LAS unsigned*)(lds + (bufoff) + ldsw + _i * 8192), 16, 0, 0); } while (0)
; #define PG8_LDA(dst, b, h) do { _Pragma("unroll") for (int m = 0; m < 4; ++m) _Pragma("unroll") for (int k = 0; k < 2; ++k) dst[m][k] = *(const PG8_LAS bf16x8*)(lds + PG8_SA(b, h) + aoff + m * 2048 + k * 1024); } while (0)
; #define PG8_LDB(dst, b, h) do { _Pragma("unroll") for (int n = 0; n < 2; ++n) _Pragma("unroll") for (int k = 0; k < 2; ++k) dst[n][k] = *(const PG8_LAS bf16x8*)(lds + PG8_SB(b, h) + boff + n * 2048 + k * 1024); } while (0)
; #define PG8_MMA(ai, bj, At, Bt) do { __builtin_amdgcn_s_setprio(1); _Pragma("unroll") for (int m = 0; m < 4; ++m) _Pragma("unroll") for (int n = 0; n < 2; ++n) _Pragma("unroll") for (int k = 0; k < 2; ++k) \
;         acc[ai][bj][m][n] = __builtin_amdgcn_mfma_f32_16x16x32_bf16(Bt[n][k], At[m][k], acc[ai][bj][m][n], 0, 0, 0); __builtin_amdgcn_s_setprio(0); } while (0)
; #define PG8_WAIT_V(n) asm volatile("s_waitcnt vmcnt(" #n ")" ::: "memory")
; #define PG8_WAIT_L(n) asm volatile("s_waitcnt lgkmcnt(" #n ")" ::: "memory")
; #define PG8_BAR __builtin_amdgcn_s_barrier()
; #define PG8_SCHED __builtin_amdgcn_sched_barrier(0)
; template <class Epi, class Sched, bool ALIGN_EPI = false, bool SP2 = false>
; __device__ __forceinline__ void gemm_phase(PG8_LAS unsigned char* lds, const Gemm g, const Sched& S, const Epi& E, const int wv  ) {
;     ...
;             PG8_WAIT_V(8); PG8_WAIT_L(0); PG8_BAR; PG8_MMA(1, 0, At, B0); PG8_MMA(1, 1, At, B1); PG8_BAR; PG8_SCHED;
;             PG8_LDB(B0, 1, 0); PG8_LDB(B1, 1, 1); PG8_SCHED; PG8_LDA(At, 1, 0); PG8_STAGE(PG8_SA(0, 1), a2 + hstepA, voffA);
;             PG8_WAIT_V(8); PG8_WAIT_L(0); PG8_BAR; PG8_MMA(0, 0, At, B0); PG8_MMA(0, 1, At, B1); PG8_BAR; PG8_SCHED;
	s_setprio 1
	s_waitcnt lgkmcnt(0)
	v_mfma_f32_16x16x32_bf16 v[28:31], v[146:149], v[184:187], v[28:31]
	v_mfma_f32_16x16x32_bf16 v[24:27], v[160:163], v[184:187], v[24:27]
	v_mfma_f32_16x16x32_bf16 v[20:23], v[146:149], v[192:195], v[20:23]
	v_mfma_f32_16x16x32_bf16 v[16:19], v[160:163], v[192:195], v[16:19]
	v_mfma_f32_16x16x32_bf16 v[12:15], v[146:149], v[200:203], v[12:15]
	v_mfma_f32_16x16x32_bf16 v[8:11], v[160:163], v[200:203], v[8:11]
	v_mfma_f32_16x16x32_bf16 v[4:7], v[146:149], v[208:211], v[4:7]
	v_mfma_f32_16x16x32_bf16 v[0:3], v[160:163], v[208:211], v[0:3]
	v_mfma_f32_16x16x32_bf16 v[28:31], v[156:159], v[188:191], v[28:31]
	v_mfma_f32_16x16x32_bf16 v[24:27], v[164:167], v[188:191], v[24:27]
	v_mfma_f32_16x16x32_bf16 v[20:23], v[156:159], v[196:199], v[20:23]
	v_mfma_f32_16x16x32_bf16 v[16:19], v[164:167], v[196:199], v[16:19]
	v_mfma_f32_16x16x32_bf16 v[12:15], v[156:159], v[204:207], v[12:15]
	v_mfma_f32_16x16x32_bf16 v[8:11], v[164:167], v[204:207], v[8:11]
	v_mfma_f32_16x16x32_bf16 v[4:7], v[156:159], v[212:215], v[4:7]
	v_mfma_f32_16x16x32_bf16 v[0:3], v[164:167], v[212:215], v[0:3]
	s_setprio 0
	s_setprio 1
	v_mfma_f32_16x16x32_bf16 v[92:95], v[168:171], v[184:187], v[92:95]
	v_mfma_f32_16x16x32_bf16 v[88:91], v[176:179], v[184:187], v[88:91]
	v_mfma_f32_16x16x32_bf16 v[84:87], v[168:171], v[192:195], v[84:87]
	v_mfma_f32_16x16x32_bf16 v[80:83], v[176:179], v[192:195], v[80:83]
	v_mfma_f32_16x16x32_bf16 v[60:63], v[168:171], v[200:203], v[60:63]
	v_mfma_f32_16x16x32_bf16 v[48:51], v[176:179], v[200:203], v[48:51]
	v_mfma_f32_16x16x32_bf16 v[36:39], v[168:171], v[208:211], v[36:39]
	v_mfma_f32_16x16x32_bf16 v[32:35], v[176:179], v[208:211], v[32:35]
	v_mfma_f32_16x16x32_bf16 v[92:95], v[172:175], v[188:191], v[92:95]
	v_mfma_f32_16x16x32_bf16 v[88:91], v[180:183], v[188:191], v[88:91]
	v_mfma_f32_16x16x32_bf16 v[84:87], v[172:175], v[196:199], v[84:87]
	v_mfma_f32_16x16x32_bf16 v[80:83], v[180:183], v[196:199], v[80:83]
	v_mfma_f32_16x16x32_bf16 v[60:63], v[172:175], v[204:207], v[60:63]
	v_mfma_f32_16x16x32_bf16 v[48:51], v[180:183], v[204:207], v[48:51]
	s_setprio 2
	s_barrier
	v_mfma_f32_16x16x32_bf16 v[36:39], v[172:175], v[212:215], v[36:39]
	v_mfma_f32_16x16x32_bf16 v[32:35], v[180:183], v[212:215], v[32:35]
	s_setprio 0
	s_add_i32 s85, 0, 0x18000
	v_add_u32_e32 v155, s85, v150
	s_add_i32 s86, 0, 0x1c000
	ds_read_b128 v[146:149], v155
	ds_read_b128 v[156:159], v155 offset:1024
	ds_read_b128 v[160:163], v155 offset:2048
	ds_read_b128 v[164:167], v155 offset:3072
	v_add_u32_e32 v155, s86, v150
	ds_read_b128 v[168:171], v155
	ds_read_b128 v[172:175], v155 offset:1024
	ds_read_b128 v[176:179], v155 offset:2048
	ds_read_b128 v[180:183], v155 offset:3072
	s_add_u32 s52, s58, 0x2b0000
	s_addc_u32 s53, s59, 0
	s_mov_b32 m0, s65
	v_lshl_add_u64 v[224:225], s[52:53], 0, v[128:129]
	ds_read_b128 v[184:187], v154 offset:32768
	ds_read_b128 v[188:191], v154 offset:33792
	ds_read_b128 v[192:195], v154 offset:34816
	ds_read_b128 v[196:199], v154 offset:35840
	ds_read_b128 v[200:203], v154 offset:36864
	ds_read_b128 v[204:207], v154 offset:37888
	ds_read_b128 v[208:211], v154 offset:38912
	ds_read_b128 v[212:215], v154 offset:39936
	global_load_lds_dwordx4 v[224:225], off
	v_lshl_add_u64 v[224:225], s[52:53], 0, v[132:133]
	s_mov_b32 m0, s66
	s_nop 0
	global_load_lds_dwordx4 v[224:225], off
	s_waitcnt vmcnt(8)
	s_waitcnt lgkmcnt(0)
	s_barrier
	s_setprio 1
	s_waitcnt lgkmcnt(0)
	v_mfma_f32_16x16x32_bf16 v[76:79], v[146:149], v[184:187], v[76:79]
	v_mfma_f32_16x16x32_bf16 v[72:75], v[160:163], v[184:187], v[72:75]
	v_mfma_f32_16x16x32_bf16 v[68:71], v[146:149], v[192:195], v[68:71]
	v_mfma_f32_16x16x32_bf16 v[64:67], v[160:163], v[192:195], v[64:67]
	v_mfma_f32_16x16x32_bf16 v[56:59], v[146:149], v[200:203], v[56:59]
	v_mfma_f32_16x16x32_bf16 v[52:55], v[160:163], v[200:203], v[52:55]
	v_mfma_f32_16x16x32_bf16 v[44:47], v[146:149], v[208:211], v[44:47]
	v_mfma_f32_16x16x32_bf16 v[40:43], v[160:163], v[208:211], v[40:43]
	v_mfma_f32_16x16x32_bf16 v[76:79], v[156:159], v[188:191], v[76:79]
	v_mfma_f32_16x16x32_bf16 v[72:75], v[164:167], v[188:191], v[72:75]
	v_mfma_f32_16x16x32_bf16 v[68:71], v[156:159], v[196:199], v[68:71]
	v_mfma_f32_16x16x32_bf16 v[64:67], v[164:167], v[196:199], v[64:67]
	v_mfma_f32_16x16x32_bf16 v[56:59], v[156:159], v[204:207], v[56:59]
	v_mfma_f32_16x16x32_bf16 v[52:55], v[164:167], v[204:207], v[52:55]
	v_mfma_f32_16x16x32_bf16 v[44:47], v[156:159], v[212:215], v[44:47]
	v_mfma_f32_16x16x32_bf16 v[40:43], v[164:167], v[212:215], v[40:43]
	s_setprio 0
	s_setprio 1
	v_mfma_f32_16x16x32_bf16 v[124:127], v[168:171], v[184:187], v[124:127]
	v_mfma_f32_16x16x32_bf16 v[120:123], v[176:179], v[184:187], v[120:123]
	v_mfma_f32_16x16x32_bf16 v[116:119], v[168:171], v[192:195], v[116:119]
	v_mfma_f32_16x16x32_bf16 v[112:115], v[176:179], v[192:195], v[112:115]
	v_mfma_f32_16x16x32_bf16 v[108:111], v[168:171], v[200:203], v[108:111]
	v_mfma_f32_16x16x32_bf16 v[104:107], v[176:179], v[200:203], v[104:107]
	v_mfma_f32_16x16x32_bf16 v[100:103], v[168:171], v[208:211], v[100:103]
	v_mfma_f32_16x16x32_bf16 v[96:99], v[176:179], v[208:211], v[96:99]
	v_mfma_f32_16x16x32_bf16 v[124:127], v[172:175], v[188:191], v[124:127]
	v_mfma_f32_16x16x32_bf16 v[120:123], v[180:183], v[188:191], v[120:123]
	v_mfma_f32_16x16x32_bf16 v[116:119], v[172:175], v[196:199], v[116:119]
	v_mfma_f32_16x16x32_bf16 v[112:115], v[180:183], v[196:199], v[112:115]
	v_mfma_f32_16x16x32_bf16 v[108:111], v[172:175], v[204:207], v[108:111]
	v_mfma_f32_16x16x32_bf16 v[104:107], v[180:183], v[204:207], v[104:107]
	s_setprio 2
	s_barrier
; #define PG8_STAGE(bufoff, gbase, voff) do { _Pragma("unroll") for (int _i = 0; _i < 2; ++_i) \
;         __builtin_amdgcn_global_load_lds((const unsigned*)((const char*)(gbase) + (voff)[_i]), (PG8_LAS unsigned*)(lds + (bufoff) + ldsw + _i * 8192), 16, 0, 0); } while (0)
; #define PG8_LDA(dst, b, h) do { _Pragma("unroll") for (int m = 0; m < 4; ++m) _Pragma("unroll") for (int k = 0; k < 2; ++k) dst[m][k] = *(const PG8_LAS bf16x8*)(lds + PG8_SA(b, h) + aoff + m * 2048 + k * 1024); } while (0)
; #define PG8_MMA(ai, bj, At, Bt) do { __builtin_amdgcn_s_setprio(1); _Pragma("unroll") for (int m = 0; m < 4; ++m) _Pragma("unroll") for (int n = 0; n < 2; ++n) _Pragma("unroll") for (int k = 0; k < 2; ++k) \
;         acc[ai][bj][m][n] = __builtin_amdgcn_mfma_f32_16x16x32_bf16(Bt[n][k], At[m][k], acc[ai][bj][m][n], 0, 0, 0); __builtin_amdgcn_s_setprio(0); } while (0)
; #define PG8_WAIT_V(n) asm volatile("s_waitcnt vmcnt(" #n ")" ::: "memory")
; #define PG8_WAIT_L(n) asm volatile("s_waitcnt lgkmcnt(" #n ")" ::: "memory")
; #define PG8_BAR __builtin_amdgcn_s_barrier()
; #define PG8_SCHED __builtin_amdgcn_sched_barrier(0)
; template <class Epi, class Sched, bool ALIGN_EPI = false, bool SP2 = false>
; __device__ __forceinline__ void gemm_phase(PG8_LAS unsigned char* lds, const Gemm g, const Sched& S, const Epi& E, const int wv  ) {
;     ...
;             PG8_WAIT_V(8); PG8_WAIT_L(0); PG8_BAR; PG8_MMA(0, 0, At, B0); PG8_MMA(0, 1, At, B1); PG8_BAR; PG8_SCHED;
;             PG8_LDA(At, 1, 1); PG8_STAGE(PG8_SB(1, 0), b3, voffB); PG8_STAGE(PG8_SB(1, 1), b3 + hstepB, voffB); PG8_STAGE(PG8_SA(1, 0), a3, voffA);
;             PG8_WAIT_V(8); PG8_WAIT_L(0); PG8_BAR; PG8_MMA(1, 0, At, B0); PG8_MMA(1, 1, At, B1); PG8_BAR; PG8_SCHED;
;     ...
;         if constexpr (ALIGN_EPI) { if (wr == 0) PG8_BAR; }
	v_mfma_f32_16x16x32_bf16 v[100:103], v[172:175], v[212:215], v[100:103]
	v_mfma_f32_16x16x32_bf16 v[96:99], v[180:183], v[212:215], v[96:99]
	s_setprio 0
	s_add_i32 s52, s85, s62
	v_lshl_add_u64 v[216:217], v[216:217], 0, s[12:13]
	s_mov_b32 m0, s52
	ds_read_b128 v[184:187], v154 offset:49152
	ds_read_b128 v[188:191], v154 offset:50176
	ds_read_b128 v[192:195], v154 offset:51200
	ds_read_b128 v[196:199], v154 offset:52224
	ds_read_b128 v[200:203], v154 offset:53248
	ds_read_b128 v[204:207], v154 offset:54272
	ds_read_b128 v[208:211], v154 offset:55296
	ds_read_b128 v[212:215], v154 offset:56320
	global_load_lds_dwordx4 v[216:217], off
	s_add_i32 m0, s52, 0x2000
	s_add_u32 s52, s56, 0x2b0080
	v_lshl_add_u64 v[216:217], v[218:219], 0, s[12:13]
	s_addc_u32 s53, s57, 0
	s_add_i32 s56, s86, s62
	global_load_lds_dwordx4 v[216:217], off
	v_lshl_add_u64 v[216:217], s[52:53], 0, v[130:131]
	s_mov_b32 m0, s56
	s_nop 0
	global_load_lds_dwordx4 v[216:217], off
	v_lshl_add_u64 v[216:217], s[52:53], 0, v[134:135]
	s_add_i32 m0, s56, 0x2000
	s_nop 0
	global_load_lds_dwordx4 v[216:217], off
	v_lshl_add_u64 v[216:217], v[220:221], 0, s[12:13]
	s_mov_b32 m0, s69
	s_nop 0
	global_load_lds_dwordx4 v[216:217], off
	v_lshl_add_u64 v[216:217], v[222:223], 0, s[12:13]
	s_mov_b32 m0, s70
	s_nop 0
	global_load_lds_dwordx4 v[216:217], off
	s_waitcnt vmcnt(8)
	s_waitcnt lgkmcnt(0)
	s_barrier
	s_setprio 1
	s_waitcnt lgkmcnt(0)
	v_mfma_f32_16x16x32_bf16 v[28:31], v[146:149], v[184:187], v[28:31]
	v_mfma_f32_16x16x32_bf16 v[24:27], v[160:163], v[184:187], v[24:27]
	v_mfma_f32_16x16x32_bf16 v[20:23], v[146:149], v[192:195], v[20:23]
	v_mfma_f32_16x16x32_bf16 v[16:19], v[160:163], v[192:195], v[16:19]
	v_mfma_f32_16x16x32_bf16 v[12:15], v[146:149], v[200:203], v[12:15]
	v_mfma_f32_16x16x32_bf16 v[8:11], v[160:163], v[200:203], v[8:11]
	v_mfma_f32_16x16x32_bf16 v[4:7], v[146:149], v[208:211], v[4:7]
	v_mfma_f32_16x16x32_bf16 v[0:3], v[160:163], v[208:211], v[0:3]
	v_mfma_f32_16x16x32_bf16 v[28:31], v[156:159], v[188:191], v[28:31]
	v_mfma_f32_16x16x32_bf16 v[24:27], v[164:167], v[188:191], v[24:27]
	v_mfma_f32_16x16x32_bf16 v[20:23], v[156:159], v[196:199], v[20:23]
	v_mfma_f32_16x16x32_bf16 v[16:19], v[164:167], v[196:199], v[16:19]
	v_mfma_f32_16x16x32_bf16 v[12:15], v[156:159], v[204:207], v[12:15]
	v_mfma_f32_16x16x32_bf16 v[8:11], v[164:167], v[204:207], v[8:11]
	v_mfma_f32_16x16x32_bf16 v[4:7], v[156:159], v[212:215], v[4:7]
	v_mfma_f32_16x16x32_bf16 v[0:3], v[164:167], v[212:215], v[0:3]
	s_setprio 0
	s_setprio 1
	v_mfma_f32_16x16x32_bf16 v[92:95], v[168:171], v[184:187], v[92:95]
	v_mfma_f32_16x16x32_bf16 v[88:91], v[176:179], v[184:187], v[88:91]
	v_mfma_f32_16x16x32_bf16 v[84:87], v[168:171], v[192:195], v[84:87]
	v_mfma_f32_16x16x32_bf16 v[80:83], v[176:179], v[192:195], v[80:83]
	v_mfma_f32_16x16x32_bf16 v[60:63], v[168:171], v[200:203], v[60:63]
	v_mfma_f32_16x16x32_bf16 v[48:51], v[176:179], v[200:203], v[48:51]
	v_mfma_f32_16x16x32_bf16 v[36:39], v[168:171], v[208:211], v[36:39]
	v_mfma_f32_16x16x32_bf16 v[32:35], v[176:179], v[208:211], v[32:35]
	v_mfma_f32_16x16x32_bf16 v[92:95], v[172:175], v[188:191], v[92:95]
	v_mfma_f32_16x16x32_bf16 v[88:91], v[180:183], v[188:191], v[88:91]
	v_mfma_f32_16x16x32_bf16 v[84:87], v[172:175], v[196:199], v[84:87]
	v_mfma_f32_16x16x32_bf16 v[80:83], v[180:183], v[196:199], v[80:83]
	v_mfma_f32_16x16x32_bf16 v[60:63], v[172:175], v[204:207], v[60:63]
	v_mfma_f32_16x16x32_bf16 v[48:51], v[180:183], v[204:207], v[48:51]
	s_setprio 2
	s_barrier
	v_mfma_f32_16x16x32_bf16 v[36:39], v[172:175], v[212:215], v[36:39]
	v_mfma_f32_16x16x32_bf16 v[32:35], v[180:183], v[212:215], v[32:35]
	s_setprio 0
	s_add_i32 s84, s84, 2
	s_add_u32 s82, s82, 0x100
	s_addc_u32 s83, s83, 0
	s_cmpk_gt_u32 s84, 0xa9
	s_mov_b64 s[52:53], s[54:55]
	s_cbranch_scc0 .LBB0_2756
	s_and_b64 vcc, exec, s[14:15]
	s_cbranch_vccz .LBB0_2759
	s_barrier
